# v9 + GEMM phases: per-phase s_setprio flips deleted, one static s_setprio 1 for waves 4-7 (younger half) per GEMM phase
# speedup vs baseline: 1.0084x; 1.0084x over previous
; template <class Epi, class Sched>
; __device__ __forceinline__ void gemm_phase(const int wv, LAS unsigned char* lds, const Gemm g, const Sched& S, const Epi& E) {
;     ...
;     for (;;) {
;         const bool has_next = S.next(ui + 1, nxt);
;         const char* nA = has_next ? (const char*)g.A + (size_t)nxt.pm * tstepA : cA; const char* nB = has_next ? (const char*)g.Bt + (size_t)nxt.pn * tstepB : cB;
;         for (int t = 0; t < nt; t += 2) {
.LBB0_132:
	s_cmpk_lt_u32 s53, 0x100
	s_cbranch_scc1 .Lgprio_ip
	s_setprio 1

; #define PG8_STAGE(bufoff, gbase, voff) do { _Pragma("unroll") for (int _i = 0; _i < 2; ++_i) \
;         __builtin_amdgcn_global_load_lds((const unsigned*)((const char*)(gbase) + (voff)[_i]), (LAS unsigned*)(lds + (bufoff) + ldsw + _i * 8192), 16, 0, 0); } while (0)
; #define PG8_LDA(dst, b, h) do { _Pragma("unroll") for (int m = 0; m < 4; ++m) _Pragma("unroll") for (int k = 0; k < 2; ++k) dst[m][k] = *(const LAS bf16x8*)(lds + PG8_SA(b, h) + aoff + m * 2048 + k * 1024); } while (0)
; #define PG8_LDB(dst, b, h) do { _Pragma("unroll") for (int n = 0; n < 2; ++n) _Pragma("unroll") for (int k = 0; k < 2; ++k) dst[n][k] = *(const LAS bf16x8*)(lds + PG8_SB(b, h) + boff + n * 2048 + k * 1024); } while (0)
; #define PG8_MMA(ai, bj, At, Bt) do { __builtin_amdgcn_s_setprio(1); _Pragma("unroll") for (int m = 0; m < 4; ++m) _Pragma("unroll") for (int n = 0; n < 2; ++n) _Pragma("unroll") for (int k = 0; k < 2; ++k) \
;         acc[ai][bj][m][n] = __builtin_amdgcn_mfma_f32_16x16x32_bf16(Bt[n][k], At[m][k], acc[ai][bj][m][n], 0, 0, 0); __builtin_amdgcn_s_setprio(0); } while (0)
; #define PG8_WAIT_V(n) asm volatile("s_waitcnt vmcnt(" #n ")" ::: "memory")
; #define PG8_WAIT_L(n) asm volatile("s_waitcnt lgkmcnt(" #n ")" ::: "memory")
; #define PG8_BAR __builtin_amdgcn_s_barrier()
; #define PG8_SCHED __builtin_amdgcn_sched_barrier(0)
; template <class Epi, class Sched>
; __device__ __forceinline__ void gemm_phase(const int wv, LAS unsigned char* lds, const Gemm g, const Sched& S, const Epi& E) {
;     ...
;             PG8_LDB(B0, 0, 0); PG8_SCHED; PG8_LDA(At, 0, 0); PG8_STAGE(PG8_SA(1, 1), a1 + hstepA, voffA);
;             PG8_WAIT_L(8); PG8_BAR; PG8_WAIT_L(0); PG8_MMA(0, 0, At, B0); PG8_BAR; PG8_SCHED;
;             PG8_LDB(B1, 0, 1); PG8_STAGE(PG8_SB(0, 0), b2, voffB);
;             PG8_BAR; PG8_WAIT_L(0); PG8_MMA(0, 1, At, B1); PG8_BAR;
;             PG8_LDA(At, 0, 1); PG8_STAGE(PG8_SA(0, 0), a2, voffA);
;             PG8_BAR; PG8_WAIT_L(0); PG8_MMA(1, 0, At, B0); PG8_BAR; PG8_SCHED;
;             PG8_STAGE(PG8_SB(0, 1), b2 + hstepB, voffB);
;             PG8_WAIT_V(6); PG8_BAR; PG8_MMA(1, 1, At, B1); PG8_BAR;
.LBB0_147:
	s_add_u32 s24, s22, 0xfffc0080
	s_addc_u32 s25, s23, -1
	s_add_i32 s31, 0, 0x10000
	v_add_u32_e32 v150, s31, v152
	ds_read_b128 v[142:145], v150
	ds_read_b128 v[146:149], v150 offset:1024
	ds_read_b128 v[160:163], v150 offset:2048
	ds_read_b128 v[164:167], v150 offset:3072
	s_cmp_eq_u32 s30, 12
	s_cselect_b32 s27, s1, s25
	s_cselect_b32 s26, s3, s24
	s_cselect_b32 s25, s13, s29
	s_cselect_b32 s24, s15, s28
	v_lshl_add_u64 v[150:151], s[22:23], 0, v[138:139]
	s_add_i32 m0, s45, 0xc000
	ds_read_b128 v[168:171], v158
	ds_read_b128 v[172:175], v158 offset:1024
	ds_read_b128 v[180:183], v158 offset:2048
	ds_read_b128 v[192:195], v158 offset:3072
	ds_read_b128 v[196:199], v158 offset:4096
	ds_read_b128 v[200:203], v158 offset:5120
	ds_read_b128 v[204:207], v158 offset:6144
	ds_read_b128 v[208:211], v158 offset:7168
	global_load_lds_dwordx4 v[150:151], off
	v_lshl_add_u64 v[150:151], s[22:23], 0, v[140:141]
	s_add_i32 m0, s45, 0xe000
	s_nop 0
	global_load_lds_dwordx4 v[150:151], off
	s_waitcnt lgkmcnt(8)
	s_barrier
	s_waitcnt lgkmcnt(0)
	s_waitcnt lgkmcnt(0)
	v_mfma_f32_16x16x32_bf16 v[126:129], v[142:145], v[168:171], v[126:129]
	v_mfma_f32_16x16x32_bf16 v[122:125], v[160:163], v[168:171], v[122:125]
	v_mfma_f32_16x16x32_bf16 v[110:113], v[142:145], v[180:183], v[110:113]
	v_mfma_f32_16x16x32_bf16 v[106:109], v[160:163], v[180:183], v[106:109]
	v_mfma_f32_16x16x32_bf16 v[94:97], v[142:145], v[196:199], v[94:97]
	v_mfma_f32_16x16x32_bf16 v[90:93], v[160:163], v[196:199], v[90:93]
	v_mfma_f32_16x16x32_bf16 v[78:81], v[142:145], v[204:207], v[78:81]
	v_mfma_f32_16x16x32_bf16 v[74:77], v[160:163], v[204:207], v[74:77]
	v_mfma_f32_16x16x32_bf16 v[126:129], v[146:149], v[172:175], v[126:129]
	v_mfma_f32_16x16x32_bf16 v[122:125], v[164:167], v[172:175], v[122:125]
	v_mfma_f32_16x16x32_bf16 v[110:113], v[146:149], v[192:195], v[110:113]
	v_mfma_f32_16x16x32_bf16 v[106:109], v[164:167], v[192:195], v[106:109]
	v_mfma_f32_16x16x32_bf16 v[94:97], v[146:149], v[200:203], v[94:97]
	v_mfma_f32_16x16x32_bf16 v[90:93], v[164:167], v[200:203], v[90:93]
	v_mfma_f32_16x16x32_bf16 v[78:81], v[146:149], v[208:211], v[78:81]
	v_mfma_f32_16x16x32_bf16 v[74:77], v[164:167], v[208:211], v[74:77]
	s_barrier
	s_add_i32 s52, 0, 0x14000
	v_add_u32_e32 v150, s52, v152
	s_add_i32 s31, s31, s44
	ds_read_b128 v[212:215], v150
	ds_read_b128 v[216:219], v150 offset:1024
	ds_read_b128 v[220:223], v150 offset:2048
	ds_read_b128 v[224:227], v150 offset:3072
	v_lshl_add_u64 v[150:151], s[24:25], 0, v[132:133]
	s_mov_b32 m0, s31
	v_lshl_add_u64 v[176:177], s[24:25], 0, v[136:137]
	global_load_lds_dwordx4 v[150:151], off
	s_add_i32 m0, s31, 0x2000
	s_nop 0
	global_load_lds_dwordx4 v[176:177], off
	s_barrier
	s_waitcnt lgkmcnt(0)
	s_waitcnt lgkmcnt(0)
	v_mfma_f32_16x16x32_bf16 v[118:121], v[212:215], v[168:171], v[118:121]
	v_mfma_f32_16x16x32_bf16 v[114:117], v[220:223], v[168:171], v[114:117]
	v_mfma_f32_16x16x32_bf16 v[102:105], v[212:215], v[180:183], v[102:105]
	v_mfma_f32_16x16x32_bf16 v[98:101], v[220:223], v[180:183], v[98:101]
	v_mfma_f32_16x16x32_bf16 v[86:89], v[212:215], v[196:199], v[86:89]
	v_mfma_f32_16x16x32_bf16 v[82:85], v[220:223], v[196:199], v[82:85]
	v_mfma_f32_16x16x32_bf16 v[70:73], v[212:215], v[204:207], v[70:73]
	v_mfma_f32_16x16x32_bf16 v[66:69], v[220:223], v[204:207], v[66:69]
	v_mfma_f32_16x16x32_bf16 v[118:121], v[216:219], v[172:175], v[118:121]
	v_mfma_f32_16x16x32_bf16 v[114:117], v[224:227], v[172:175], v[114:117]
	v_mfma_f32_16x16x32_bf16 v[102:105], v[216:219], v[192:195], v[102:105]
	v_mfma_f32_16x16x32_bf16 v[98:101], v[224:227], v[192:195], v[98:101]
	v_mfma_f32_16x16x32_bf16 v[86:89], v[216:219], v[200:203], v[86:89]
	v_mfma_f32_16x16x32_bf16 v[82:85], v[224:227], v[200:203], v[82:85]
	v_mfma_f32_16x16x32_bf16 v[70:73], v[216:219], v[208:211], v[70:73]
	v_mfma_f32_16x16x32_bf16 v[66:69], v[224:227], v[208:211], v[66:69]
	s_mov_b32 m0, s45
	v_lshl_add_u64 v[228:229], s[26:27], 0, v[130:131]
	s_barrier
	ds_read_b128 v[168:171], v158 offset:16384
	ds_read_b128 v[172:175], v158 offset:17408
	ds_read_b128 v[180:183], v158 offset:18432
	ds_read_b128 v[192:195], v158 offset:19456
	ds_read_b128 v[196:199], v158 offset:20480
	ds_read_b128 v[200:203], v158 offset:21504
	ds_read_b128 v[204:207], v158 offset:22528
	ds_read_b128 v[208:211], v158 offset:23552
	global_load_lds_dwordx4 v[228:229], off
	v_lshl_add_u64 v[230:231], s[26:27], 0, v[134:135]
	s_mov_b32 m0, s46
	s_nop 0
	global_load_lds_dwordx4 v[230:231], off
	s_barrier
	s_waitcnt lgkmcnt(0)
	s_waitcnt lgkmcnt(0)
	v_mfma_f32_16x16x32_bf16 v[62:65], v[142:145], v[168:171], v[62:65]
	v_mfma_f32_16x16x32_bf16 v[58:61], v[160:163], v[168:171], v[58:61]
	v_mfma_f32_16x16x32_bf16 v[46:49], v[142:145], v[180:183], v[46:49]
	v_mfma_f32_16x16x32_bf16 v[42:45], v[160:163], v[180:183], v[42:45]
	v_mfma_f32_16x16x32_bf16 v[30:33], v[142:145], v[196:199], v[30:33]
	v_mfma_f32_16x16x32_bf16 v[26:29], v[160:163], v[196:199], v[26:29]
	v_mfma_f32_16x16x32_bf16 v[14:17], v[142:145], v[204:207], v[14:17]
	v_mfma_f32_16x16x32_bf16 v[10:13], v[160:163], v[204:207], v[10:13]
	v_mfma_f32_16x16x32_bf16 v[62:65], v[146:149], v[172:175], v[62:65]
	v_mfma_f32_16x16x32_bf16 v[58:61], v[164:167], v[172:175], v[58:61]
	v_mfma_f32_16x16x32_bf16 v[46:49], v[146:149], v[192:195], v[46:49]
	v_mfma_f32_16x16x32_bf16 v[42:45], v[164:167], v[192:195], v[42:45]
	v_mfma_f32_16x16x32_bf16 v[30:33], v[146:149], v[200:203], v[30:33]
	v_mfma_f32_16x16x32_bf16 v[26:29], v[164:167], v[200:203], v[26:29]
	v_mfma_f32_16x16x32_bf16 v[14:17], v[146:149], v[208:211], v[14:17]
	v_mfma_f32_16x16x32_bf16 v[10:13], v[164:167], v[208:211], v[10:13]
	s_barrier
; #define PG8_STAGE(bufoff, gbase, voff) do { _Pragma("unroll") for (int _i = 0; _i < 2; ++_i) \
;         __builtin_amdgcn_global_load_lds((const unsigned*)((const char*)(gbase) + (voff)[_i]), (LAS unsigned*)(lds + (bufoff) + ldsw + _i * 8192), 16, 0, 0); } while (0)
; #define PG8_LDA(dst, b, h) do { _Pragma("unroll") for (int m = 0; m < 4; ++m) _Pragma("unroll") for (int k = 0; k < 2; ++k) dst[m][k] = *(const LAS bf16x8*)(lds + PG8_SA(b, h) + aoff + m * 2048 + k * 1024); } while (0)
; #define PG8_LDB(dst, b, h) do { _Pragma("unroll") for (int n = 0; n < 2; ++n) _Pragma("unroll") for (int k = 0; k < 2; ++k) dst[n][k] = *(const LAS bf16x8*)(lds + PG8_SB(b, h) + boff + n * 2048 + k * 1024); } while (0)
; #define PG8_MMA(ai, bj, At, Bt) do { __builtin_amdgcn_s_setprio(1); _Pragma("unroll") for (int m = 0; m < 4; ++m) _Pragma("unroll") for (int n = 0; n < 2; ++n) _Pragma("unroll") for (int k = 0; k < 2; ++k) \
;         acc[ai][bj][m][n] = __builtin_amdgcn_mfma_f32_16x16x32_bf16(Bt[n][k], At[m][k], acc[ai][bj][m][n], 0, 0, 0); __builtin_amdgcn_s_setprio(0); } while (0)
; #define PG8_WAIT_V(n) asm volatile("s_waitcnt vmcnt(" #n ")" ::: "memory")
; #define PG8_WAIT_L(n) asm volatile("s_waitcnt lgkmcnt(" #n ")" ::: "memory")
; #define PG8_BAR __builtin_amdgcn_s_barrier()
; #define PG8_SCHED __builtin_amdgcn_sched_barrier(0)
; template <class Epi, class Sched>
; __device__ __forceinline__ void gemm_phase(const int wv, LAS unsigned char* lds, const Gemm g, const Sched& S, const Epi& E) {
;     ...
;             PG8_STAGE(PG8_SB(0, 1), b2 + hstepB, voffB);
;             PG8_WAIT_V(6); PG8_BAR; PG8_MMA(1, 1, At, B1); PG8_BAR;
;             PG8_LDB(B0, 1, 0); PG8_SCHED; PG8_LDA(At, 1, 0); PG8_STAGE(PG8_SA(0, 1), a2 + hstepA, voffA);
;             PG8_WAIT_L(8); PG8_BAR; PG8_WAIT_L(0); PG8_MMA(0, 0, At, B0); PG8_BAR; PG8_SCHED;
;             PG8_LDB(B1, 1, 1); PG8_STAGE(PG8_SB(1, 0), b3, voffB);
;             PG8_BAR; PG8_WAIT_L(0); PG8_MMA(0, 1, At, B1); PG8_BAR;
;             PG8_LDA(At, 1, 1); PG8_STAGE(PG8_SA(1, 0), a3, voffA);
;             PG8_BAR; PG8_WAIT_L(0); PG8_MMA(1, 0, At, B0); PG8_BAR; PG8_SCHED;
	s_add_u32 s34, s24, 0x40000
	s_addc_u32 s35, s25, 0
	s_add_i32 s31, s52, s44
	v_lshl_add_u64 v[142:143], s[34:35], 0, v[132:133]
	s_mov_b32 m0, s31
	s_nop 0
	global_load_lds_dwordx4 v[142:143], off
	v_lshl_add_u64 v[142:143], s[34:35], 0, v[136:137]
	s_add_i32 m0, s31, 0x2000
	s_nop 0
	global_load_lds_dwordx4 v[142:143], off
	s_waitcnt vmcnt(6)
	s_barrier
	v_mfma_f32_16x16x32_bf16 v[54:57], v[212:215], v[168:171], v[54:57]
	v_mfma_f32_16x16x32_bf16 v[50:53], v[220:223], v[168:171], v[50:53]
	v_mfma_f32_16x16x32_bf16 v[38:41], v[212:215], v[180:183], v[38:41]
	v_mfma_f32_16x16x32_bf16 v[34:37], v[220:223], v[180:183], v[34:37]
	v_mfma_f32_16x16x32_bf16 v[22:25], v[212:215], v[196:199], v[22:25]
	v_mfma_f32_16x16x32_bf16 v[18:21], v[220:223], v[196:199], v[18:21]
	v_mfma_f32_16x16x32_bf16 v[6:9], v[212:215], v[204:207], v[6:9]
	v_mfma_f32_16x16x32_bf16 v[2:5], v[220:223], v[204:207], v[2:5]
	v_mfma_f32_16x16x32_bf16 v[54:57], v[216:219], v[172:175], v[54:57]
	v_mfma_f32_16x16x32_bf16 v[50:53], v[224:227], v[172:175], v[50:53]
	v_mfma_f32_16x16x32_bf16 v[38:41], v[216:219], v[192:195], v[38:41]
	v_mfma_f32_16x16x32_bf16 v[34:37], v[224:227], v[192:195], v[34:37]
	v_mfma_f32_16x16x32_bf16 v[22:25], v[216:219], v[200:203], v[22:25]
	v_mfma_f32_16x16x32_bf16 v[18:21], v[224:227], v[200:203], v[18:21]
	v_mfma_f32_16x16x32_bf16 v[6:9], v[216:219], v[208:211], v[6:9]
	v_mfma_f32_16x16x32_bf16 v[2:5], v[224:227], v[208:211], v[2:5]
	s_add_i32 s31, 0, 0x18000
	v_add_u32_e32 v159, s31, v152
	s_barrier
	ds_read_b128 v[142:145], v159
	ds_read_b128 v[146:149], v159 offset:1024
	ds_read_b128 v[160:163], v159 offset:2048
	ds_read_b128 v[164:167], v159 offset:3072
	s_add_u32 s26, s26, 0x40000
	s_addc_u32 s27, s27, 0
	s_mov_b32 m0, s47
	v_lshl_add_u64 v[212:213], s[26:27], 0, v[130:131]
	ds_read_b128 v[168:171], v158 offset:32768
	ds_read_b128 v[172:175], v158 offset:33792
	ds_read_b128 v[180:183], v158 offset:34816
	ds_read_b128 v[192:195], v158 offset:35840
	ds_read_b128 v[196:199], v158 offset:36864
	ds_read_b128 v[200:203], v158 offset:37888
	ds_read_b128 v[204:207], v158 offset:38912
	ds_read_b128 v[208:211], v158 offset:39936
	global_load_lds_dwordx4 v[212:213], off
	v_lshl_add_u64 v[212:213], s[26:27], 0, v[134:135]
	s_mov_b32 m0, s48
	s_nop 0
	global_load_lds_dwordx4 v[212:213], off
	s_waitcnt lgkmcnt(8)
	s_barrier
	s_waitcnt lgkmcnt(0)
	s_waitcnt lgkmcnt(0)
	v_mfma_f32_16x16x32_bf16 v[126:129], v[142:145], v[168:171], v[126:129]
	v_mfma_f32_16x16x32_bf16 v[122:125], v[160:163], v[168:171], v[122:125]
	v_mfma_f32_16x16x32_bf16 v[110:113], v[142:145], v[180:183], v[110:113]
	v_mfma_f32_16x16x32_bf16 v[106:109], v[160:163], v[180:183], v[106:109]
	v_mfma_f32_16x16x32_bf16 v[94:97], v[142:145], v[196:199], v[94:97]
	v_mfma_f32_16x16x32_bf16 v[90:93], v[160:163], v[196:199], v[90:93]
	v_mfma_f32_16x16x32_bf16 v[78:81], v[142:145], v[204:207], v[78:81]
	v_mfma_f32_16x16x32_bf16 v[74:77], v[160:163], v[204:207], v[74:77]
	v_mfma_f32_16x16x32_bf16 v[126:129], v[146:149], v[172:175], v[126:129]
	v_mfma_f32_16x16x32_bf16 v[122:125], v[164:167], v[172:175], v[122:125]
	v_mfma_f32_16x16x32_bf16 v[110:113], v[146:149], v[192:195], v[110:113]
	v_mfma_f32_16x16x32_bf16 v[106:109], v[164:167], v[192:195], v[106:109]
	v_mfma_f32_16x16x32_bf16 v[94:97], v[146:149], v[200:203], v[94:97]
	v_mfma_f32_16x16x32_bf16 v[90:93], v[164:167], v[200:203], v[90:93]
	v_mfma_f32_16x16x32_bf16 v[78:81], v[146:149], v[208:211], v[78:81]
	v_mfma_f32_16x16x32_bf16 v[74:77], v[164:167], v[208:211], v[74:77]
	s_barrier
	s_add_i32 s26, 0, 0x1c000
	s_add_i32 s27, s31, s44
	v_add_u32_e32 v159, s26, v152
	v_lshl_add_u64 v[150:151], v[150:151], 0, s[88:89]
	s_mov_b32 m0, s27
	ds_read_b128 v[212:215], v159
	ds_read_b128 v[216:219], v159 offset:1024
	ds_read_b128 v[220:223], v159 offset:2048
	ds_read_b128 v[224:227], v159 offset:3072
	global_load_lds_dwordx4 v[150:151], off
	v_lshl_add_u64 v[150:151], v[176:177], 0, s[88:89]
	s_add_i32 m0, s27, 0x2000
	s_nop 0
	global_load_lds_dwordx4 v[150:151], off
	s_barrier
; #define PG8_STAGE(bufoff, gbase, voff) do { _Pragma("unroll") for (int _i = 0; _i < 2; ++_i) \
;         __builtin_amdgcn_global_load_lds((const unsigned*)((const char*)(gbase) + (voff)[_i]), (LAS unsigned*)(lds + (bufoff) + ldsw + _i * 8192), 16, 0, 0); } while (0)
; #define PG8_LDA(dst, b, h) do { _Pragma("unroll") for (int m = 0; m < 4; ++m) _Pragma("unroll") for (int k = 0; k < 2; ++k) dst[m][k] = *(const LAS bf16x8*)(lds + PG8_SA(b, h) + aoff + m * 2048 + k * 1024); } while (0)
; #define PG8_MMA(ai, bj, At, Bt) do { __builtin_amdgcn_s_setprio(1); _Pragma("unroll") for (int m = 0; m < 4; ++m) _Pragma("unroll") for (int n = 0; n < 2; ++n) _Pragma("unroll") for (int k = 0; k < 2; ++k) \
;         acc[ai][bj][m][n] = __builtin_amdgcn_mfma_f32_16x16x32_bf16(Bt[n][k], At[m][k], acc[ai][bj][m][n], 0, 0, 0); __builtin_amdgcn_s_setprio(0); } while (0)
; #define PG8_WAIT_V(n) asm volatile("s_waitcnt vmcnt(" #n ")" ::: "memory")
; #define PG8_WAIT_L(n) asm volatile("s_waitcnt lgkmcnt(" #n ")" ::: "memory")
; #define PG8_BAR __builtin_amdgcn_s_barrier()
; #define PG8_SCHED __builtin_amdgcn_sched_barrier(0)
; template <class Epi, class Sched>
; __device__ __forceinline__ void gemm_phase(const int wv, LAS unsigned char* lds, const Gemm g, const Sched& S, const Epi& E) {
;     ...
;             PG8_LDA(At, 1, 1); PG8_STAGE(PG8_SA(1, 0), a3, voffA);
;             PG8_BAR; PG8_WAIT_L(0); PG8_MMA(1, 0, At, B0); PG8_BAR; PG8_SCHED;
;             PG8_STAGE(PG8_SB(1, 1), b3 + hstepB, voffB);
;             PG8_WAIT_V(6); PG8_BAR; PG8_MMA(1, 1, At, B1); PG8_BAR;
;         }
;     __device__ __forceinline__ void operator()(const f32x4 (&acc)[2][2][4][2], const Unit& u, int wr, int wc, int fr, int fq) const {
;         const int row0 = (u.pm >> 6) * TB + (u.pm & 63) * 256 + wr * 64 + fr; const int pn = u.pn;
;         bf16_t* base; int ld, colt, act;
;         if (pn < 34) { base = qkvr; ld = QKVR_LD; colt = pn * 256; act = 0; }
;         else if (pn < 42) { base = gr; ld = 2048; colt = (pn - 34) * 256; act = 1; }
;         else { base = gates; ld = 2048; colt = (pn - 42) * 256; act = 2; }
	s_waitcnt lgkmcnt(0)
	s_waitcnt lgkmcnt(0)
	v_mfma_f32_16x16x32_bf16 v[118:121], v[212:215], v[168:171], v[118:121]
	v_mfma_f32_16x16x32_bf16 v[114:117], v[220:223], v[168:171], v[114:117]
	v_mfma_f32_16x16x32_bf16 v[102:105], v[212:215], v[180:183], v[102:105]
	v_mfma_f32_16x16x32_bf16 v[98:101], v[220:223], v[180:183], v[98:101]
	v_mfma_f32_16x16x32_bf16 v[86:89], v[212:215], v[196:199], v[86:89]
	v_mfma_f32_16x16x32_bf16 v[82:85], v[220:223], v[196:199], v[82:85]
	v_mfma_f32_16x16x32_bf16 v[70:73], v[212:215], v[204:207], v[70:73]
	v_mfma_f32_16x16x32_bf16 v[66:69], v[220:223], v[204:207], v[66:69]
	v_mfma_f32_16x16x32_bf16 v[118:121], v[216:219], v[172:175], v[118:121]
	v_mfma_f32_16x16x32_bf16 v[114:117], v[224:227], v[172:175], v[114:117]
	v_mfma_f32_16x16x32_bf16 v[102:105], v[216:219], v[192:195], v[102:105]
	v_mfma_f32_16x16x32_bf16 v[98:101], v[224:227], v[192:195], v[98:101]
	v_mfma_f32_16x16x32_bf16 v[86:89], v[216:219], v[200:203], v[86:89]
	v_mfma_f32_16x16x32_bf16 v[82:85], v[224:227], v[200:203], v[82:85]
	v_mfma_f32_16x16x32_bf16 v[70:73], v[216:219], v[208:211], v[70:73]
	v_mfma_f32_16x16x32_bf16 v[66:69], v[224:227], v[208:211], v[66:69]
	s_mov_b32 m0, s49
	v_lshl_add_u64 v[150:151], v[228:229], 0, s[88:89]
	s_barrier
	ds_read_b128 v[168:171], v158 offset:49152
	ds_read_b128 v[172:175], v158 offset:50176
	ds_read_b128 v[180:183], v158 offset:51200
	ds_read_b128 v[192:195], v158 offset:52224
	ds_read_b128 v[196:199], v158 offset:53248
	ds_read_b128 v[200:203], v158 offset:54272
	ds_read_b128 v[204:207], v158 offset:55296
	ds_read_b128 v[208:211], v158 offset:56320
	global_load_lds_dwordx4 v[150:151], off
	v_lshl_add_u64 v[150:151], v[230:231], 0, s[88:89]
	s_mov_b32 m0, s50
	s_nop 0
	global_load_lds_dwordx4 v[150:151], off
	s_barrier
	s_waitcnt lgkmcnt(0)
	s_waitcnt lgkmcnt(0)
	v_mfma_f32_16x16x32_bf16 v[62:65], v[142:145], v[168:171], v[62:65]
	v_mfma_f32_16x16x32_bf16 v[58:61], v[160:163], v[168:171], v[58:61]
	v_mfma_f32_16x16x32_bf16 v[46:49], v[142:145], v[180:183], v[46:49]
	v_mfma_f32_16x16x32_bf16 v[42:45], v[160:163], v[180:183], v[42:45]
	v_mfma_f32_16x16x32_bf16 v[30:33], v[142:145], v[196:199], v[30:33]
	v_mfma_f32_16x16x32_bf16 v[26:29], v[160:163], v[196:199], v[26:29]
	v_mfma_f32_16x16x32_bf16 v[14:17], v[142:145], v[204:207], v[14:17]
	v_mfma_f32_16x16x32_bf16 v[10:13], v[160:163], v[204:207], v[10:13]
	v_mfma_f32_16x16x32_bf16 v[62:65], v[146:149], v[172:175], v[62:65]
	v_mfma_f32_16x16x32_bf16 v[58:61], v[164:167], v[172:175], v[58:61]
	v_mfma_f32_16x16x32_bf16 v[46:49], v[146:149], v[192:195], v[46:49]
	v_mfma_f32_16x16x32_bf16 v[42:45], v[164:167], v[192:195], v[42:45]
	v_mfma_f32_16x16x32_bf16 v[30:33], v[146:149], v[200:203], v[30:33]
	v_mfma_f32_16x16x32_bf16 v[26:29], v[164:167], v[200:203], v[26:29]
	v_mfma_f32_16x16x32_bf16 v[14:17], v[146:149], v[208:211], v[14:17]
	v_mfma_f32_16x16x32_bf16 v[10:13], v[164:167], v[208:211], v[10:13]
	s_barrier
	s_add_u32 s24, s24, 0x40080
	s_addc_u32 s25, s25, 0
	s_add_i32 s26, s26, s44
	v_lshl_add_u64 v[142:143], s[24:25], 0, v[132:133]
	s_mov_b32 m0, s26
	s_nop 0
	global_load_lds_dwordx4 v[142:143], off
	v_lshl_add_u64 v[142:143], s[24:25], 0, v[136:137]
	s_add_i32 m0, s26, 0x2000
	s_nop 0
	global_load_lds_dwordx4 v[142:143], off
	s_waitcnt vmcnt(6)
	s_barrier
	v_mfma_f32_16x16x32_bf16 v[54:57], v[212:215], v[168:171], v[54:57]
	v_mfma_f32_16x16x32_bf16 v[50:53], v[220:223], v[168:171], v[50:53]
	v_mfma_f32_16x16x32_bf16 v[38:41], v[212:215], v[180:183], v[38:41]
	v_mfma_f32_16x16x32_bf16 v[34:37], v[220:223], v[180:183], v[34:37]
	v_mfma_f32_16x16x32_bf16 v[22:25], v[212:215], v[196:199], v[22:25]
	v_mfma_f32_16x16x32_bf16 v[18:21], v[220:223], v[196:199], v[18:21]
	v_mfma_f32_16x16x32_bf16 v[6:9], v[212:215], v[204:207], v[6:9]
	v_mfma_f32_16x16x32_bf16 v[2:5], v[220:223], v[204:207], v[2:5]
	v_mfma_f32_16x16x32_bf16 v[54:57], v[216:219], v[172:175], v[54:57]
	v_mfma_f32_16x16x32_bf16 v[50:53], v[224:227], v[172:175], v[50:53]
	v_mfma_f32_16x16x32_bf16 v[38:41], v[216:219], v[192:195], v[38:41]
	v_mfma_f32_16x16x32_bf16 v[34:37], v[224:227], v[192:195], v[34:37]
	v_mfma_f32_16x16x32_bf16 v[22:25], v[216:219], v[200:203], v[22:25]
	v_mfma_f32_16x16x32_bf16 v[18:21], v[224:227], v[200:203], v[18:21]
	v_mfma_f32_16x16x32_bf16 v[6:9], v[216:219], v[208:211], v[6:9]
	v_mfma_f32_16x16x32_bf16 v[2:5], v[224:227], v[208:211], v[2:5]
	s_add_i32 s30, s30, 2
	s_add_u32 s22, s22, 0x100
	s_addc_u32 s23, s23, 0
	s_add_u32 s28, s28, 0x100
	s_addc_u32 s29, s29, 0
	s_cmp_gt_u32 s30, 13
	s_barrier
	s_cbranch_scc0 .LBB0_147
	s_cmp_gt_i32 s0, 33
	s_mov_b64 s[22:23], -1
	s_cbranch_scc0 .LBB0_153
	s_lshl_b32 s1, s0, 8
	s_cmp_gt_u32 s0, 41
	s_mov_b64 s[28:29], -1
	s_mov_b64 s[24:25], -1
	s_cbranch_scc0 .LBB0_151
	s_add_i32 s3, s1, 0xffffd600
	s_mov_b64 s[24:25], 0

; #define PG8_WAIT_V(n) asm volatile("s_waitcnt vmcnt(" #n ")" ::: "memory")
; #define PG8_BAR __builtin_amdgcn_s_barrier()
; template <class Epi, class Sched>
; __device__ __forceinline__ void gemm_phase(const int wv, LAS unsigned char* lds, const Gemm g, const Sched& S, const Epi& E) {
;     ...
;     PG8_WAIT_V(0);
;     if (wr == 0) PG8_BAR;
;     PG8_BAR;
; __device__ __forceinline__ void xcd_barrier(const int wv, const XcdBarrier& b) {
;     asm volatile("s_waitcnt vmcnt(0)" ::: "memory");
;     __syncthreads();
;     if (TIDX == 0) {
;         unsigned long long barq = (unsigned long long)b.bar; asm volatile("" : "+s"(barq));
;         unsigned* bar = (unsigned*)barq;
;         __builtin_amdgcn_s_waitcnt(0);
;         unsigned nloc = b.st[0], nx = b.st[1];
;         if (nloc == 0u) { xcd_barrier_complete(bar, b.x, nloc, nx); b.st[0] = nloc; b.st[1] = nx; }
.LBB0_266:
	s_setprio 0
	s_waitcnt vmcnt(0)
	s_waitcnt vmcnt(0) lgkmcnt(0)
	s_barrier
	v_mbcnt_lo_u32_b32 v1, -1, 0
	v_mbcnt_hi_u32_b32 v1, -1, v1
	s_nop 0
	v_sub_u32_e32 v1, 0, v1
	v_cmp_eq_u32_e32 vcc, s53, v1
	s_and_saveexec_b64 s[0:1], vcc
	s_cbranch_execz .LBB0_310
	s_mov_b64 s[2:3], s[58:59]
	v_mov_b32_e32 v1, s73
	s_waitcnt vmcnt(0) expcnt(0) lgkmcnt(0)
	ds_read_b32 v6, v1
	v_mov_b32_e32 v1, s74
	ds_read_b32 v4, v1
	s_waitcnt lgkmcnt(1)
	v_cmp_ne_u32_e32 vcc, 0, v6
	s_cbranch_vccnz .LBB0_281
	s_add_u32 s4, s2, 0x1000
	s_addc_u32 s5, s3, 0
	s_add_u32 s6, s2, 0x1100
	s_addc_u32 s7, s3, 0
	s_add_u32 s8, s2, 0x1200
	s_addc_u32 s9, s3, 0
	s_add_u32 s10, s2, 0x1300
	s_addc_u32 s11, s3, 0
	s_mov_b32 s30, 1
	s_mov_b64 s[12:13], 0
	s_branch .LBB0_271

; #define PG8_STAGE(bufoff, gbase, voff) do { _Pragma("unroll") for (int _i = 0; _i < 2; ++_i) \
;         __builtin_amdgcn_global_load_lds((const unsigned*)((const char*)(gbase) + (voff)[_i]), (LAS unsigned*)(lds + (bufoff) + ldsw + _i * 8192), 16, 0, 0); } while (0)
; #define PG8_LDA(dst, b, h) do { _Pragma("unroll") for (int m = 0; m < 4; ++m) _Pragma("unroll") for (int k = 0; k < 2; ++k) dst[m][k] = *(const LAS bf16x8*)(lds + PG8_SA(b, h) + aoff + m * 2048 + k * 1024); } while (0)
; #define PG8_LDB(dst, b, h) do { _Pragma("unroll") for (int n = 0; n < 2; ++n) _Pragma("unroll") for (int k = 0; k < 2; ++k) dst[n][k] = *(const LAS bf16x8*)(lds + PG8_SB(b, h) + boff + n * 2048 + k * 1024); } while (0)
; #define PG8_MMA(ai, bj, At, Bt) do { __builtin_amdgcn_s_setprio(1); _Pragma("unroll") for (int m = 0; m < 4; ++m) _Pragma("unroll") for (int n = 0; n < 2; ++n) _Pragma("unroll") for (int k = 0; k < 2; ++k) \
;         acc[ai][bj][m][n] = __builtin_amdgcn_mfma_f32_16x16x32_bf16(Bt[n][k], At[m][k], acc[ai][bj][m][n], 0, 0, 0); __builtin_amdgcn_s_setprio(0); } while (0)
; #define PG8_WAIT_V(n) asm volatile("s_waitcnt vmcnt(" #n ")" ::: "memory")
; #define PG8_WAIT_L(n) asm volatile("s_waitcnt lgkmcnt(" #n ")" ::: "memory")
; #define PG8_BAR __builtin_amdgcn_s_barrier()
; #define PG8_SCHED __builtin_amdgcn_sched_barrier(0)
; template <class Epi, class Sched>
; __device__ __forceinline__ void gemm_phase(const int wv, LAS unsigned char* lds, const Gemm g, const Sched& S, const Epi& E) {
;     ...
;             PG8_LDB(B0, 0, 0); PG8_SCHED; PG8_LDA(At, 0, 0); PG8_STAGE(PG8_SA(1, 1), a1 + hstepA, voffA);
;             PG8_WAIT_L(8); PG8_BAR; PG8_WAIT_L(0); PG8_MMA(0, 0, At, B0); PG8_BAR; PG8_SCHED;
;             PG8_LDB(B1, 0, 1); PG8_STAGE(PG8_SB(0, 0), b2, voffB);
;             PG8_BAR; PG8_WAIT_L(0); PG8_MMA(0, 1, At, B1); PG8_BAR;
;             PG8_LDA(At, 0, 1); PG8_STAGE(PG8_SA(0, 0), a2, voffA);
;             PG8_BAR; PG8_WAIT_L(0); PG8_MMA(1, 0, At, B0); PG8_BAR; PG8_SCHED;
;             PG8_STAGE(PG8_SB(0, 1), b2 + hstepB, voffB);
;             PG8_WAIT_V(6); PG8_BAR; PG8_MMA(1, 1, At, B1); PG8_BAR;
.LBB0_577:
	ds_read_b128 v[144:147], v151
	ds_read_b128 v[154:157], v151 offset:1024
	ds_read_b128 v[158:161], v151 offset:2048
	ds_read_b128 v[162:165], v151 offset:3072
	s_add_u32 s22, s20, 0xfffe0080
	s_addc_u32 s23, s21, -1
	s_cmp_eq_u32 s46, 4
	s_cselect_b32 s25, s13, s23
	s_cselect_b32 s24, s42, s22
	s_cselect_b32 s23, s11, s45
	s_cselect_b32 s22, s43, s44
	v_lshl_add_u64 v[200:201], s[20:21], 0, v[136:137]
	s_add_i32 m0, s19, 0xc000
	ds_read_b128 v[166:169], v152
	ds_read_b128 v[170:173], v152 offset:1024
	ds_read_b128 v[174:177], v152 offset:2048
	ds_read_b128 v[180:183], v152 offset:3072
	ds_read_b128 v[184:187], v152 offset:4096
	ds_read_b128 v[188:191], v152 offset:5120
	ds_read_b128 v[192:195], v152 offset:6144
	ds_read_b128 v[196:199], v152 offset:7168
	global_load_lds_dwordx4 v[200:201], off
	v_lshl_add_u64 v[200:201], s[20:21], 0, v[138:139]
	s_add_i32 m0, s19, 0xe000
	s_nop 0
	global_load_lds_dwordx4 v[200:201], off
	s_waitcnt lgkmcnt(8)
	s_barrier
	s_waitcnt lgkmcnt(0)
	s_waitcnt lgkmcnt(0)
	v_mfma_f32_16x16x32_bf16 v[124:127], v[144:147], v[166:169], v[124:127]
	v_mfma_f32_16x16x32_bf16 v[120:123], v[158:161], v[166:169], v[120:123]
	v_mfma_f32_16x16x32_bf16 v[116:119], v[144:147], v[174:177], v[116:119]
	v_mfma_f32_16x16x32_bf16 v[104:107], v[158:161], v[174:177], v[104:107]
	v_mfma_f32_16x16x32_bf16 v[96:99], v[144:147], v[184:187], v[96:99]
	v_mfma_f32_16x16x32_bf16 v[88:91], v[158:161], v[184:187], v[88:91]
	v_mfma_f32_16x16x32_bf16 v[80:83], v[144:147], v[192:195], v[80:83]
	v_mfma_f32_16x16x32_bf16 v[72:75], v[158:161], v[192:195], v[72:75]
	v_mfma_f32_16x16x32_bf16 v[124:127], v[154:157], v[170:173], v[124:127]
	v_mfma_f32_16x16x32_bf16 v[120:123], v[162:165], v[170:173], v[120:123]
	v_mfma_f32_16x16x32_bf16 v[116:119], v[154:157], v[180:183], v[116:119]
	v_mfma_f32_16x16x32_bf16 v[104:107], v[162:165], v[180:183], v[104:107]
	v_mfma_f32_16x16x32_bf16 v[96:99], v[154:157], v[188:191], v[96:99]
	v_mfma_f32_16x16x32_bf16 v[88:91], v[162:165], v[188:191], v[88:91]
	v_mfma_f32_16x16x32_bf16 v[80:83], v[154:157], v[196:199], v[80:83]
	v_mfma_f32_16x16x32_bf16 v[72:75], v[162:165], v[196:199], v[72:75]
	s_barrier
	s_add_i32 s47, s39, s31
	v_lshl_add_u64 v[216:217], s[22:23], 0, v[130:131]
	s_mov_b32 m0, s47
	ds_read_b128 v[200:203], v153
	ds_read_b128 v[204:207], v153 offset:1024
	ds_read_b128 v[208:211], v153 offset:2048
	ds_read_b128 v[212:215], v153 offset:3072
	global_load_lds_dwordx4 v[216:217], off
	v_lshl_add_u64 v[218:219], s[22:23], 0, v[134:135]
	s_add_i32 m0, s47, 0x2000
	s_nop 0
	global_load_lds_dwordx4 v[218:219], off
	s_barrier
	s_waitcnt lgkmcnt(0)
	s_waitcnt lgkmcnt(0)
	v_mfma_f32_16x16x32_bf16 v[112:115], v[200:203], v[166:169], v[112:115]
	v_mfma_f32_16x16x32_bf16 v[108:111], v[208:211], v[166:169], v[108:111]
	v_mfma_f32_16x16x32_bf16 v[100:103], v[200:203], v[174:177], v[100:103]
	v_mfma_f32_16x16x32_bf16 v[92:95], v[208:211], v[174:177], v[92:95]
	v_mfma_f32_16x16x32_bf16 v[84:87], v[200:203], v[184:187], v[84:87]
	v_mfma_f32_16x16x32_bf16 v[76:79], v[208:211], v[184:187], v[76:79]
	v_mfma_f32_16x16x32_bf16 v[68:71], v[200:203], v[192:195], v[68:71]
	v_mfma_f32_16x16x32_bf16 v[64:67], v[208:211], v[192:195], v[64:67]
	v_mfma_f32_16x16x32_bf16 v[112:115], v[204:207], v[170:173], v[112:115]
	v_mfma_f32_16x16x32_bf16 v[108:111], v[212:215], v[170:173], v[108:111]
	v_mfma_f32_16x16x32_bf16 v[100:103], v[204:207], v[180:183], v[100:103]
	v_mfma_f32_16x16x32_bf16 v[92:95], v[212:215], v[180:183], v[92:95]
	v_mfma_f32_16x16x32_bf16 v[84:87], v[204:207], v[188:191], v[84:87]
	v_mfma_f32_16x16x32_bf16 v[76:79], v[212:215], v[188:191], v[76:79]
	v_mfma_f32_16x16x32_bf16 v[68:71], v[204:207], v[196:199], v[68:71]
	v_mfma_f32_16x16x32_bf16 v[64:67], v[212:215], v[196:199], v[64:67]
	s_mov_b32 m0, s19
	v_lshl_add_u64 v[220:221], s[24:25], 0, v[128:129]
	s_barrier
	ds_read_b128 v[166:169], v152 offset:16384
	ds_read_b128 v[170:173], v152 offset:17408
	ds_read_b128 v[174:177], v152 offset:18432
	ds_read_b128 v[180:183], v152 offset:19456
	ds_read_b128 v[184:187], v152 offset:20480
	ds_read_b128 v[188:191], v152 offset:21504
	ds_read_b128 v[192:195], v152 offset:22528
	ds_read_b128 v[196:199], v152 offset:23552
	global_load_lds_dwordx4 v[220:221], off
	v_lshl_add_u64 v[222:223], s[24:25], 0, v[132:133]
	s_mov_b32 m0, s33
	s_nop 0
	global_load_lds_dwordx4 v[222:223], off
	s_barrier
	s_waitcnt lgkmcnt(0)
	s_waitcnt lgkmcnt(0)
	v_mfma_f32_16x16x32_bf16 v[60:63], v[144:147], v[166:169], v[60:63]
	v_mfma_f32_16x16x32_bf16 v[56:59], v[158:161], v[166:169], v[56:59]
	v_mfma_f32_16x16x32_bf16 v[48:51], v[144:147], v[174:177], v[48:51]
	v_mfma_f32_16x16x32_bf16 v[40:43], v[158:161], v[174:177], v[40:43]
	v_mfma_f32_16x16x32_bf16 v[32:35], v[144:147], v[184:187], v[32:35]
	v_mfma_f32_16x16x32_bf16 v[24:27], v[158:161], v[184:187], v[24:27]
	v_mfma_f32_16x16x32_bf16 v[16:19], v[144:147], v[192:195], v[16:19]
	v_mfma_f32_16x16x32_bf16 v[8:11], v[158:161], v[192:195], v[8:11]
	v_mfma_f32_16x16x32_bf16 v[60:63], v[154:157], v[170:173], v[60:63]
	v_mfma_f32_16x16x32_bf16 v[56:59], v[162:165], v[170:173], v[56:59]
	v_mfma_f32_16x16x32_bf16 v[48:51], v[154:157], v[180:183], v[48:51]
	v_mfma_f32_16x16x32_bf16 v[40:43], v[162:165], v[180:183], v[40:43]
	v_mfma_f32_16x16x32_bf16 v[32:35], v[154:157], v[188:191], v[32:35]
	v_mfma_f32_16x16x32_bf16 v[24:27], v[162:165], v[188:191], v[24:27]
	v_mfma_f32_16x16x32_bf16 v[16:19], v[154:157], v[196:199], v[16:19]
	v_mfma_f32_16x16x32_bf16 v[8:11], v[162:165], v[196:199], v[8:11]
	s_barrier
; #define PG8_STAGE(bufoff, gbase, voff) do { _Pragma("unroll") for (int _i = 0; _i < 2; ++_i) \
;         __builtin_amdgcn_global_load_lds((const unsigned*)((const char*)(gbase) + (voff)[_i]), (LAS unsigned*)(lds + (bufoff) + ldsw + _i * 8192), 16, 0, 0); } while (0)
; #define PG8_LDA(dst, b, h) do { _Pragma("unroll") for (int m = 0; m < 4; ++m) _Pragma("unroll") for (int k = 0; k < 2; ++k) dst[m][k] = *(const LAS bf16x8*)(lds + PG8_SA(b, h) + aoff + m * 2048 + k * 1024); } while (0)
; #define PG8_LDB(dst, b, h) do { _Pragma("unroll") for (int n = 0; n < 2; ++n) _Pragma("unroll") for (int k = 0; k < 2; ++k) dst[n][k] = *(const LAS bf16x8*)(lds + PG8_SB(b, h) + boff + n * 2048 + k * 1024); } while (0)
; #define PG8_MMA(ai, bj, At, Bt) do { __builtin_amdgcn_s_setprio(1); _Pragma("unroll") for (int m = 0; m < 4; ++m) _Pragma("unroll") for (int n = 0; n < 2; ++n) _Pragma("unroll") for (int k = 0; k < 2; ++k) \
;         acc[ai][bj][m][n] = __builtin_amdgcn_mfma_f32_16x16x32_bf16(Bt[n][k], At[m][k], acc[ai][bj][m][n], 0, 0, 0); __builtin_amdgcn_s_setprio(0); } while (0)
; #define PG8_WAIT_V(n) asm volatile("s_waitcnt vmcnt(" #n ")" ::: "memory")
; #define PG8_WAIT_L(n) asm volatile("s_waitcnt lgkmcnt(" #n ")" ::: "memory")
; #define PG8_BAR __builtin_amdgcn_s_barrier()
; #define PG8_SCHED __builtin_amdgcn_sched_barrier(0)
; template <class Epi, class Sched>
; __device__ __forceinline__ void gemm_phase(const int wv, LAS unsigned char* lds, const Gemm g, const Sched& S, const Epi& E) {
;     ...
;             PG8_STAGE(PG8_SB(0, 1), b2 + hstepB, voffB);
;             PG8_WAIT_V(6); PG8_BAR; PG8_MMA(1, 1, At, B1); PG8_BAR;
;             PG8_LDB(B0, 1, 0); PG8_SCHED; PG8_LDA(At, 1, 0); PG8_STAGE(PG8_SA(0, 1), a2 + hstepA, voffA);
;             PG8_WAIT_L(8); PG8_BAR; PG8_WAIT_L(0); PG8_MMA(0, 0, At, B0); PG8_BAR; PG8_SCHED;
;             PG8_LDB(B1, 1, 1); PG8_STAGE(PG8_SB(1, 0), b3, voffB);
;             PG8_BAR; PG8_WAIT_L(0); PG8_MMA(0, 1, At, B1); PG8_BAR;
;             PG8_LDA(At, 1, 1); PG8_STAGE(PG8_SA(1, 0), a3, voffA);
	s_add_u32 s48, s22, 0x20000
	s_addc_u32 s49, s23, 0
	s_add_i32 s47, s40, s31
	v_lshl_add_u64 v[144:145], s[48:49], 0, v[130:131]
	s_mov_b32 m0, s47
	s_nop 0
	global_load_lds_dwordx4 v[144:145], off
	v_lshl_add_u64 v[144:145], s[48:49], 0, v[134:135]
	s_add_i32 m0, s47, 0x2000
	s_nop 0
	global_load_lds_dwordx4 v[144:145], off
	s_waitcnt vmcnt(6)
	s_barrier
	v_mfma_f32_16x16x32_bf16 v[52:55], v[200:203], v[166:169], v[52:55]
	v_mfma_f32_16x16x32_bf16 v[44:47], v[208:211], v[166:169], v[44:47]
	v_mfma_f32_16x16x32_bf16 v[36:39], v[200:203], v[174:177], v[36:39]
	v_mfma_f32_16x16x32_bf16 v[28:31], v[208:211], v[174:177], v[28:31]
	v_mfma_f32_16x16x32_bf16 v[20:23], v[200:203], v[184:187], v[20:23]
	v_mfma_f32_16x16x32_bf16 v[12:15], v[208:211], v[184:187], v[12:15]
	v_mfma_f32_16x16x32_bf16 v[4:7], v[200:203], v[192:195], v[4:7]
	v_mfma_f32_16x16x32_bf16 v[0:3], v[208:211], v[192:195], v[0:3]
	v_mfma_f32_16x16x32_bf16 v[52:55], v[204:207], v[170:173], v[52:55]
	v_mfma_f32_16x16x32_bf16 v[44:47], v[212:215], v[170:173], v[44:47]
	v_mfma_f32_16x16x32_bf16 v[36:39], v[204:207], v[180:183], v[36:39]
	v_mfma_f32_16x16x32_bf16 v[28:31], v[212:215], v[180:183], v[28:31]
	v_mfma_f32_16x16x32_bf16 v[20:23], v[204:207], v[188:191], v[20:23]
	v_mfma_f32_16x16x32_bf16 v[12:15], v[212:215], v[188:191], v[12:15]
	v_mfma_f32_16x16x32_bf16 v[4:7], v[204:207], v[196:199], v[4:7]
	v_mfma_f32_16x16x32_bf16 v[0:3], v[212:215], v[196:199], v[0:3]
	s_add_i32 s47, 0, 0x18000
	v_add_u32_e32 v162, s47, v149
	s_barrier
	ds_read_b128 v[144:147], v162
	ds_read_b128 v[154:157], v162 offset:1024
	ds_read_b128 v[158:161], v162 offset:2048
	ds_read_b128 v[162:165], v162 offset:3072
	s_add_u32 s24, s24, 0x20000
	s_addc_u32 s25, s25, 0
	s_mov_b32 m0, s34
	v_lshl_add_u64 v[200:201], s[24:25], 0, v[128:129]
	ds_read_b128 v[166:169], v152 offset:32768
	ds_read_b128 v[170:173], v152 offset:33792
	ds_read_b128 v[174:177], v152 offset:34816
	ds_read_b128 v[180:183], v152 offset:35840
	ds_read_b128 v[184:187], v152 offset:36864
	ds_read_b128 v[188:191], v152 offset:37888
	ds_read_b128 v[192:195], v152 offset:38912
	ds_read_b128 v[196:199], v152 offset:39936
	global_load_lds_dwordx4 v[200:201], off
	v_lshl_add_u64 v[200:201], s[24:25], 0, v[132:133]
	s_mov_b32 m0, s35
	s_nop 0
	global_load_lds_dwordx4 v[200:201], off
	s_waitcnt lgkmcnt(8)
	s_barrier
	s_waitcnt lgkmcnt(0)
	s_waitcnt lgkmcnt(0)
	v_mfma_f32_16x16x32_bf16 v[124:127], v[144:147], v[166:169], v[124:127]
	v_mfma_f32_16x16x32_bf16 v[120:123], v[158:161], v[166:169], v[120:123]
	v_mfma_f32_16x16x32_bf16 v[116:119], v[144:147], v[174:177], v[116:119]
	v_mfma_f32_16x16x32_bf16 v[104:107], v[158:161], v[174:177], v[104:107]
	v_mfma_f32_16x16x32_bf16 v[96:99], v[144:147], v[184:187], v[96:99]
	v_mfma_f32_16x16x32_bf16 v[88:91], v[158:161], v[184:187], v[88:91]
	v_mfma_f32_16x16x32_bf16 v[80:83], v[144:147], v[192:195], v[80:83]
	v_mfma_f32_16x16x32_bf16 v[72:75], v[158:161], v[192:195], v[72:75]
	v_mfma_f32_16x16x32_bf16 v[124:127], v[154:157], v[170:173], v[124:127]
	v_mfma_f32_16x16x32_bf16 v[120:123], v[162:165], v[170:173], v[120:123]
	v_mfma_f32_16x16x32_bf16 v[116:119], v[154:157], v[180:183], v[116:119]
	v_mfma_f32_16x16x32_bf16 v[104:107], v[162:165], v[180:183], v[104:107]
	v_mfma_f32_16x16x32_bf16 v[96:99], v[154:157], v[188:191], v[96:99]
	v_mfma_f32_16x16x32_bf16 v[88:91], v[162:165], v[188:191], v[88:91]
	v_mfma_f32_16x16x32_bf16 v[80:83], v[154:157], v[196:199], v[80:83]
	v_mfma_f32_16x16x32_bf16 v[72:75], v[162:165], v[196:199], v[72:75]
	s_barrier
	s_add_i32 s24, 0, 0x1c000
	s_add_i32 s25, s47, s31
	v_add_u32_e32 v212, s24, v149
	v_lshl_add_u64 v[216:217], v[216:217], 0, s[8:9]
	s_mov_b32 m0, s25
	ds_read_b128 v[200:203], v212
	ds_read_b128 v[204:207], v212 offset:1024
	ds_read_b128 v[208:211], v212 offset:2048
	ds_read_b128 v[212:215], v212 offset:3072
	global_load_lds_dwordx4 v[216:217], off
	v_lshl_add_u64 v[216:217], v[218:219], 0, s[8:9]
	s_add_i32 m0, s25, 0x2000
	s_nop 0
	global_load_lds_dwordx4 v[216:217], off
	s_barrier
	s_waitcnt lgkmcnt(0)
	s_waitcnt lgkmcnt(0)
	v_mfma_f32_16x16x32_bf16 v[112:115], v[200:203], v[166:169], v[112:115]
	v_mfma_f32_16x16x32_bf16 v[108:111], v[208:211], v[166:169], v[108:111]
	v_mfma_f32_16x16x32_bf16 v[100:103], v[200:203], v[174:177], v[100:103]
	v_mfma_f32_16x16x32_bf16 v[92:95], v[208:211], v[174:177], v[92:95]
	v_mfma_f32_16x16x32_bf16 v[84:87], v[200:203], v[184:187], v[84:87]
	v_mfma_f32_16x16x32_bf16 v[76:79], v[208:211], v[184:187], v[76:79]
	v_mfma_f32_16x16x32_bf16 v[68:71], v[200:203], v[192:195], v[68:71]
	v_mfma_f32_16x16x32_bf16 v[64:67], v[208:211], v[192:195], v[64:67]
	v_mfma_f32_16x16x32_bf16 v[112:115], v[204:207], v[170:173], v[112:115]
	v_mfma_f32_16x16x32_bf16 v[108:111], v[212:215], v[170:173], v[108:111]
	v_mfma_f32_16x16x32_bf16 v[100:103], v[204:207], v[180:183], v[100:103]
	v_mfma_f32_16x16x32_bf16 v[92:95], v[212:215], v[180:183], v[92:95]
	v_mfma_f32_16x16x32_bf16 v[84:87], v[204:207], v[188:191], v[84:87]
	v_mfma_f32_16x16x32_bf16 v[76:79], v[212:215], v[188:191], v[76:79]
	v_mfma_f32_16x16x32_bf16 v[68:71], v[204:207], v[196:199], v[68:71]
	v_mfma_f32_16x16x32_bf16 v[64:67], v[212:215], v[196:199], v[64:67]
	s_mov_b32 m0, s37
	v_lshl_add_u64 v[216:217], v[220:221], 0, s[8:9]
	s_barrier
	ds_read_b128 v[166:169], v152 offset:49152
	ds_read_b128 v[170:173], v152 offset:50176
	ds_read_b128 v[174:177], v152 offset:51200
	ds_read_b128 v[180:183], v152 offset:52224
	ds_read_b128 v[184:187], v152 offset:53248
	ds_read_b128 v[188:191], v152 offset:54272
	ds_read_b128 v[192:195], v152 offset:55296
	ds_read_b128 v[196:199], v152 offset:56320
	global_load_lds_dwordx4 v[216:217], off
	v_lshl_add_u64 v[216:217], v[222:223], 0, s[8:9]
	s_mov_b32 m0, s38
	s_nop 0
	global_load_lds_dwordx4 v[216:217], off
	s_barrier
; #define PG8_STAGE(bufoff, gbase, voff) do { _Pragma("unroll") for (int _i = 0; _i < 2; ++_i) \
;         __builtin_amdgcn_global_load_lds((const unsigned*)((const char*)(gbase) + (voff)[_i]), (LAS unsigned*)(lds + (bufoff) + ldsw + _i * 8192), 16, 0, 0); } while (0)
; #define PG8_LDA(dst, b, h) do { _Pragma("unroll") for (int m = 0; m < 4; ++m) _Pragma("unroll") for (int k = 0; k < 2; ++k) dst[m][k] = *(const LAS bf16x8*)(lds + PG8_SA(b, h) + aoff + m * 2048 + k * 1024); } while (0)
; #define PG8_MMA(ai, bj, At, Bt) do { __builtin_amdgcn_s_setprio(1); _Pragma("unroll") for (int m = 0; m < 4; ++m) _Pragma("unroll") for (int n = 0; n < 2; ++n) _Pragma("unroll") for (int k = 0; k < 2; ++k) \
;         acc[ai][bj][m][n] = __builtin_amdgcn_mfma_f32_16x16x32_bf16(Bt[n][k], At[m][k], acc[ai][bj][m][n], 0, 0, 0); __builtin_amdgcn_s_setprio(0); } while (0)
; #define PG8_WAIT_V(n) asm volatile("s_waitcnt vmcnt(" #n ")" ::: "memory")
; #define PG8_WAIT_L(n) asm volatile("s_waitcnt lgkmcnt(" #n ")" ::: "memory")
; #define PG8_BAR __builtin_amdgcn_s_barrier()
; #define PG8_SCHED __builtin_amdgcn_sched_barrier(0)
; template <class Epi, class Sched>
; __device__ __forceinline__ void gemm_phase(const int wv, LAS unsigned char* lds, const Gemm g, const Sched& S, const Epi& E) {
;     ...
;             PG8_LDA(At, 1, 1); PG8_STAGE(PG8_SA(1, 0), a3, voffA);
;             PG8_BAR; PG8_WAIT_L(0); PG8_MMA(1, 0, At, B0); PG8_BAR; PG8_SCHED;
;             PG8_STAGE(PG8_SB(1, 1), b3 + hstepB, voffB);
;             PG8_WAIT_V(6); PG8_BAR; PG8_MMA(1, 1, At, B1); PG8_BAR;
;         }
;     __device__ __forceinline__ void operator()(const f32x4 (&acc)[2][2][4][2], const Unit& u, int wr, int wc, int fr, int fq) const {
;         const int row0 = u.pm * 256 + wr * 64 + fr; const int col0 = u.pn * 256 + wc * 32 + 8 * fq;
; #pragma unroll
;         for (int ai = 0; ai < 2; ++ai) {
;             u32x4 gv[4][2], yv[4][2];
; #pragma unroll
;             for (int m = 0; m < 4; ++m)
; #pragma unroll
;                 for (int bj = 0; bj < 2; ++bj) {
;                     const int row = row0 + ai * 128 + m * 16, col = col0 + bj * 128;
;                     gv[m][bj] = *(const u32x4*)(gates + (size_t)row * 2048 + SECOND * 1024 + col);
;                     if (SECOND) yv[m][bj] = *(const u32x4*)(Y + (size_t)row * 1024 + col);
;                 }
	s_waitcnt lgkmcnt(0)
	s_waitcnt lgkmcnt(0)
	v_mfma_f32_16x16x32_bf16 v[60:63], v[144:147], v[166:169], v[60:63]
	v_mfma_f32_16x16x32_bf16 v[56:59], v[158:161], v[166:169], v[56:59]
	v_mfma_f32_16x16x32_bf16 v[48:51], v[144:147], v[174:177], v[48:51]
	v_mfma_f32_16x16x32_bf16 v[40:43], v[158:161], v[174:177], v[40:43]
	v_mfma_f32_16x16x32_bf16 v[32:35], v[144:147], v[184:187], v[32:35]
	v_mfma_f32_16x16x32_bf16 v[24:27], v[158:161], v[184:187], v[24:27]
	v_mfma_f32_16x16x32_bf16 v[16:19], v[144:147], v[192:195], v[16:19]
	v_mfma_f32_16x16x32_bf16 v[8:11], v[158:161], v[192:195], v[8:11]
	v_mfma_f32_16x16x32_bf16 v[60:63], v[154:157], v[170:173], v[60:63]
	v_mfma_f32_16x16x32_bf16 v[56:59], v[162:165], v[170:173], v[56:59]
	v_mfma_f32_16x16x32_bf16 v[48:51], v[154:157], v[180:183], v[48:51]
	v_mfma_f32_16x16x32_bf16 v[40:43], v[162:165], v[180:183], v[40:43]
	v_mfma_f32_16x16x32_bf16 v[32:35], v[154:157], v[188:191], v[32:35]
	v_mfma_f32_16x16x32_bf16 v[24:27], v[162:165], v[188:191], v[24:27]
	v_mfma_f32_16x16x32_bf16 v[16:19], v[154:157], v[196:199], v[16:19]
	v_mfma_f32_16x16x32_bf16 v[8:11], v[162:165], v[196:199], v[8:11]
	s_barrier
	s_add_u32 s22, s22, 0x20080
	s_addc_u32 s23, s23, 0
	s_add_i32 s24, s24, s31
	v_lshl_add_u64 v[144:145], s[22:23], 0, v[130:131]
	s_mov_b32 m0, s24
	s_nop 0
	global_load_lds_dwordx4 v[144:145], off
	v_lshl_add_u64 v[144:145], s[22:23], 0, v[134:135]
	s_add_i32 m0, s24, 0x2000
	s_nop 0
	global_load_lds_dwordx4 v[144:145], off
	s_waitcnt vmcnt(6)
	s_barrier
	v_mfma_f32_16x16x32_bf16 v[52:55], v[200:203], v[166:169], v[52:55]
	v_mfma_f32_16x16x32_bf16 v[44:47], v[208:211], v[166:169], v[44:47]
	v_mfma_f32_16x16x32_bf16 v[36:39], v[200:203], v[174:177], v[36:39]
	v_mfma_f32_16x16x32_bf16 v[28:31], v[208:211], v[174:177], v[28:31]
	v_mfma_f32_16x16x32_bf16 v[20:23], v[200:203], v[184:187], v[20:23]
	v_mfma_f32_16x16x32_bf16 v[12:15], v[208:211], v[184:187], v[12:15]
	v_mfma_f32_16x16x32_bf16 v[4:7], v[200:203], v[192:195], v[4:7]
	v_mfma_f32_16x16x32_bf16 v[0:3], v[208:211], v[192:195], v[0:3]
	v_mfma_f32_16x16x32_bf16 v[52:55], v[204:207], v[170:173], v[52:55]
	v_mfma_f32_16x16x32_bf16 v[44:47], v[212:215], v[170:173], v[44:47]
	v_mfma_f32_16x16x32_bf16 v[36:39], v[204:207], v[180:183], v[36:39]
	v_mfma_f32_16x16x32_bf16 v[28:31], v[212:215], v[180:183], v[28:31]
	v_mfma_f32_16x16x32_bf16 v[20:23], v[204:207], v[188:191], v[20:23]
	v_mfma_f32_16x16x32_bf16 v[12:15], v[212:215], v[188:191], v[12:15]
	v_mfma_f32_16x16x32_bf16 v[4:7], v[204:207], v[196:199], v[4:7]
	v_mfma_f32_16x16x32_bf16 v[0:3], v[212:215], v[196:199], v[0:3]
	s_add_i32 s46, s46, 2
	s_add_u32 s20, s20, 0x100
	s_addc_u32 s21, s21, 0
	s_add_u32 s44, s44, 0x100
	s_addc_u32 s45, s45, 0
	s_cmp_gt_u32 s46, 5
	s_barrier
	s_cbranch_scc0 .LBB0_577
	v_lshl_add_u32 v146, s18, 8, v148
	v_lshl_or_b32 v144, s41, 8, v150
	v_ashrrev_i32_e32 v147, 31, v146
	v_or_b32_e32 v170, 16, v146
	v_ashrrev_i32_e32 v145, 31, v144
	v_lshlrev_b64 v[154:155], 12, v[146:147]
	v_ashrrev_i32_e32 v171, 31, v170
	v_lshl_add_u64 v[154:155], s[4:5], 0, v[154:155]
	v_lshlrev_b64 v[144:145], 1, v[144:145]
	v_lshlrev_b64 v[162:163], 12, v[170:171]
	v_lshl_add_u64 v[158:159], v[154:155], 0, v[144:145]
	v_lshl_add_u64 v[162:163], s[4:5], 0, v[162:163]
	global_load_dwordx4 v[154:157], v[158:159], off
	s_nop 0
	global_load_dwordx4 v[158:161], v[158:159], off offset:256
	v_lshl_add_u64 v[166:167], v[162:163], 0, v[144:145]
	global_load_dwordx4 v[162:165], v[166:167], off
	v_or_b32_e32 v188, 32, v146
	global_load_dwordx4 v[166:169], v[166:167], off offset:256
	v_or_b32_e32 v190, 48, v146
	v_ashrrev_i32_e32 v189, 31, v188
	v_ashrrev_i32_e32 v191, 31, v190
	v_lshlrev_b64 v[174:175], 12, v[188:189]
	v_lshlrev_b64 v[176:177], 12, v[190:191]
	v_lshlrev_b64 v[172:173], 11, v[146:147]
	v_lshlrev_b64 v[192:193], 11, v[170:171]
	v_lshl_add_u64 v[170:171], s[4:5], 0, v[174:175]
	v_lshl_add_u64 v[174:175], s[4:5], 0, v[176:177]
	v_lshl_add_u64 v[172:173], s[2:3], 0, v[172:173]
	v_lshl_add_u64 v[176:177], v[170:171], 0, v[144:145]
	v_lshl_add_u64 v[184:185], v[174:175], 0, v[144:145]
	v_lshl_add_u64 v[194:195], v[172:173], 0, v[144:145]
	global_load_dwordx4 v[170:173], v[176:177], off
	s_nop 0
	global_load_dwordx4 v[174:177], v[176:177], off offset:256
	s_nop 0
	global_load_dwordx4 v[180:183], v[184:185], off
	s_nop 0
	global_load_dwordx4 v[184:187], v[184:185], off offset:256
	s_and_b64 vcc, exec, s[0:1]
	s_mov_b32 s41, s10
	s_mov_b32 s18, s12
	s_mov_b64 s[22:23], s[16:17]
	s_mov_b64 s[20:21], s[14:15]
	s_waitcnt vmcnt(0)
; __device__ __forceinline__ unsigned cvt_pk_bf16(float lo, float hi) { unsigned r; asm volatile("v_cvt_pk_bf16_f32 %0, %1, %2" : "=v"(r) : "v"(lo), "v"(hi)); return r; }
; __device__ __forceinline__ float bflo(unsigned u) { return __uint_as_float(u << 16); }
; __device__ __forceinline__ float bfhi(unsigned u) { return __uint_as_float(u & 0xffff0000u); }
;     __device__ __forceinline__ void operator()(const f32x4 (&acc)[2][2][4][2], const Unit& u, int wr, int wc, int fr, int fq) const {
;     ...
;         for (int ai = 0; ai < 2; ++ai) {
;             u32x4 gv[4][2], yv[4][2];
; #pragma unroll
;             for (int m = 0; m < 4; ++m)
; #pragma unroll
;                 for (int bj = 0; bj < 2; ++bj) {
;                     const int row = row0 + ai * 128 + m * 16, col = col0 + bj * 128;
;                     gv[m][bj] = *(const u32x4*)(gates + (size_t)row * 2048 + SECOND * 1024 + col);
;                     if (SECOND) yv[m][bj] = *(const u32x4*)(Y + (size_t)row * 1024 + col);
;                 }
; #pragma unroll
;             for (int m = 0; m < 4; ++m)
; #pragma unroll
;                 for (int bj = 0; bj < 2; ++bj) {
;                     const int row = row0 + ai * 128 + m * 16, col = col0 + bj * 128;
;                     const u32x4 g = gv[m][bj];
;                     const f32x4 a0 = acc[ai][bj][m][0], a1 = acc[ai][bj][m][1];
;                     float r[8] = {a0[0] * bflo(g.x), a0[1] * bfhi(g.x), a0[2] * bflo(g.y), a0[3] * bfhi(g.y), a1[0] * bflo(g.z), a1[1] * bfhi(g.z), a1[2] * bflo(g.w), a1[3] * bfhi(g.w)};
;                     if (SECOND) { const u32x4 y = yv[m][bj];
;                         r[0] += bflo(y.x); r[1] += bfhi(y.x); r[2] += bflo(y.y); r[3] += bfhi(y.y); r[4] += bflo(y.z); r[5] += bfhi(y.z); r[6] += bflo(y.w); r[7] += bfhi(y.w); }
;                     u32x4 w; w.x = cvt_pk_bf16(r[0], r[1]); w.y = cvt_pk_bf16(r[2], r[3]); w.z = cvt_pk_bf16(r[4], r[5]); w.w = cvt_pk_bf16(r[6], r[7]);
;                     *(u32x4*)(Y + (size_t)row * 1024 + col) = w;
;                 }
	v_lshlrev_b32_e32 v147, 16, v154
	v_lshlrev_b32_e32 v201, 16, v160
	v_and_b32_e32 v154, 0xffff0000, v154
	v_lshlrev_b32_e32 v196, 16, v155
	v_and_b32_e32 v155, 0xffff0000, v155
	v_lshlrev_b32_e32 v197, 16, v156
	v_and_b32_e32 v156, 0xffff0000, v156
	v_lshlrev_b32_e32 v198, 16, v157
	v_and_b32_e32 v157, 0xffff0000, v157
	v_and_b32_e32 v160, 0xffff0000, v160
	v_lshlrev_b32_e32 v202, 16, v161
	v_and_b32_e32 v161, 0xffff0000, v161
	v_mul_f32_e32 v124, v124, v147
	v_mul_f32_e32 v147, v108, v201
	v_lshlrev_b32_e32 v108, 16, v162
	v_lshlrev_b32_e32 v199, 16, v158
	v_and_b32_e32 v158, 0xffff0000, v158
	v_lshlrev_b32_e32 v200, 16, v159
	v_and_b32_e32 v159, 0xffff0000, v159
	v_mul_f32_e32 v125, v125, v154
	v_mul_f32_e32 v127, v127, v155
	v_mul_f32_e32 v120, v120, v197
	v_mul_f32_e32 v121, v121, v156
	v_mul_f32_e32 v123, v123, v157
	v_mul_f32_e32 v154, v109, v160
	v_mul_f32_e32 v155, v110, v202
	v_mul_f32_e32 v156, v111, v161
	v_and_b32_e32 v109, 0xffff0000, v162
	v_lshlrev_b32_e32 v110, 16, v163
	v_and_b32_e32 v111, 0xffff0000, v163
	v_lshlrev_b32_e32 v157, 16, v164
	v_mul_f32_e32 v116, v116, v108
	v_cvt_pk_bf16_f32 v108, v124, v125
	v_mul_f32_e32 v126, v126, v196
	v_mul_f32_e32 v122, v122, v198
	v_mul_f32_e32 v112, v112, v199
	v_mul_f32_e32 v113, v113, v158
	v_mul_f32_e32 v115, v115, v159
	v_lshlrev_b32_e32 v159, 16, v165
	v_mul_f32_e32 v117, v117, v109
	v_mul_f32_e32 v118, v118, v110
	v_mul_f32_e32 v119, v119, v111
	v_cvt_pk_bf16_f32 v109, v126, v127
	v_cvt_pk_bf16_f32 v110, v120, v121
	v_cvt_pk_bf16_f32 v111, v122, v123
	v_mul_f32_e32 v120, v104, v157
	global_store_dwordx4 v[194:195], v[108:111], off
	v_and_b32_e32 v104, 0xffff0000, v165
	v_mul_f32_e32 v114, v114, v200
	v_cvt_pk_bf16_f32 v108, v112, v113
	v_and_b32_e32 v158, 0xffff0000, v164
	v_cvt_pk_bf16_f32 v109, v114, v115
	v_cvt_pk_bf16_f32 v110, v147, v154
	v_cvt_pk_bf16_f32 v111, v155, v156
	global_store_dwordx4 v[194:195], v[108:111], off offset:256
	v_mul_f32_e32 v107, v107, v104
	v_mul_f32_e32 v121, v105, v158
	v_mul_f32_e32 v108, v106, v159
	v_cvt_pk_bf16_f32 v104, v116, v117
	v_cvt_pk_bf16_f32 v105, v118, v119
	v_cvt_pk_bf16_f32 v106, v120, v121
	v_cvt_pk_bf16_f32 v107, v108, v107
	v_lshl_add_u64 v[108:109], s[2:3], 0, v[192:193]
	v_lshl_add_u64 v[108:109], v[108:109], 0, v[144:145]
	global_store_dwordx4 v[108:109], v[104:107], off
	s_nop 1
	v_lshlrev_b32_e32 v104, 16, v166
	v_mul_f32_e32 v100, v100, v104
	v_and_b32_e32 v104, 0xffff0000, v166
	v_mul_f32_e32 v101, v101, v104
	v_lshlrev_b32_e32 v104, 16, v167
	v_mul_f32_e32 v102, v102, v104
	v_and_b32_e32 v104, 0xffff0000, v167
	v_mul_f32_e32 v103, v103, v104
	v_lshlrev_b32_e32 v104, 16, v168
	v_mul_f32_e32 v104, v92, v104
	v_and_b32_e32 v92, 0xffff0000, v168
	v_mul_f32_e32 v105, v93, v92
	v_lshlrev_b32_e32 v92, 16, v169
	v_mul_f32_e32 v106, v94, v92
	v_and_b32_e32 v92, 0xffff0000, v169
	v_mul_f32_e32 v95, v95, v92
	v_cvt_pk_bf16_f32 v92, v100, v101
	v_cvt_pk_bf16_f32 v93, v102, v103
	v_cvt_pk_bf16_f32 v94, v104, v105
	v_cvt_pk_bf16_f32 v95, v106, v95
	global_store_dwordx4 v[108:109], v[92:95], off offset:256
	v_add_u32_e32 v102, 0xb0, v146
	v_ashrrev_i32_e32 v103, 31, v102
	v_lshlrev_b32_e32 v94, 16, v170
	v_mul_f32_e32 v94, v96, v94
	v_lshlrev_b32_e32 v96, 16, v171
	v_and_b32_e32 v95, 0xffff0000, v170
	v_mul_f32_e32 v96, v98, v96
	v_lshlrev_b32_e32 v98, 16, v172
	v_mul_f32_e32 v95, v97, v95
	v_and_b32_e32 v97, 0xffff0000, v171
	v_mul_f32_e32 v98, v88, v98
	v_and_b32_e32 v88, 0xffff0000, v172
	v_lshlrev_b64 v[92:93], 11, v[188:189]
	v_mul_f32_e32 v97, v99, v97
	v_mul_f32_e32 v99, v89, v88
	v_lshlrev_b32_e32 v88, 16, v173
	v_mul_f32_e32 v100, v90, v88
	v_and_b32_e32 v88, 0xffff0000, v173
	v_lshl_add_u64 v[92:93], s[2:3], 0, v[92:93]
	v_mul_f32_e32 v91, v91, v88
	v_cvt_pk_bf16_f32 v88, v94, v95
	v_lshl_add_u64 v[92:93], v[92:93], 0, v[144:145]
	v_cvt_pk_bf16_f32 v89, v96, v97
	v_cvt_pk_bf16_f32 v90, v98, v99
	v_cvt_pk_bf16_f32 v91, v100, v91
	global_store_dwordx4 v[92:93], v[88:91], off
	v_add_u32_e32 v96, 0x80, v146
	v_ashrrev_i32_e32 v97, 31, v96
	v_lshlrev_b32_e32 v88, 16, v174
	v_mul_f32_e32 v84, v84, v88
	v_and_b32_e32 v88, 0xffff0000, v174
	v_mul_f32_e32 v85, v85, v88
	v_lshlrev_b32_e32 v88, 16, v175
	v_mul_f32_e32 v86, v86, v88
	v_and_b32_e32 v88, 0xffff0000, v175
	v_mul_f32_e32 v87, v87, v88
	v_lshlrev_b32_e32 v88, 16, v176
	v_mul_f32_e32 v88, v76, v88
	v_and_b32_e32 v76, 0xffff0000, v176
	v_mul_f32_e32 v89, v77, v76
	v_lshlrev_b32_e32 v76, 16, v177
	v_mul_f32_e32 v90, v78, v76
	v_and_b32_e32 v76, 0xffff0000, v177
	v_mul_f32_e32 v79, v79, v76
	v_cvt_pk_bf16_f32 v76, v84, v85
	v_cvt_pk_bf16_f32 v77, v86, v87
	v_cvt_pk_bf16_f32 v78, v88, v89
	v_cvt_pk_bf16_f32 v79, v90, v79
	global_store_dwordx4 v[92:93], v[76:79], off offset:256
	v_add_u32_e32 v98, 0x90, v146
	v_ashrrev_i32_e32 v99, 31, v98
	v_lshlrev_b32_e32 v78, 16, v180
	v_mul_f32_e32 v78, v80, v78
	v_lshlrev_b32_e32 v80, 16, v181
	v_and_b32_e32 v79, 0xffff0000, v180
	v_mul_f32_e32 v80, v82, v80
	v_lshlrev_b32_e32 v82, 16, v182
	v_mul_f32_e32 v79, v81, v79
	v_and_b32_e32 v81, 0xffff0000, v181
	v_mul_f32_e32 v82, v72, v82
	v_and_b32_e32 v72, 0xffff0000, v182
	v_lshlrev_b64 v[76:77], 11, v[190:191]
	v_mul_f32_e32 v81, v83, v81
	v_mul_f32_e32 v83, v73, v72
	v_lshlrev_b32_e32 v72, 16, v183
	v_mul_f32_e32 v84, v74, v72
	v_and_b32_e32 v72, 0xffff0000, v183
	v_lshl_add_u64 v[76:77], s[2:3], 0, v[76:77]
	v_mul_f32_e32 v75, v75, v72
	v_cvt_pk_bf16_f32 v72, v78, v79
	v_lshl_add_u64 v[76:77], v[76:77], 0, v[144:145]
	v_cvt_pk_bf16_f32 v73, v80, v81
	v_cvt_pk_bf16_f32 v74, v82, v83
	v_cvt_pk_bf16_f32 v75, v84, v75
	global_store_dwordx4 v[76:77], v[72:75], off
	v_add_u32_e32 v100, 0xa0, v146
; __device__ __forceinline__ unsigned cvt_pk_bf16(float lo, float hi) { unsigned r; asm volatile("v_cvt_pk_bf16_f32 %0, %1, %2" : "=v"(r) : "v"(lo), "v"(hi)); return r; }
; __device__ __forceinline__ float bflo(unsigned u) { return __uint_as_float(u << 16); }
; __device__ __forceinline__ float bfhi(unsigned u) { return __uint_as_float(u & 0xffff0000u); }
;     __device__ __forceinline__ void operator()(const f32x4 (&acc)[2][2][4][2], const Unit& u, int wr, int wc, int fr, int fq) const {
;     ...
;         for (int ai = 0; ai < 2; ++ai) {
;             u32x4 gv[4][2], yv[4][2];
; #pragma unroll
;             for (int m = 0; m < 4; ++m)
; #pragma unroll
;                 for (int bj = 0; bj < 2; ++bj) {
;                     const int row = row0 + ai * 128 + m * 16, col = col0 + bj * 128;
;                     gv[m][bj] = *(const u32x4*)(gates + (size_t)row * 2048 + SECOND * 1024 + col);
;                     if (SECOND) yv[m][bj] = *(const u32x4*)(Y + (size_t)row * 1024 + col);
;                 }
; #pragma unroll
;             for (int m = 0; m < 4; ++m)
; #pragma unroll
;                 for (int bj = 0; bj < 2; ++bj) {
;                     const int row = row0 + ai * 128 + m * 16, col = col0 + bj * 128;
;                     const u32x4 g = gv[m][bj];
;                     const f32x4 a0 = acc[ai][bj][m][0], a1 = acc[ai][bj][m][1];
;                     float r[8] = {a0[0] * bflo(g.x), a0[1] * bfhi(g.x), a0[2] * bflo(g.y), a0[3] * bfhi(g.y), a1[0] * bflo(g.z), a1[1] * bfhi(g.z), a1[2] * bflo(g.w), a1[3] * bfhi(g.w)};
;                     if (SECOND) { const u32x4 y = yv[m][bj];
;                         r[0] += bflo(y.x); r[1] += bfhi(y.x); r[2] += bflo(y.y); r[3] += bfhi(y.y); r[4] += bflo(y.z); r[5] += bfhi(y.z); r[6] += bflo(y.w); r[7] += bfhi(y.w); }
;                     u32x4 w; w.x = cvt_pk_bf16(r[0], r[1]); w.y = cvt_pk_bf16(r[2], r[3]); w.z = cvt_pk_bf16(r[4], r[5]); w.w = cvt_pk_bf16(r[6], r[7]);
;                     *(u32x4*)(Y + (size_t)row * 1024 + col) = w;
;                 }
	v_ashrrev_i32_e32 v101, 31, v100
	v_lshlrev_b32_e32 v72, 16, v184
	v_mul_f32_e32 v68, v68, v72
	v_and_b32_e32 v72, 0xffff0000, v184
	v_mul_f32_e32 v69, v69, v72
	v_lshlrev_b32_e32 v72, 16, v185
	v_mul_f32_e32 v70, v70, v72
	v_and_b32_e32 v72, 0xffff0000, v185
	v_mul_f32_e32 v71, v71, v72
	v_lshlrev_b32_e32 v72, 16, v186
	v_mul_f32_e32 v72, v64, v72
	v_and_b32_e32 v64, 0xffff0000, v186
	v_mul_f32_e32 v73, v65, v64
	v_lshlrev_b32_e32 v64, 16, v187
	v_mul_f32_e32 v74, v66, v64
	v_and_b32_e32 v64, 0xffff0000, v187
	v_mul_f32_e32 v67, v67, v64
	v_cvt_pk_bf16_f32 v64, v68, v69
	v_cvt_pk_bf16_f32 v65, v70, v71
	v_cvt_pk_bf16_f32 v66, v72, v73
	v_cvt_pk_bf16_f32 v67, v74, v67
	global_store_dwordx4 v[76:77], v[64:67], off offset:256
	v_lshlrev_b64 v[72:73], 12, v[98:99]
	v_lshl_add_u64 v[72:73], s[4:5], 0, v[72:73]
	v_lshlrev_b64 v[64:65], 12, v[96:97]
	v_lshl_add_u64 v[64:65], s[4:5], 0, v[64:65]
	v_lshl_add_u64 v[68:69], v[64:65], 0, v[144:145]
	global_load_dwordx4 v[64:67], v[68:69], off
	s_nop 0
	global_load_dwordx4 v[68:71], v[68:69], off offset:256
	v_lshl_add_u64 v[76:77], v[72:73], 0, v[144:145]
	global_load_dwordx4 v[72:75], v[76:77], off
	s_nop 0
	global_load_dwordx4 v[76:79], v[76:77], off offset:256
	v_lshlrev_b64 v[80:81], 12, v[100:101]
	v_lshl_add_u64 v[80:81], s[4:5], 0, v[80:81]
	v_lshl_add_u64 v[84:85], v[80:81], 0, v[144:145]
	global_load_dwordx4 v[80:83], v[84:85], off
	s_nop 0
	global_load_dwordx4 v[84:87], v[84:85], off offset:256
	v_lshlrev_b64 v[88:89], 12, v[102:103]
	v_lshl_add_u64 v[88:89], s[4:5], 0, v[88:89]
	v_lshl_add_u64 v[92:93], v[88:89], 0, v[144:145]
	global_load_dwordx4 v[88:91], v[92:93], off
	s_nop 0
	global_load_dwordx4 v[92:95], v[92:93], off offset:256
	v_lshlrev_b64 v[96:97], 11, v[96:97]
	s_waitcnt vmcnt(0)
; __device__ __forceinline__ float bflo(unsigned u) { return __uint_as_float(u << 16); }
; template <class Epi, class Sched>
; __device__ __forceinline__ void gemm_phase(const int wv, LAS unsigned char* lds, const Gemm g, const Sched& S, const Epi& E) {
;     ...
;         E(acc, cur, wr, wc, fr, fq); S.done(cur);
;         if (!has_next) break;
; #pragma unroll
;         for (int a = 0; a < 2; ++a)
; #pragma unroll
;             for (int b = 0; b < 2; ++b)
; #pragma unroll
;                 for (int m = 0; m < 4; ++m)
; #pragma unroll
;                     for (int n = 0; n < 2; ++n) acc[a][b][m][n] = (f32x4){0.f, 0.f, 0.f, 0.f};
;         cur = nxt; cA = nA; cB = nB; ++ui;
;     }
;     PG8_WAIT_V(0);
;     if (wr == 0) PG8_BAR;
;     __device__ __forceinline__ void operator()(const f32x4 (&acc)[2][2][4][2], const Unit& u, int wr, int wc, int fr, int fq) const {
;     ...
;         for (int ai = 0; ai < 2; ++ai) {
;             u32x4 gv[4][2], yv[4][2];
; #pragma unroll
;             for (int m = 0; m < 4; ++m)
; #pragma unroll
;                 for (int bj = 0; bj < 2; ++bj) {
;                     const int row = row0 + ai * 128 + m * 16, col = col0 + bj * 128;
;                     gv[m][bj] = *(const u32x4*)(gates + (size_t)row * 2048 + SECOND * 1024 + col);
;                     if (SECOND) yv[m][bj] = *(const u32x4*)(Y + (size_t)row * 1024 + col);
;                 }
; #pragma unroll
;             for (int m = 0; m < 4; ++m)
; #pragma unroll
;                 for (int bj = 0; bj < 2; ++bj) {
;                     const int row = row0 + ai * 128 + m * 16, col = col0 + bj * 128;
;                     const u32x4 g = gv[m][bj];
;                     const f32x4 a0 = acc[ai][bj][m][0], a1 = acc[ai][bj][m][1];
;                     float r[8] = {a0[0] * bflo(g.x), a0[1] * bfhi(g.x), a0[2] * bflo(g.y), a0[3] * bfhi(g.y), a1[0] * bflo(g.z), a1[1] * bfhi(g.z), a1[2] * bflo(g.w), a1[3] * bfhi(g.w)};
;                     if (SECOND) { const u32x4 y = yv[m][bj];
;                         r[0] += bflo(y.x); r[1] += bfhi(y.x); r[2] += bflo(y.y); r[3] += bfhi(y.y); r[4] += bflo(y.z); r[5] += bfhi(y.z); r[6] += bflo(y.w); r[7] += bfhi(y.w); }
;                     u32x4 w; w.x = cvt_pk_bf16(r[0], r[1]); w.y = cvt_pk_bf16(r[2], r[3]); w.z = cvt_pk_bf16(r[4], r[5]); w.w = cvt_pk_bf16(r[6], r[7]);
;                     *(u32x4*)(Y + (size_t)row * 1024 + col) = w;
;                 }
	v_lshlrev_b32_e32 v104, 16, v64
	v_and_b32_e32 v64, 0xffff0000, v64
	v_mul_f32_e32 v61, v61, v64
	v_lshlrev_b32_e32 v64, 16, v65
	v_mul_f32_e32 v62, v62, v64
	v_and_b32_e32 v64, 0xffff0000, v65
	v_mul_f32_e32 v63, v63, v64
	v_lshlrev_b32_e32 v64, 16, v66
	v_mul_f32_e32 v64, v56, v64
	v_and_b32_e32 v56, 0xffff0000, v66
	v_mul_f32_e32 v65, v57, v56
	v_lshlrev_b32_e32 v56, 16, v67
	v_mul_f32_e32 v60, v60, v104
	v_mul_f32_e32 v66, v58, v56
	v_and_b32_e32 v56, 0xffff0000, v67
	v_mul_f32_e32 v59, v59, v56
	v_cvt_pk_bf16_f32 v56, v60, v61
	v_lshl_add_u64 v[60:61], s[2:3], 0, v[96:97]
	v_lshl_add_u64 v[60:61], v[60:61], 0, v[144:145]
	v_cvt_pk_bf16_f32 v57, v62, v63
	v_cvt_pk_bf16_f32 v58, v64, v65
	v_cvt_pk_bf16_f32 v59, v66, v59
	global_store_dwordx4 v[60:61], v[56:59], off
	s_nop 1
	v_lshlrev_b32_e32 v56, 16, v68
	v_mul_f32_e32 v52, v52, v56
	v_and_b32_e32 v56, 0xffff0000, v68
	v_mul_f32_e32 v53, v53, v56
	v_lshlrev_b32_e32 v56, 16, v69
	v_mul_f32_e32 v54, v54, v56
	v_and_b32_e32 v56, 0xffff0000, v69
	v_mul_f32_e32 v55, v55, v56
	v_lshlrev_b32_e32 v56, 16, v70
	v_mul_f32_e32 v56, v44, v56
	v_and_b32_e32 v44, 0xffff0000, v70
	v_mul_f32_e32 v57, v45, v44
	v_lshlrev_b32_e32 v44, 16, v71
	v_mul_f32_e32 v58, v46, v44
	v_and_b32_e32 v44, 0xffff0000, v71
	v_mul_f32_e32 v47, v47, v44
	v_cvt_pk_bf16_f32 v44, v52, v53
	v_cvt_pk_bf16_f32 v45, v54, v55
	v_cvt_pk_bf16_f32 v46, v56, v57
	v_cvt_pk_bf16_f32 v47, v58, v47
	global_store_dwordx4 v[60:61], v[44:47], off offset:256
	s_nop 1
	v_lshlrev_b32_e32 v46, 16, v72
	v_mul_f32_e32 v46, v48, v46
	v_lshlrev_b32_e32 v48, 16, v73
	v_and_b32_e32 v47, 0xffff0000, v72
	v_mul_f32_e32 v48, v50, v48
	v_lshlrev_b32_e32 v50, 16, v74
	v_mul_f32_e32 v47, v49, v47
	v_and_b32_e32 v49, 0xffff0000, v73
	v_mul_f32_e32 v50, v40, v50
	v_and_b32_e32 v40, 0xffff0000, v74
	v_lshlrev_b64 v[44:45], 11, v[98:99]
	v_mul_f32_e32 v49, v51, v49
	v_mul_f32_e32 v51, v41, v40
	v_lshlrev_b32_e32 v40, 16, v75
	v_mul_f32_e32 v52, v42, v40
	v_and_b32_e32 v40, 0xffff0000, v75
	v_lshl_add_u64 v[44:45], s[2:3], 0, v[44:45]
	v_mul_f32_e32 v43, v43, v40
	v_cvt_pk_bf16_f32 v40, v46, v47
	v_lshl_add_u64 v[44:45], v[44:45], 0, v[144:145]
	v_cvt_pk_bf16_f32 v41, v48, v49
	v_cvt_pk_bf16_f32 v42, v50, v51
	v_cvt_pk_bf16_f32 v43, v52, v43
	global_store_dwordx4 v[44:45], v[40:43], off
	s_nop 1
	v_lshlrev_b32_e32 v40, 16, v76
	v_mul_f32_e32 v36, v36, v40
	v_and_b32_e32 v40, 0xffff0000, v76
	v_mul_f32_e32 v37, v37, v40
	v_lshlrev_b32_e32 v40, 16, v77
	v_mul_f32_e32 v38, v38, v40
	v_and_b32_e32 v40, 0xffff0000, v77
	v_mul_f32_e32 v39, v39, v40
	v_lshlrev_b32_e32 v40, 16, v78
	v_mul_f32_e32 v40, v28, v40
	v_and_b32_e32 v28, 0xffff0000, v78
	v_mul_f32_e32 v41, v29, v28
	v_lshlrev_b32_e32 v28, 16, v79
	v_mul_f32_e32 v42, v30, v28
	v_and_b32_e32 v28, 0xffff0000, v79
	v_mul_f32_e32 v31, v31, v28
	v_cvt_pk_bf16_f32 v28, v36, v37
	v_cvt_pk_bf16_f32 v29, v38, v39
	v_cvt_pk_bf16_f32 v30, v40, v41
	v_cvt_pk_bf16_f32 v31, v42, v31
	global_store_dwordx4 v[44:45], v[28:31], off offset:256
	s_nop 1
	v_lshlrev_b32_e32 v30, 16, v80
	v_mul_f32_e32 v30, v32, v30
	v_lshlrev_b32_e32 v32, 16, v81
	v_and_b32_e32 v31, 0xffff0000, v80
	v_mul_f32_e32 v32, v34, v32
	v_lshlrev_b32_e32 v34, 16, v82
	v_mul_f32_e32 v31, v33, v31
	v_and_b32_e32 v33, 0xffff0000, v81
	v_mul_f32_e32 v34, v24, v34
	v_and_b32_e32 v24, 0xffff0000, v82
	v_lshlrev_b64 v[28:29], 11, v[100:101]
	v_mul_f32_e32 v33, v35, v33
	v_mul_f32_e32 v35, v25, v24
	v_lshlrev_b32_e32 v24, 16, v83
	v_mul_f32_e32 v36, v26, v24
	v_and_b32_e32 v24, 0xffff0000, v83
	v_lshl_add_u64 v[28:29], s[2:3], 0, v[28:29]
	v_mul_f32_e32 v27, v27, v24
	v_cvt_pk_bf16_f32 v24, v30, v31
	v_lshl_add_u64 v[28:29], v[28:29], 0, v[144:145]
	v_cvt_pk_bf16_f32 v25, v32, v33
	v_cvt_pk_bf16_f32 v26, v34, v35
	v_cvt_pk_bf16_f32 v27, v36, v27
	global_store_dwordx4 v[28:29], v[24:27], off
	s_nop 1
	v_lshlrev_b32_e32 v24, 16, v84
	v_mul_f32_e32 v20, v20, v24
	v_and_b32_e32 v24, 0xffff0000, v84
	v_mul_f32_e32 v21, v21, v24
	v_lshlrev_b32_e32 v24, 16, v85
	v_mul_f32_e32 v22, v22, v24
	v_and_b32_e32 v24, 0xffff0000, v85
	v_mul_f32_e32 v23, v23, v24
	v_lshlrev_b32_e32 v24, 16, v86
	v_mul_f32_e32 v24, v12, v24
	v_and_b32_e32 v12, 0xffff0000, v86
	v_mul_f32_e32 v25, v13, v12
	v_lshlrev_b32_e32 v12, 16, v87
	v_mul_f32_e32 v26, v14, v12
	v_and_b32_e32 v12, 0xffff0000, v87
	v_mul_f32_e32 v15, v15, v12
	v_cvt_pk_bf16_f32 v12, v20, v21
	v_cvt_pk_bf16_f32 v13, v22, v23
	v_cvt_pk_bf16_f32 v14, v24, v25
	v_cvt_pk_bf16_f32 v15, v26, v15
	global_store_dwordx4 v[28:29], v[12:15], off offset:256
	s_nop 1
	v_lshlrev_b32_e32 v14, 16, v88
	v_mul_f32_e32 v14, v16, v14
	v_lshlrev_b32_e32 v16, 16, v89
	v_and_b32_e32 v15, 0xffff0000, v88
	v_mul_f32_e32 v16, v18, v16
	v_lshlrev_b32_e32 v18, 16, v90
	v_mul_f32_e32 v15, v17, v15
	v_and_b32_e32 v17, 0xffff0000, v89
	v_mul_f32_e32 v18, v8, v18
	v_and_b32_e32 v8, 0xffff0000, v90
	v_lshlrev_b64 v[12:13], 11, v[102:103]
	v_mul_f32_e32 v17, v19, v17
	v_mul_f32_e32 v19, v9, v8
	v_lshlrev_b32_e32 v8, 16, v91
	v_mul_f32_e32 v20, v10, v8
	v_and_b32_e32 v8, 0xffff0000, v91
	v_lshl_add_u64 v[12:13], s[2:3], 0, v[12:13]
	v_mul_f32_e32 v11, v11, v8
	v_cvt_pk_bf16_f32 v8, v14, v15
	v_lshl_add_u64 v[12:13], v[12:13], 0, v[144:145]
	v_cvt_pk_bf16_f32 v9, v16, v17
	v_cvt_pk_bf16_f32 v10, v18, v19
	v_cvt_pk_bf16_f32 v11, v20, v11
	global_store_dwordx4 v[12:13], v[8:11], off
	s_nop 1
	v_lshlrev_b32_e32 v8, 16, v92
	v_mul_f32_e32 v4, v4, v8
	v_and_b32_e32 v8, 0xffff0000, v92
	v_mul_f32_e32 v5, v5, v8
	v_lshlrev_b32_e32 v8, 16, v93
	v_mul_f32_e32 v6, v6, v8
	v_and_b32_e32 v8, 0xffff0000, v93
	v_mul_f32_e32 v7, v7, v8
	v_lshlrev_b32_e32 v8, 16, v94
	v_mul_f32_e32 v8, v0, v8
	v_and_b32_e32 v0, 0xffff0000, v94
	v_mul_f32_e32 v9, v1, v0
	v_lshlrev_b32_e32 v0, 16, v95
	v_mul_f32_e32 v10, v2, v0
	v_and_b32_e32 v0, 0xffff0000, v95
	v_mul_f32_e32 v3, v3, v0
	v_cvt_pk_bf16_f32 v0, v4, v5
	v_cvt_pk_bf16_f32 v1, v6, v7
	v_cvt_pk_bf16_f32 v2, v8, v9
	v_cvt_pk_bf16_f32 v3, v10, v3
	global_store_dwordx4 v[12:13], v[0:3], off offset:256
	s_cbranch_vccz .LBB0_570
	s_waitcnt vmcnt(0)
	s_cmpk_gt_u32 s26, 0xff
	s_cbranch_scc1 .LBB0_581
	s_barrier

; #define PG8_STAGE(bufoff, gbase, voff) do { _Pragma("unroll") for (int _i = 0; _i < 2; ++_i) \
;         __builtin_amdgcn_global_load_lds((const unsigned*)((const char*)(gbase) + (voff)[_i]), (LAS unsigned*)(lds + (bufoff) + ldsw + _i * 8192), 16, 0, 0); } while (0)
; #define PG8_LDA(dst, b, h) do { _Pragma("unroll") for (int m = 0; m < 4; ++m) _Pragma("unroll") for (int k = 0; k < 2; ++k) dst[m][k] = *(const LAS bf16x8*)(lds + PG8_SA(b, h) + aoff + m * 2048 + k * 1024); } while (0)
; #define PG8_LDB(dst, b, h) do { _Pragma("unroll") for (int n = 0; n < 2; ++n) _Pragma("unroll") for (int k = 0; k < 2; ++k) dst[n][k] = *(const LAS bf16x8*)(lds + PG8_SB(b, h) + boff + n * 2048 + k * 1024); } while (0)
; #define PG8_MMA(ai, bj, At, Bt) do { __builtin_amdgcn_s_setprio(1); _Pragma("unroll") for (int m = 0; m < 4; ++m) _Pragma("unroll") for (int n = 0; n < 2; ++n) _Pragma("unroll") for (int k = 0; k < 2; ++k) \
;         acc[ai][bj][m][n] = __builtin_amdgcn_mfma_f32_16x16x32_bf16(Bt[n][k], At[m][k], acc[ai][bj][m][n], 0, 0, 0); __builtin_amdgcn_s_setprio(0); } while (0)
; #define PG8_WAIT_V(n) asm volatile("s_waitcnt vmcnt(" #n ")" ::: "memory")
; #define PG8_WAIT_L(n) asm volatile("s_waitcnt lgkmcnt(" #n ")" ::: "memory")
; #define PG8_BAR __builtin_amdgcn_s_barrier()
; #define PG8_SCHED __builtin_amdgcn_sched_barrier(0)
; template <class Epi, class Sched>
; __device__ __forceinline__ void gemm_phase(const int wv, LAS unsigned char* lds, const Gemm g, const Sched& S, const Epi& E) {
;     ...
;             PG8_LDB(B0, 0, 0); PG8_SCHED; PG8_LDA(At, 0, 0); PG8_STAGE(PG8_SA(1, 1), a1 + hstepA, voffA);
;             PG8_WAIT_L(8); PG8_BAR; PG8_WAIT_L(0); PG8_MMA(0, 0, At, B0); PG8_BAR; PG8_SCHED;
;             PG8_LDB(B1, 0, 1); PG8_STAGE(PG8_SB(0, 0), b2, voffB);
;             PG8_BAR; PG8_WAIT_L(0); PG8_MMA(0, 1, At, B1); PG8_BAR;
;             PG8_LDA(At, 0, 1); PG8_STAGE(PG8_SA(0, 0), a2, voffA);
;             PG8_BAR; PG8_WAIT_L(0); PG8_MMA(1, 0, At, B0); PG8_BAR; PG8_SCHED;
;             PG8_STAGE(PG8_SB(0, 1), b2 + hstepB, voffB);
;             PG8_WAIT_V(6); PG8_BAR; PG8_MMA(1, 1, At, B1); PG8_BAR;
.LBB0_597:
	ds_read_b128 v[128:131], v175
	ds_read_b128 v[132:135], v175 offset:1024
	ds_read_b128 v[136:139], v175 offset:2048
	ds_read_b128 v[140:143], v175 offset:3072
	s_add_u32 s20, s18, 0xfff80080
	s_addc_u32 s21, s19, -1
	s_cmp_eq_u32 s44, 28
	s_cselect_b32 s23, s11, s21
	s_cselect_b32 s22, s40, s20
	s_cselect_b32 s21, s9, s43
	s_cselect_b32 s20, s41, s42
	v_lshl_add_u64 v[200:201], s[18:19], 0, v[156:157]
	s_add_i32 m0, s17, 0xc000
	ds_read_b128 v[144:147], v176
	ds_read_b128 v[164:167], v176 offset:1024
	ds_read_b128 v[168:171], v176 offset:2048
	ds_read_b128 v[180:183], v176 offset:3072
	ds_read_b128 v[184:187], v176 offset:4096
	ds_read_b128 v[188:191], v176 offset:5120
	ds_read_b128 v[192:195], v176 offset:6144
	ds_read_b128 v[196:199], v176 offset:7168
	global_load_lds_dwordx4 v[200:201], off
	v_lshl_add_u64 v[200:201], s[18:19], 0, v[158:159]
	s_add_i32 m0, s17, 0xe000
	s_nop 0
	global_load_lds_dwordx4 v[200:201], off
	s_waitcnt lgkmcnt(8)
	s_barrier
	s_waitcnt lgkmcnt(0)
	s_waitcnt lgkmcnt(0)
	v_mfma_f32_16x16x32_bf16 v[124:127], v[128:131], v[144:147], v[124:127]
	v_mfma_f32_16x16x32_bf16 v[120:123], v[136:139], v[144:147], v[120:123]
	v_mfma_f32_16x16x32_bf16 v[108:111], v[128:131], v[168:171], v[108:111]
	v_mfma_f32_16x16x32_bf16 v[104:107], v[136:139], v[168:171], v[104:107]
	v_mfma_f32_16x16x32_bf16 v[92:95], v[128:131], v[184:187], v[92:95]
	v_mfma_f32_16x16x32_bf16 v[88:91], v[136:139], v[184:187], v[88:91]
	v_mfma_f32_16x16x32_bf16 v[76:79], v[128:131], v[192:195], v[76:79]
	v_mfma_f32_16x16x32_bf16 v[72:75], v[136:139], v[192:195], v[72:75]
	v_mfma_f32_16x16x32_bf16 v[124:127], v[132:135], v[164:167], v[124:127]
	v_mfma_f32_16x16x32_bf16 v[120:123], v[140:143], v[164:167], v[120:123]
	v_mfma_f32_16x16x32_bf16 v[108:111], v[132:135], v[180:183], v[108:111]
	v_mfma_f32_16x16x32_bf16 v[104:107], v[140:143], v[180:183], v[104:107]
	v_mfma_f32_16x16x32_bf16 v[92:95], v[132:135], v[188:191], v[92:95]
	v_mfma_f32_16x16x32_bf16 v[88:91], v[140:143], v[188:191], v[88:91]
	v_mfma_f32_16x16x32_bf16 v[76:79], v[132:135], v[196:199], v[76:79]
	v_mfma_f32_16x16x32_bf16 v[72:75], v[140:143], v[196:199], v[72:75]
	s_barrier
	s_add_i32 s45, s37, s29
	v_lshl_add_u64 v[216:217], s[20:21], 0, v[150:151]
	s_mov_b32 m0, s45
	ds_read_b128 v[200:203], v177
	ds_read_b128 v[204:207], v177 offset:1024
	ds_read_b128 v[208:211], v177 offset:2048
	ds_read_b128 v[212:215], v177 offset:3072
	global_load_lds_dwordx4 v[216:217], off
	v_lshl_add_u64 v[218:219], s[20:21], 0, v[154:155]
	s_add_i32 m0, s45, 0x2000
	s_nop 0
	global_load_lds_dwordx4 v[218:219], off
	s_barrier
	s_waitcnt lgkmcnt(0)
	s_waitcnt lgkmcnt(0)
	v_mfma_f32_16x16x32_bf16 v[116:119], v[200:203], v[144:147], v[116:119]
	v_mfma_f32_16x16x32_bf16 v[112:115], v[208:211], v[144:147], v[112:115]
	v_mfma_f32_16x16x32_bf16 v[100:103], v[200:203], v[168:171], v[100:103]
	v_mfma_f32_16x16x32_bf16 v[96:99], v[208:211], v[168:171], v[96:99]
	v_mfma_f32_16x16x32_bf16 v[84:87], v[200:203], v[184:187], v[84:87]
	v_mfma_f32_16x16x32_bf16 v[80:83], v[208:211], v[184:187], v[80:83]
	v_mfma_f32_16x16x32_bf16 v[68:71], v[200:203], v[192:195], v[68:71]
	v_mfma_f32_16x16x32_bf16 v[64:67], v[208:211], v[192:195], v[64:67]
	v_mfma_f32_16x16x32_bf16 v[116:119], v[204:207], v[164:167], v[116:119]
	v_mfma_f32_16x16x32_bf16 v[112:115], v[212:215], v[164:167], v[112:115]
	v_mfma_f32_16x16x32_bf16 v[100:103], v[204:207], v[180:183], v[100:103]
	v_mfma_f32_16x16x32_bf16 v[96:99], v[212:215], v[180:183], v[96:99]
	v_mfma_f32_16x16x32_bf16 v[84:87], v[204:207], v[188:191], v[84:87]
	v_mfma_f32_16x16x32_bf16 v[80:83], v[212:215], v[188:191], v[80:83]
	v_mfma_f32_16x16x32_bf16 v[68:71], v[204:207], v[196:199], v[68:71]
	v_mfma_f32_16x16x32_bf16 v[64:67], v[212:215], v[196:199], v[64:67]
	s_mov_b32 m0, s17
	v_lshl_add_u64 v[220:221], s[22:23], 0, v[148:149]
	s_barrier
	ds_read_b128 v[144:147], v176 offset:16384
	ds_read_b128 v[164:167], v176 offset:17408
	ds_read_b128 v[168:171], v176 offset:18432
	ds_read_b128 v[180:183], v176 offset:19456
	ds_read_b128 v[184:187], v176 offset:20480
	ds_read_b128 v[188:191], v176 offset:21504
	ds_read_b128 v[192:195], v176 offset:22528
	ds_read_b128 v[196:199], v176 offset:23552
	global_load_lds_dwordx4 v[220:221], off
	v_lshl_add_u64 v[222:223], s[22:23], 0, v[152:153]
	s_mov_b32 m0, s30
	s_nop 0
	global_load_lds_dwordx4 v[222:223], off
	s_barrier
	s_waitcnt lgkmcnt(0)
	s_waitcnt lgkmcnt(0)
	v_mfma_f32_16x16x32_bf16 v[60:63], v[128:131], v[144:147], v[60:63]
	v_mfma_f32_16x16x32_bf16 v[56:59], v[136:139], v[144:147], v[56:59]
	v_mfma_f32_16x16x32_bf16 v[44:47], v[128:131], v[168:171], v[44:47]
	v_mfma_f32_16x16x32_bf16 v[40:43], v[136:139], v[168:171], v[40:43]
	v_mfma_f32_16x16x32_bf16 v[28:31], v[128:131], v[184:187], v[28:31]
	v_mfma_f32_16x16x32_bf16 v[24:27], v[136:139], v[184:187], v[24:27]
	v_mfma_f32_16x16x32_bf16 v[12:15], v[128:131], v[192:195], v[12:15]
	v_mfma_f32_16x16x32_bf16 v[8:11], v[136:139], v[192:195], v[8:11]
	v_mfma_f32_16x16x32_bf16 v[60:63], v[132:135], v[164:167], v[60:63]
	v_mfma_f32_16x16x32_bf16 v[56:59], v[140:143], v[164:167], v[56:59]
	v_mfma_f32_16x16x32_bf16 v[44:47], v[132:135], v[180:183], v[44:47]
	v_mfma_f32_16x16x32_bf16 v[40:43], v[140:143], v[180:183], v[40:43]
	v_mfma_f32_16x16x32_bf16 v[28:31], v[132:135], v[188:191], v[28:31]
	v_mfma_f32_16x16x32_bf16 v[24:27], v[140:143], v[188:191], v[24:27]
	v_mfma_f32_16x16x32_bf16 v[12:15], v[132:135], v[196:199], v[12:15]
	v_mfma_f32_16x16x32_bf16 v[8:11], v[140:143], v[196:199], v[8:11]
	s_barrier
; #define PG8_STAGE(bufoff, gbase, voff) do { _Pragma("unroll") for (int _i = 0; _i < 2; ++_i) \
;         __builtin_amdgcn_global_load_lds((const unsigned*)((const char*)(gbase) + (voff)[_i]), (LAS unsigned*)(lds + (bufoff) + ldsw + _i * 8192), 16, 0, 0); } while (0)
; #define PG8_LDA(dst, b, h) do { _Pragma("unroll") for (int m = 0; m < 4; ++m) _Pragma("unroll") for (int k = 0; k < 2; ++k) dst[m][k] = *(const LAS bf16x8*)(lds + PG8_SA(b, h) + aoff + m * 2048 + k * 1024); } while (0)
; #define PG8_LDB(dst, b, h) do { _Pragma("unroll") for (int n = 0; n < 2; ++n) _Pragma("unroll") for (int k = 0; k < 2; ++k) dst[n][k] = *(const LAS bf16x8*)(lds + PG8_SB(b, h) + boff + n * 2048 + k * 1024); } while (0)
; #define PG8_MMA(ai, bj, At, Bt) do { __builtin_amdgcn_s_setprio(1); _Pragma("unroll") for (int m = 0; m < 4; ++m) _Pragma("unroll") for (int n = 0; n < 2; ++n) _Pragma("unroll") for (int k = 0; k < 2; ++k) \
;         acc[ai][bj][m][n] = __builtin_amdgcn_mfma_f32_16x16x32_bf16(Bt[n][k], At[m][k], acc[ai][bj][m][n], 0, 0, 0); __builtin_amdgcn_s_setprio(0); } while (0)
; #define PG8_WAIT_V(n) asm volatile("s_waitcnt vmcnt(" #n ")" ::: "memory")
; #define PG8_WAIT_L(n) asm volatile("s_waitcnt lgkmcnt(" #n ")" ::: "memory")
; #define PG8_BAR __builtin_amdgcn_s_barrier()
; #define PG8_SCHED __builtin_amdgcn_sched_barrier(0)
; template <class Epi, class Sched>
; __device__ __forceinline__ void gemm_phase(const int wv, LAS unsigned char* lds, const Gemm g, const Sched& S, const Epi& E) {
;     ...
;             PG8_STAGE(PG8_SB(0, 1), b2 + hstepB, voffB);
;             PG8_WAIT_V(6); PG8_BAR; PG8_MMA(1, 1, At, B1); PG8_BAR;
;             PG8_LDB(B0, 1, 0); PG8_SCHED; PG8_LDA(At, 1, 0); PG8_STAGE(PG8_SA(0, 1), a2 + hstepA, voffA);
;             PG8_WAIT_L(8); PG8_BAR; PG8_WAIT_L(0); PG8_MMA(0, 0, At, B0); PG8_BAR; PG8_SCHED;
;             PG8_LDB(B1, 1, 1); PG8_STAGE(PG8_SB(1, 0), b3, voffB);
;             PG8_BAR; PG8_WAIT_L(0); PG8_MMA(0, 1, At, B1); PG8_BAR;
;             PG8_LDA(At, 1, 1); PG8_STAGE(PG8_SA(1, 0), a3, voffA);
	s_add_u32 s46, s20, 0x80000
	s_addc_u32 s47, s21, 0
	s_add_i32 s45, s38, s29
	v_lshl_add_u64 v[128:129], s[46:47], 0, v[150:151]
	s_mov_b32 m0, s45
	s_nop 0
	global_load_lds_dwordx4 v[128:129], off
	v_lshl_add_u64 v[128:129], s[46:47], 0, v[154:155]
	s_add_i32 m0, s45, 0x2000
	s_nop 0
	global_load_lds_dwordx4 v[128:129], off
	s_waitcnt vmcnt(6)
	s_barrier
	v_mfma_f32_16x16x32_bf16 v[52:55], v[200:203], v[144:147], v[52:55]
	v_mfma_f32_16x16x32_bf16 v[48:51], v[208:211], v[144:147], v[48:51]
	v_mfma_f32_16x16x32_bf16 v[36:39], v[200:203], v[168:171], v[36:39]
	v_mfma_f32_16x16x32_bf16 v[32:35], v[208:211], v[168:171], v[32:35]
	v_mfma_f32_16x16x32_bf16 v[20:23], v[200:203], v[184:187], v[20:23]
	v_mfma_f32_16x16x32_bf16 v[16:19], v[208:211], v[184:187], v[16:19]
	v_mfma_f32_16x16x32_bf16 v[4:7], v[200:203], v[192:195], v[4:7]
	v_mfma_f32_16x16x32_bf16 v[0:3], v[208:211], v[192:195], v[0:3]
	v_mfma_f32_16x16x32_bf16 v[52:55], v[204:207], v[164:167], v[52:55]
	v_mfma_f32_16x16x32_bf16 v[48:51], v[212:215], v[164:167], v[48:51]
	v_mfma_f32_16x16x32_bf16 v[36:39], v[204:207], v[180:183], v[36:39]
	v_mfma_f32_16x16x32_bf16 v[32:35], v[212:215], v[180:183], v[32:35]
	v_mfma_f32_16x16x32_bf16 v[20:23], v[204:207], v[188:191], v[20:23]
	v_mfma_f32_16x16x32_bf16 v[16:19], v[212:215], v[188:191], v[16:19]
	v_mfma_f32_16x16x32_bf16 v[4:7], v[204:207], v[196:199], v[4:7]
	v_mfma_f32_16x16x32_bf16 v[0:3], v[212:215], v[196:199], v[0:3]
	s_add_i32 s45, 0, 0x18000
	v_add_u32_e32 v140, s45, v173
	s_barrier
	ds_read_b128 v[128:131], v140
	ds_read_b128 v[132:135], v140 offset:1024
	ds_read_b128 v[136:139], v140 offset:2048
	ds_read_b128 v[140:143], v140 offset:3072
	s_add_u32 s22, s22, 0x80000
	s_addc_u32 s23, s23, 0
	s_mov_b32 m0, s31
	v_lshl_add_u64 v[200:201], s[22:23], 0, v[148:149]
	ds_read_b128 v[144:147], v176 offset:32768
	ds_read_b128 v[164:167], v176 offset:33792
	ds_read_b128 v[168:171], v176 offset:34816
	ds_read_b128 v[180:183], v176 offset:35840
	ds_read_b128 v[184:187], v176 offset:36864
	ds_read_b128 v[188:191], v176 offset:37888
	ds_read_b128 v[192:195], v176 offset:38912
	ds_read_b128 v[196:199], v176 offset:39936
	global_load_lds_dwordx4 v[200:201], off
	v_lshl_add_u64 v[200:201], s[22:23], 0, v[152:153]
	s_mov_b32 m0, s33
	s_nop 0
	global_load_lds_dwordx4 v[200:201], off
	s_waitcnt lgkmcnt(8)
	s_barrier
	s_waitcnt lgkmcnt(0)
	s_waitcnt lgkmcnt(0)
	v_mfma_f32_16x16x32_bf16 v[124:127], v[128:131], v[144:147], v[124:127]
	v_mfma_f32_16x16x32_bf16 v[120:123], v[136:139], v[144:147], v[120:123]
	v_mfma_f32_16x16x32_bf16 v[108:111], v[128:131], v[168:171], v[108:111]
	v_mfma_f32_16x16x32_bf16 v[104:107], v[136:139], v[168:171], v[104:107]
	v_mfma_f32_16x16x32_bf16 v[92:95], v[128:131], v[184:187], v[92:95]
	v_mfma_f32_16x16x32_bf16 v[88:91], v[136:139], v[184:187], v[88:91]
	v_mfma_f32_16x16x32_bf16 v[76:79], v[128:131], v[192:195], v[76:79]
	v_mfma_f32_16x16x32_bf16 v[72:75], v[136:139], v[192:195], v[72:75]
	v_mfma_f32_16x16x32_bf16 v[124:127], v[132:135], v[164:167], v[124:127]
	v_mfma_f32_16x16x32_bf16 v[120:123], v[140:143], v[164:167], v[120:123]
	v_mfma_f32_16x16x32_bf16 v[108:111], v[132:135], v[180:183], v[108:111]
	v_mfma_f32_16x16x32_bf16 v[104:107], v[140:143], v[180:183], v[104:107]
	v_mfma_f32_16x16x32_bf16 v[92:95], v[132:135], v[188:191], v[92:95]
	v_mfma_f32_16x16x32_bf16 v[88:91], v[140:143], v[188:191], v[88:91]
	v_mfma_f32_16x16x32_bf16 v[76:79], v[132:135], v[196:199], v[76:79]
	v_mfma_f32_16x16x32_bf16 v[72:75], v[140:143], v[196:199], v[72:75]
	s_barrier
	s_add_i32 s22, 0, 0x1c000
	s_add_i32 s23, s45, s29
	v_add_u32_e32 v212, s22, v173
	v_lshl_add_u64 v[216:217], v[216:217], 0, s[6:7]
	s_mov_b32 m0, s23
	ds_read_b128 v[200:203], v212
	ds_read_b128 v[204:207], v212 offset:1024
	ds_read_b128 v[208:211], v212 offset:2048
	ds_read_b128 v[212:215], v212 offset:3072
	global_load_lds_dwordx4 v[216:217], off
	v_lshl_add_u64 v[216:217], v[218:219], 0, s[6:7]
	s_add_i32 m0, s23, 0x2000
	s_nop 0
	global_load_lds_dwordx4 v[216:217], off
	s_barrier
	s_waitcnt lgkmcnt(0)
	s_waitcnt lgkmcnt(0)
	v_mfma_f32_16x16x32_bf16 v[116:119], v[200:203], v[144:147], v[116:119]
	v_mfma_f32_16x16x32_bf16 v[112:115], v[208:211], v[144:147], v[112:115]
	v_mfma_f32_16x16x32_bf16 v[100:103], v[200:203], v[168:171], v[100:103]
	v_mfma_f32_16x16x32_bf16 v[96:99], v[208:211], v[168:171], v[96:99]
	v_mfma_f32_16x16x32_bf16 v[84:87], v[200:203], v[184:187], v[84:87]
	v_mfma_f32_16x16x32_bf16 v[80:83], v[208:211], v[184:187], v[80:83]
	v_mfma_f32_16x16x32_bf16 v[68:71], v[200:203], v[192:195], v[68:71]
	v_mfma_f32_16x16x32_bf16 v[64:67], v[208:211], v[192:195], v[64:67]
	v_mfma_f32_16x16x32_bf16 v[116:119], v[204:207], v[164:167], v[116:119]
	v_mfma_f32_16x16x32_bf16 v[112:115], v[212:215], v[164:167], v[112:115]
	v_mfma_f32_16x16x32_bf16 v[100:103], v[204:207], v[180:183], v[100:103]
	v_mfma_f32_16x16x32_bf16 v[96:99], v[212:215], v[180:183], v[96:99]
	v_mfma_f32_16x16x32_bf16 v[84:87], v[204:207], v[188:191], v[84:87]
	v_mfma_f32_16x16x32_bf16 v[80:83], v[212:215], v[188:191], v[80:83]
	v_mfma_f32_16x16x32_bf16 v[68:71], v[204:207], v[196:199], v[68:71]
	v_mfma_f32_16x16x32_bf16 v[64:67], v[212:215], v[196:199], v[64:67]
	s_mov_b32 m0, s35
	v_lshl_add_u64 v[216:217], v[220:221], 0, s[6:7]
	s_barrier
	ds_read_b128 v[144:147], v176 offset:49152
	ds_read_b128 v[164:167], v176 offset:50176
	ds_read_b128 v[168:171], v176 offset:51200
	ds_read_b128 v[180:183], v176 offset:52224
	ds_read_b128 v[184:187], v176 offset:53248
	ds_read_b128 v[188:191], v176 offset:54272
	ds_read_b128 v[192:195], v176 offset:55296
	ds_read_b128 v[196:199], v176 offset:56320
	global_load_lds_dwordx4 v[216:217], off
	v_lshl_add_u64 v[216:217], v[222:223], 0, s[6:7]
	s_mov_b32 m0, s36
	s_nop 0
	global_load_lds_dwordx4 v[216:217], off
	s_barrier
; #define PG8_STAGE(bufoff, gbase, voff) do { _Pragma("unroll") for (int _i = 0; _i < 2; ++_i) \
;         __builtin_amdgcn_global_load_lds((const unsigned*)((const char*)(gbase) + (voff)[_i]), (LAS unsigned*)(lds + (bufoff) + ldsw + _i * 8192), 16, 0, 0); } while (0)
; #define PG8_LDA(dst, b, h) do { _Pragma("unroll") for (int m = 0; m < 4; ++m) _Pragma("unroll") for (int k = 0; k < 2; ++k) dst[m][k] = *(const LAS bf16x8*)(lds + PG8_SA(b, h) + aoff + m * 2048 + k * 1024); } while (0)
; #define PG8_MMA(ai, bj, At, Bt) do { __builtin_amdgcn_s_setprio(1); _Pragma("unroll") for (int m = 0; m < 4; ++m) _Pragma("unroll") for (int n = 0; n < 2; ++n) _Pragma("unroll") for (int k = 0; k < 2; ++k) \
;         acc[ai][bj][m][n] = __builtin_amdgcn_mfma_f32_16x16x32_bf16(Bt[n][k], At[m][k], acc[ai][bj][m][n], 0, 0, 0); __builtin_amdgcn_s_setprio(0); } while (0)
; #define PG8_WAIT_V(n) asm volatile("s_waitcnt vmcnt(" #n ")" ::: "memory")
; #define PG8_WAIT_L(n) asm volatile("s_waitcnt lgkmcnt(" #n ")" ::: "memory")
; #define PG8_BAR __builtin_amdgcn_s_barrier()
; #define PG8_SCHED __builtin_amdgcn_sched_barrier(0)
; template <class Epi, class Sched>
; __device__ __forceinline__ void gemm_phase(const int wv, LAS unsigned char* lds, const Gemm g, const Sched& S, const Epi& E) {
;     ...
;             PG8_LDA(At, 1, 1); PG8_STAGE(PG8_SA(1, 0), a3, voffA);
;             PG8_BAR; PG8_WAIT_L(0); PG8_MMA(1, 0, At, B0); PG8_BAR; PG8_SCHED;
;             PG8_STAGE(PG8_SB(1, 1), b3 + hstepB, voffB);
;             PG8_WAIT_V(6); PG8_BAR; PG8_MMA(1, 1, At, B1); PG8_BAR;
;         }
;     __device__ __forceinline__ void operator()(const f32x4 (&acc)[2][2][4][2], const Unit& u, int wr, int wc, int fr, int fq) const {
;         const int row0 = u.pm * 256 + wr * 64 + fr; const int col0 = u.pn * 256 + wc * 32 + 8 * fq;
; #pragma unroll
;         for (int ai = 0; ai < 2; ++ai) {
;             u32x4 gv[4][2], yv[4][2];
; #pragma unroll
;             for (int m = 0; m < 4; ++m)
; #pragma unroll
;                 for (int bj = 0; bj < 2; ++bj) {
;                     const int row = row0 + ai * 128 + m * 16, col = col0 + bj * 128;
;                     gv[m][bj] = *(const u32x4*)(gates + (size_t)row * 2048 + SECOND * 1024 + col);
;                     if (SECOND) yv[m][bj] = *(const u32x4*)(Y + (size_t)row * 1024 + col);
;                 }
	s_waitcnt lgkmcnt(0)
	s_waitcnt lgkmcnt(0)
	v_mfma_f32_16x16x32_bf16 v[60:63], v[128:131], v[144:147], v[60:63]
	v_mfma_f32_16x16x32_bf16 v[56:59], v[136:139], v[144:147], v[56:59]
	v_mfma_f32_16x16x32_bf16 v[44:47], v[128:131], v[168:171], v[44:47]
	v_mfma_f32_16x16x32_bf16 v[40:43], v[136:139], v[168:171], v[40:43]
	v_mfma_f32_16x16x32_bf16 v[28:31], v[128:131], v[184:187], v[28:31]
	v_mfma_f32_16x16x32_bf16 v[24:27], v[136:139], v[184:187], v[24:27]
	v_mfma_f32_16x16x32_bf16 v[12:15], v[128:131], v[192:195], v[12:15]
	v_mfma_f32_16x16x32_bf16 v[8:11], v[136:139], v[192:195], v[8:11]
	v_mfma_f32_16x16x32_bf16 v[60:63], v[132:135], v[164:167], v[60:63]
	v_mfma_f32_16x16x32_bf16 v[56:59], v[140:143], v[164:167], v[56:59]
	v_mfma_f32_16x16x32_bf16 v[44:47], v[132:135], v[180:183], v[44:47]
	v_mfma_f32_16x16x32_bf16 v[40:43], v[140:143], v[180:183], v[40:43]
	v_mfma_f32_16x16x32_bf16 v[28:31], v[132:135], v[188:191], v[28:31]
	v_mfma_f32_16x16x32_bf16 v[24:27], v[140:143], v[188:191], v[24:27]
	v_mfma_f32_16x16x32_bf16 v[12:15], v[132:135], v[196:199], v[12:15]
	v_mfma_f32_16x16x32_bf16 v[8:11], v[140:143], v[196:199], v[8:11]
	s_barrier
	s_add_u32 s20, s20, 0x80080
	s_addc_u32 s21, s21, 0
	s_add_i32 s22, s22, s29
	v_lshl_add_u64 v[128:129], s[20:21], 0, v[150:151]
	s_mov_b32 m0, s22
	s_nop 0
	global_load_lds_dwordx4 v[128:129], off
	v_lshl_add_u64 v[128:129], s[20:21], 0, v[154:155]
	s_add_i32 m0, s22, 0x2000
	s_nop 0
	global_load_lds_dwordx4 v[128:129], off
	s_waitcnt vmcnt(6)
	s_barrier
	v_mfma_f32_16x16x32_bf16 v[52:55], v[200:203], v[144:147], v[52:55]
	v_mfma_f32_16x16x32_bf16 v[48:51], v[208:211], v[144:147], v[48:51]
	v_mfma_f32_16x16x32_bf16 v[36:39], v[200:203], v[168:171], v[36:39]
	v_mfma_f32_16x16x32_bf16 v[32:35], v[208:211], v[168:171], v[32:35]
	v_mfma_f32_16x16x32_bf16 v[20:23], v[200:203], v[184:187], v[20:23]
	v_mfma_f32_16x16x32_bf16 v[16:19], v[208:211], v[184:187], v[16:19]
	v_mfma_f32_16x16x32_bf16 v[4:7], v[200:203], v[192:195], v[4:7]
	v_mfma_f32_16x16x32_bf16 v[0:3], v[208:211], v[192:195], v[0:3]
	v_mfma_f32_16x16x32_bf16 v[52:55], v[204:207], v[164:167], v[52:55]
	v_mfma_f32_16x16x32_bf16 v[48:51], v[212:215], v[164:167], v[48:51]
	v_mfma_f32_16x16x32_bf16 v[36:39], v[204:207], v[180:183], v[36:39]
	v_mfma_f32_16x16x32_bf16 v[32:35], v[212:215], v[180:183], v[32:35]
	v_mfma_f32_16x16x32_bf16 v[20:23], v[204:207], v[188:191], v[20:23]
	v_mfma_f32_16x16x32_bf16 v[16:19], v[212:215], v[188:191], v[16:19]
	v_mfma_f32_16x16x32_bf16 v[4:7], v[204:207], v[196:199], v[4:7]
	v_mfma_f32_16x16x32_bf16 v[0:3], v[212:215], v[196:199], v[0:3]
	s_add_i32 s44, s44, 2
	s_add_u32 s18, s18, 0x100
	s_addc_u32 s19, s19, 0
	s_add_u32 s42, s42, 0x100
	s_addc_u32 s43, s43, 0
	s_cmp_gt_u32 s44, 29
	s_barrier
	s_cbranch_scc0 .LBB0_597
	v_lshl_add_u32 v164, s16, 8, v172
	v_lshl_or_b32 v128, s39, 8, v174
	v_ashrrev_i32_e32 v165, 31, v164
	v_ashrrev_i32_e32 v129, 31, v128
	v_lshlrev_b64 v[130:131], 12, v[164:165]
	v_lshl_add_u64 v[130:131], s[4:5], 0, v[130:131]
	v_lshlrev_b64 v[166:167], 1, v[128:129]
	v_lshl_add_u64 v[128:129], v[130:131], 0, v[166:167]
	v_lshlrev_b64 v[130:131], 11, v[164:165]
	v_lshl_add_u64 v[130:131], s[2:3], 0, v[130:131]
	v_lshl_add_u64 v[224:225], v[130:131], 0, v[166:167]
	global_load_dwordx4 v[180:183], v[128:129], off offset:2048
	global_load_dwordx4 v[184:187], v[224:225], off
	global_load_dwordx4 v[188:191], v[128:129], off offset:2304
	global_load_dwordx4 v[192:195], v[224:225], off offset:256
	v_or_b32_e32 v128, 16, v164
	v_ashrrev_i32_e32 v129, 31, v128
	v_lshlrev_b64 v[134:135], 12, v[128:129]
	v_lshlrev_b64 v[128:129], 11, v[128:129]
	v_lshl_add_u64 v[134:135], s[4:5], 0, v[134:135]
	v_lshl_add_u64 v[128:129], s[2:3], 0, v[128:129]
	v_lshl_add_u64 v[134:135], v[134:135], 0, v[166:167]
	v_lshl_add_u64 v[226:227], v[128:129], 0, v[166:167]
	global_load_dwordx4 v[196:199], v[134:135], off offset:2048
	global_load_dwordx4 v[200:203], v[226:227], off
	v_or_b32_e32 v130, 32, v164
	v_or_b32_e32 v132, 48, v164
	v_ashrrev_i32_e32 v131, 31, v130
	v_ashrrev_i32_e32 v133, 31, v132
	v_lshlrev_b64 v[136:137], 12, v[130:131]
	v_lshlrev_b64 v[130:131], 11, v[130:131]
	v_lshlrev_b64 v[138:139], 12, v[132:133]
	v_lshlrev_b64 v[132:133], 11, v[132:133]
	v_lshl_add_u64 v[136:137], s[4:5], 0, v[136:137]
	v_lshl_add_u64 v[130:131], s[2:3], 0, v[130:131]
	v_lshl_add_u64 v[138:139], s[4:5], 0, v[138:139]
	v_lshl_add_u64 v[132:133], s[2:3], 0, v[132:133]
	v_lshl_add_u64 v[128:129], v[136:137], 0, v[166:167]
	v_lshl_add_u64 v[170:171], v[130:131], 0, v[166:167]
	v_lshl_add_u64 v[130:131], v[138:139], 0, v[166:167]
	v_lshl_add_u64 v[168:169], v[132:133], 0, v[166:167]
	global_load_dwordx4 v[204:207], v[134:135], off offset:2304
	global_load_dwordx4 v[208:211], v[226:227], off offset:256
	global_load_dwordx4 v[212:215], v[128:129], off offset:2048
	global_load_dwordx4 v[216:219], v[128:129], off offset:2304
	global_load_dwordx4 v[220:223], v[170:171], off
	global_load_dwordx4 v[144:147], v[170:171], off offset:256
	global_load_dwordx4 v[140:143], v[130:131], off offset:2048
	global_load_dwordx4 v[132:135], v[130:131], off offset:2304
	global_load_dwordx4 v[136:139], v[168:169], off
	s_nop 0
	global_load_dwordx4 v[128:131], v[168:169], off offset:256
	s_and_b64 vcc, exec, s[0:1]
	s_mov_b32 s39, s8
	s_mov_b32 s16, s10
	s_mov_b64 s[20:21], s[14:15]
	s_mov_b64 s[18:19], s[12:13]
	s_waitcnt vmcnt(0)
; __device__ __forceinline__ unsigned cvt_pk_bf16(float lo, float hi) { unsigned r; asm volatile("v_cvt_pk_bf16_f32 %0, %1, %2" : "=v"(r) : "v"(lo), "v"(hi)); return r; }
; __device__ __forceinline__ float bflo(unsigned u) { return __uint_as_float(u << 16); }
; __device__ __forceinline__ float bfhi(unsigned u) { return __uint_as_float(u & 0xffff0000u); }
;     __device__ __forceinline__ void operator()(const f32x4 (&acc)[2][2][4][2], const Unit& u, int wr, int wc, int fr, int fq) const {
;     ...
; #pragma unroll
;             for (int m = 0; m < 4; ++m)
; #pragma unroll
;                 for (int bj = 0; bj < 2; ++bj) {
;                     const int row = row0 + ai * 128 + m * 16, col = col0 + bj * 128;
;                     const u32x4 g = gv[m][bj];
;                     const f32x4 a0 = acc[ai][bj][m][0], a1 = acc[ai][bj][m][1];
;                     float r[8] = {a0[0] * bflo(g.x), a0[1] * bfhi(g.x), a0[2] * bflo(g.y), a0[3] * bfhi(g.y), a1[0] * bflo(g.z), a1[1] * bfhi(g.z), a1[2] * bflo(g.w), a1[3] * bfhi(g.w)};
;                     if (SECOND) { const u32x4 y = yv[m][bj];
;                         r[0] += bflo(y.x); r[1] += bfhi(y.x); r[2] += bflo(y.y); r[3] += bfhi(y.y); r[4] += bflo(y.z); r[5] += bfhi(y.z); r[6] += bflo(y.w); r[7] += bfhi(y.w); }
;                     u32x4 w; w.x = cvt_pk_bf16(r[0], r[1]); w.y = cvt_pk_bf16(r[2], r[3]); w.z = cvt_pk_bf16(r[4], r[5]); w.w = cvt_pk_bf16(r[6], r[7]);
;                     *(u32x4*)(Y + (size_t)row * 1024 + col) = w;
;                 }
	v_lshlrev_b32_e32 v231, 16, v184
	v_lshlrev_b32_e32 v235, 16, v188
	v_lshlrev_b32_e32 v239, 16, v192
	v_and_b32_e32 v188, 0xffff0000, v188
	v_fmac_f32_e32 v239, v116, v235
	v_and_b32_e32 v116, 0xffff0000, v192
	v_lshlrev_b32_e32 v165, 16, v180
	v_and_b32_e32 v180, 0xffff0000, v180
	v_lshlrev_b32_e32 v229, 16, v182
	v_and_b32_e32 v184, 0xffff0000, v184
	v_lshlrev_b32_e32 v233, 16, v186
	v_lshlrev_b32_e32 v236, 16, v189
	v_fmac_f32_e32 v116, v117, v188
	v_lshlrev_b32_e32 v117, 16, v193
	v_lshlrev_b32_e32 v228, 16, v181
	v_and_b32_e32 v181, 0xffff0000, v181
	v_and_b32_e32 v182, 0xffff0000, v182
	v_lshlrev_b32_e32 v230, 16, v183
	v_and_b32_e32 v183, 0xffff0000, v183
	v_lshlrev_b32_e32 v232, 16, v185
	v_and_b32_e32 v185, 0xffff0000, v185
	v_and_b32_e32 v186, 0xffff0000, v186
	v_lshlrev_b32_e32 v234, 16, v187
	v_and_b32_e32 v187, 0xffff0000, v187
	v_and_b32_e32 v189, 0xffff0000, v189
	v_fmac_f32_e32 v231, v124, v165
	v_fmac_f32_e32 v184, v125, v180
	v_fmac_f32_e32 v233, v120, v229
	v_cvt_pk_bf16_f32 v120, v231, v184
	v_fmac_f32_e32 v117, v118, v236
	v_and_b32_e32 v118, 0xffff0000, v193
	v_lshlrev_b32_e32 v237, 16, v190
	v_and_b32_e32 v190, 0xffff0000, v190
	v_fmac_f32_e32 v232, v126, v228
	v_fmac_f32_e32 v185, v127, v181
	v_fmac_f32_e32 v186, v121, v182
	v_fmac_f32_e32 v234, v122, v230
	v_fmac_f32_e32 v187, v123, v183
	v_cvt_pk_bf16_f32 v121, v232, v185
	v_cvt_pk_bf16_f32 v122, v233, v186
	v_cvt_pk_bf16_f32 v123, v234, v187
	global_store_dwordx4 v[224:225], v[120:123], off
	v_fmac_f32_e32 v118, v119, v189
	v_lshlrev_b32_e32 v119, 16, v194
	v_and_b32_e32 v120, 0xffff0000, v194
	v_lshlrev_b32_e32 v238, 16, v191
	v_and_b32_e32 v191, 0xffff0000, v191
	v_fmac_f32_e32 v119, v112, v237
	v_fmac_f32_e32 v120, v113, v190
	v_lshlrev_b32_e32 v121, 16, v195
	v_and_b32_e32 v122, 0xffff0000, v195
	v_cvt_pk_bf16_f32 v112, v239, v116
	v_fmac_f32_e32 v121, v114, v238
	v_fmac_f32_e32 v122, v115, v191
	v_cvt_pk_bf16_f32 v113, v117, v118
	v_cvt_pk_bf16_f32 v114, v119, v120
	v_cvt_pk_bf16_f32 v115, v121, v122
	global_store_dwordx4 v[224:225], v[112:115], off offset:256
	v_lshlrev_b32_e32 v120, 16, v200
	v_lshlrev_b32_e32 v116, 16, v198
	v_lshlrev_b32_e32 v112, 16, v196
	v_and_b32_e32 v113, 0xffff0000, v196
	v_fmac_f32_e32 v120, v108, v112
	v_and_b32_e32 v108, 0xffff0000, v200
	v_lshlrev_b32_e32 v114, 16, v197
	v_fmac_f32_e32 v108, v109, v113
	v_lshlrev_b32_e32 v109, 16, v201
	v_and_b32_e32 v115, 0xffff0000, v197
	v_fmac_f32_e32 v109, v110, v114
	v_and_b32_e32 v110, 0xffff0000, v201
	v_and_b32_e32 v117, 0xffff0000, v198
	v_fmac_f32_e32 v110, v111, v115
	v_lshlrev_b32_e32 v111, 16, v202
	v_and_b32_e32 v112, 0xffff0000, v202
	v_lshlrev_b32_e32 v118, 16, v199
	v_and_b32_e32 v119, 0xffff0000, v199
	v_fmac_f32_e32 v111, v104, v116
	v_fmac_f32_e32 v112, v105, v117
	v_lshlrev_b32_e32 v113, 16, v203
	v_and_b32_e32 v114, 0xffff0000, v203
	v_cvt_pk_bf16_f32 v104, v120, v108
	v_fmac_f32_e32 v113, v106, v118
	v_fmac_f32_e32 v114, v107, v119
	v_cvt_pk_bf16_f32 v105, v109, v110
	v_cvt_pk_bf16_f32 v106, v111, v112
	v_cvt_pk_bf16_f32 v107, v113, v114
	global_store_dwordx4 v[226:227], v[104:107], off
	v_lshlrev_b32_e32 v112, 16, v208
	v_lshlrev_b32_e32 v108, 16, v206
	v_lshlrev_b32_e32 v104, 16, v204
	v_and_b32_e32 v105, 0xffff0000, v204
	v_fmac_f32_e32 v112, v100, v104
	v_and_b32_e32 v100, 0xffff0000, v208
	v_lshlrev_b32_e32 v106, 16, v205
	v_fmac_f32_e32 v100, v101, v105
	v_lshlrev_b32_e32 v101, 16, v209
	v_and_b32_e32 v107, 0xffff0000, v205
	v_fmac_f32_e32 v101, v102, v106
	v_and_b32_e32 v102, 0xffff0000, v209
	v_and_b32_e32 v109, 0xffff0000, v206
	v_fmac_f32_e32 v102, v103, v107
	v_lshlrev_b32_e32 v103, 16, v210
	v_and_b32_e32 v104, 0xffff0000, v210
	v_lshlrev_b32_e32 v110, 16, v207
	v_and_b32_e32 v111, 0xffff0000, v207
	v_fmac_f32_e32 v103, v96, v108
	v_fmac_f32_e32 v104, v97, v109
	v_lshlrev_b32_e32 v105, 16, v211
	v_and_b32_e32 v106, 0xffff0000, v211
	v_cvt_pk_bf16_f32 v96, v112, v100
	v_fmac_f32_e32 v105, v98, v110
	v_fmac_f32_e32 v106, v99, v111
	v_cvt_pk_bf16_f32 v97, v101, v102
	v_cvt_pk_bf16_f32 v98, v103, v104
	v_cvt_pk_bf16_f32 v99, v105, v106
	global_store_dwordx4 v[226:227], v[96:99], off offset:256
	v_lshlrev_b32_e32 v104, 16, v220
	v_lshlrev_b32_e32 v100, 16, v214
	v_lshlrev_b32_e32 v96, 16, v212
	v_and_b32_e32 v97, 0xffff0000, v212
	v_fmac_f32_e32 v104, v92, v96
	v_and_b32_e32 v92, 0xffff0000, v220
	v_lshlrev_b32_e32 v98, 16, v213
	v_fmac_f32_e32 v92, v93, v97
	v_lshlrev_b32_e32 v93, 16, v221
	v_and_b32_e32 v99, 0xffff0000, v213
	v_fmac_f32_e32 v93, v94, v98
	v_and_b32_e32 v94, 0xffff0000, v221
	v_and_b32_e32 v101, 0xffff0000, v214
	v_fmac_f32_e32 v94, v95, v99
	v_lshlrev_b32_e32 v95, 16, v222
	v_and_b32_e32 v96, 0xffff0000, v222
	v_lshlrev_b32_e32 v102, 16, v215
	v_and_b32_e32 v103, 0xffff0000, v215
	v_fmac_f32_e32 v95, v88, v100
	v_fmac_f32_e32 v96, v89, v101
	v_lshlrev_b32_e32 v97, 16, v223
	v_and_b32_e32 v98, 0xffff0000, v223
	v_cvt_pk_bf16_f32 v88, v104, v92
	v_fmac_f32_e32 v97, v90, v102
	v_fmac_f32_e32 v98, v91, v103
	v_cvt_pk_bf16_f32 v89, v93, v94
	v_cvt_pk_bf16_f32 v90, v95, v96
	v_cvt_pk_bf16_f32 v91, v97, v98
	global_store_dwordx4 v[170:171], v[88:91], off
	v_lshlrev_b32_e32 v96, 16, v144
	v_lshlrev_b32_e32 v92, 16, v218
	v_lshlrev_b32_e32 v88, 16, v216
	v_and_b32_e32 v89, 0xffff0000, v216
	v_fmac_f32_e32 v96, v84, v88
	v_and_b32_e32 v84, 0xffff0000, v144
	v_lshlrev_b32_e32 v90, 16, v217
	v_fmac_f32_e32 v84, v85, v89
	v_lshlrev_b32_e32 v85, 16, v145
	v_and_b32_e32 v91, 0xffff0000, v217
	v_fmac_f32_e32 v85, v86, v90
	v_and_b32_e32 v86, 0xffff0000, v145
	v_and_b32_e32 v93, 0xffff0000, v218
	v_fmac_f32_e32 v86, v87, v91
	v_lshlrev_b32_e32 v87, 16, v146
; __device__ __forceinline__ unsigned cvt_pk_bf16(float lo, float hi) { unsigned r; asm volatile("v_cvt_pk_bf16_f32 %0, %1, %2" : "=v"(r) : "v"(lo), "v"(hi)); return r; }
; __device__ __forceinline__ float bflo(unsigned u) { return __uint_as_float(u << 16); }
; __device__ __forceinline__ float bfhi(unsigned u) { return __uint_as_float(u & 0xffff0000u); }
;     __device__ __forceinline__ void operator()(const f32x4 (&acc)[2][2][4][2], const Unit& u, int wr, int wc, int fr, int fq) const {
;     ...
;         for (int ai = 0; ai < 2; ++ai) {
;             u32x4 gv[4][2], yv[4][2];
; #pragma unroll
;             for (int m = 0; m < 4; ++m)
; #pragma unroll
;                 for (int bj = 0; bj < 2; ++bj) {
;                     const int row = row0 + ai * 128 + m * 16, col = col0 + bj * 128;
;                     gv[m][bj] = *(const u32x4*)(gates + (size_t)row * 2048 + SECOND * 1024 + col);
;                     if (SECOND) yv[m][bj] = *(const u32x4*)(Y + (size_t)row * 1024 + col);
;                 }
; #pragma unroll
;             for (int m = 0; m < 4; ++m)
; #pragma unroll
;                 for (int bj = 0; bj < 2; ++bj) {
;                     const int row = row0 + ai * 128 + m * 16, col = col0 + bj * 128;
;                     const u32x4 g = gv[m][bj];
;                     const f32x4 a0 = acc[ai][bj][m][0], a1 = acc[ai][bj][m][1];
;                     float r[8] = {a0[0] * bflo(g.x), a0[1] * bfhi(g.x), a0[2] * bflo(g.y), a0[3] * bfhi(g.y), a1[0] * bflo(g.z), a1[1] * bfhi(g.z), a1[2] * bflo(g.w), a1[3] * bfhi(g.w)};
;                     if (SECOND) { const u32x4 y = yv[m][bj];
;                         r[0] += bflo(y.x); r[1] += bfhi(y.x); r[2] += bflo(y.y); r[3] += bfhi(y.y); r[4] += bflo(y.z); r[5] += bfhi(y.z); r[6] += bflo(y.w); r[7] += bfhi(y.w); }
;                     u32x4 w; w.x = cvt_pk_bf16(r[0], r[1]); w.y = cvt_pk_bf16(r[2], r[3]); w.z = cvt_pk_bf16(r[4], r[5]); w.w = cvt_pk_bf16(r[6], r[7]);
;                     *(u32x4*)(Y + (size_t)row * 1024 + col) = w;
;                 }
	v_and_b32_e32 v88, 0xffff0000, v146
	v_lshlrev_b32_e32 v94, 16, v219
	v_and_b32_e32 v95, 0xffff0000, v219
	v_fmac_f32_e32 v87, v80, v92
	v_fmac_f32_e32 v88, v81, v93
	v_lshlrev_b32_e32 v89, 16, v147
	v_and_b32_e32 v90, 0xffff0000, v147
	v_cvt_pk_bf16_f32 v80, v96, v84
	v_fmac_f32_e32 v89, v82, v94
	v_fmac_f32_e32 v90, v83, v95
	v_cvt_pk_bf16_f32 v81, v85, v86
	v_cvt_pk_bf16_f32 v82, v87, v88
	v_cvt_pk_bf16_f32 v83, v89, v90
	global_store_dwordx4 v[170:171], v[80:83], off offset:256
	v_lshlrev_b32_e32 v88, 16, v136
	v_lshlrev_b32_e32 v84, 16, v142
	v_lshlrev_b32_e32 v80, 16, v140
	v_and_b32_e32 v81, 0xffff0000, v140
	v_fmac_f32_e32 v88, v76, v80
	v_and_b32_e32 v76, 0xffff0000, v136
	v_lshlrev_b32_e32 v82, 16, v141
	v_fmac_f32_e32 v76, v77, v81
	v_lshlrev_b32_e32 v77, 16, v137
	v_and_b32_e32 v83, 0xffff0000, v141
	v_fmac_f32_e32 v77, v78, v82
	v_and_b32_e32 v78, 0xffff0000, v137
	v_and_b32_e32 v85, 0xffff0000, v142
	v_fmac_f32_e32 v78, v79, v83
	v_lshlrev_b32_e32 v79, 16, v138
	v_and_b32_e32 v80, 0xffff0000, v138
	v_lshlrev_b32_e32 v86, 16, v143
	v_and_b32_e32 v87, 0xffff0000, v143
	v_fmac_f32_e32 v79, v72, v84
	v_fmac_f32_e32 v80, v73, v85
	v_lshlrev_b32_e32 v81, 16, v139
	v_and_b32_e32 v82, 0xffff0000, v139
	v_cvt_pk_bf16_f32 v72, v88, v76
	v_fmac_f32_e32 v81, v74, v86
	v_fmac_f32_e32 v82, v75, v87
	v_cvt_pk_bf16_f32 v73, v77, v78
	v_cvt_pk_bf16_f32 v74, v79, v80
	v_cvt_pk_bf16_f32 v75, v81, v82
	global_store_dwordx4 v[168:169], v[72:75], off
	v_lshlrev_b32_e32 v80, 16, v128
	v_lshlrev_b32_e32 v76, 16, v134
	v_lshlrev_b32_e32 v72, 16, v132
	v_and_b32_e32 v73, 0xffff0000, v132
	v_fmac_f32_e32 v80, v68, v72
	v_and_b32_e32 v68, 0xffff0000, v128
	v_lshlrev_b32_e32 v74, 16, v133
	v_fmac_f32_e32 v68, v69, v73
	v_lshlrev_b32_e32 v69, 16, v129
	v_and_b32_e32 v75, 0xffff0000, v133
	v_fmac_f32_e32 v69, v70, v74
	v_and_b32_e32 v70, 0xffff0000, v129
	v_fmac_f32_e32 v70, v71, v75
	v_lshlrev_b32_e32 v71, 16, v130
	v_and_b32_e32 v77, 0xffff0000, v134
	v_lshlrev_b32_e32 v78, 16, v135
	v_and_b32_e32 v79, 0xffff0000, v135
	v_fmac_f32_e32 v71, v64, v76
	v_and_b32_e32 v72, 0xffff0000, v130
	v_lshlrev_b32_e32 v73, 16, v131
	v_and_b32_e32 v74, 0xffff0000, v131
	v_cvt_pk_bf16_f32 v64, v80, v68
	v_fmac_f32_e32 v72, v65, v77
	v_fmac_f32_e32 v73, v66, v78
	v_fmac_f32_e32 v74, v67, v79
	v_cvt_pk_bf16_f32 v65, v69, v70
	v_cvt_pk_bf16_f32 v66, v71, v72
	v_cvt_pk_bf16_f32 v67, v73, v74
	global_store_dwordx4 v[168:169], v[64:67], off offset:256
	s_nop 1
	v_add_u32_e32 v64, 0x80, v164
	v_ashrrev_i32_e32 v65, 31, v64
	v_lshlrev_b64 v[66:67], 12, v[64:65]
	v_lshl_add_u64 v[66:67], s[4:5], 0, v[66:67]
	v_lshl_add_u64 v[66:67], v[66:67], 0, v[166:167]
	v_lshlrev_b64 v[64:65], 11, v[64:65]
	global_load_dwordx4 v[88:91], v[66:67], off offset:2048
	v_lshl_add_u64 v[64:65], s[2:3], 0, v[64:65]
	v_lshl_add_u64 v[132:133], v[64:65], 0, v[166:167]
	global_load_dwordx4 v[92:95], v[132:133], off
	global_load_dwordx4 v[96:99], v[66:67], off offset:2304
	global_load_dwordx4 v[100:103], v[132:133], off offset:256
	v_add_u32_e32 v64, 0x90, v164
	v_ashrrev_i32_e32 v65, 31, v64
	v_lshlrev_b64 v[66:67], 12, v[64:65]
	v_lshl_add_u64 v[66:67], s[4:5], 0, v[66:67]
	v_lshlrev_b64 v[64:65], 11, v[64:65]
	v_lshl_add_u64 v[64:65], s[2:3], 0, v[64:65]
	v_lshl_add_u64 v[66:67], v[66:67], 0, v[166:167]
	v_lshl_add_u64 v[134:135], v[64:65], 0, v[166:167]
	global_load_dwordx4 v[104:107], v[66:67], off offset:2048
	global_load_dwordx4 v[108:111], v[66:67], off offset:2304
	global_load_dwordx4 v[112:115], v[134:135], off
	global_load_dwordx4 v[116:119], v[134:135], off offset:256
	v_add_u32_e32 v64, 0xa0, v164
	v_ashrrev_i32_e32 v65, 31, v64
	v_lshlrev_b64 v[66:67], 12, v[64:65]
	v_lshl_add_u64 v[66:67], s[4:5], 0, v[66:67]
	v_lshlrev_b64 v[64:65], 11, v[64:65]
	v_lshl_add_u64 v[64:65], s[2:3], 0, v[64:65]
	v_lshl_add_u64 v[66:67], v[66:67], 0, v[166:167]
	v_lshl_add_u64 v[86:87], v[64:65], 0, v[166:167]
	global_load_dwordx4 v[120:123], v[66:67], off offset:2048
	global_load_dwordx4 v[124:127], v[66:67], off offset:2304
	global_load_dwordx4 v[128:131], v[86:87], off
	global_load_dwordx4 v[80:83], v[86:87], off offset:256
	v_add_u32_e32 v64, 0xb0, v164
	v_ashrrev_i32_e32 v65, 31, v64
	v_lshlrev_b64 v[66:67], 12, v[64:65]
	v_lshl_add_u64 v[66:67], s[4:5], 0, v[66:67]
	v_lshlrev_b64 v[64:65], 11, v[64:65]
	v_lshl_add_u64 v[64:65], s[2:3], 0, v[64:65]
	v_lshl_add_u64 v[66:67], v[66:67], 0, v[166:167]
	v_lshl_add_u64 v[84:85], v[64:65], 0, v[166:167]
	global_load_dwordx4 v[76:79], v[66:67], off offset:2048
	global_load_dwordx4 v[68:71], v[66:67], off offset:2304
	global_load_dwordx4 v[72:75], v[84:85], off
	s_nop 0
	global_load_dwordx4 v[64:67], v[84:85], off offset:256
	s_waitcnt vmcnt(0)
; __device__ __forceinline__ unsigned cvt_pk_bf16(float lo, float hi) { unsigned r; asm volatile("v_cvt_pk_bf16_f32 %0, %1, %2" : "=v"(r) : "v"(lo), "v"(hi)); return r; }
; __device__ __forceinline__ float bflo(unsigned u) { return __uint_as_float(u << 16); }
; __device__ __forceinline__ float bfhi(unsigned u) { return __uint_as_float(u & 0xffff0000u); }
;     __device__ __forceinline__ void operator()(const f32x4 (&acc)[2][2][4][2], const Unit& u, int wr, int wc, int fr, int fq) const {
;     ...
; #pragma unroll
;             for (int m = 0; m < 4; ++m)
; #pragma unroll
;                 for (int bj = 0; bj < 2; ++bj) {
;                     const int row = row0 + ai * 128 + m * 16, col = col0 + bj * 128;
;                     const u32x4 g = gv[m][bj];
;                     const f32x4 a0 = acc[ai][bj][m][0], a1 = acc[ai][bj][m][1];
;                     float r[8] = {a0[0] * bflo(g.x), a0[1] * bfhi(g.x), a0[2] * bflo(g.y), a0[3] * bfhi(g.y), a1[0] * bflo(g.z), a1[1] * bfhi(g.z), a1[2] * bflo(g.w), a1[3] * bfhi(g.w)};
;                     if (SECOND) { const u32x4 y = yv[m][bj];
;                         r[0] += bflo(y.x); r[1] += bfhi(y.x); r[2] += bflo(y.y); r[3] += bfhi(y.y); r[4] += bflo(y.z); r[5] += bfhi(y.z); r[6] += bflo(y.w); r[7] += bfhi(y.w); }
;                     u32x4 w; w.x = cvt_pk_bf16(r[0], r[1]); w.y = cvt_pk_bf16(r[2], r[3]); w.z = cvt_pk_bf16(r[4], r[5]); w.w = cvt_pk_bf16(r[6], r[7]);
;                     *(u32x4*)(Y + (size_t)row * 1024 + col) = w;
;                 }
	v_lshlrev_b32_e32 v136, 16, v88
	v_lshlrev_b32_e32 v140, 16, v92
	v_and_b32_e32 v88, 0xffff0000, v88
	v_fmac_f32_e32 v140, v60, v136
	v_and_b32_e32 v60, 0xffff0000, v92
	v_lshlrev_b32_e32 v137, 16, v89
	v_fmac_f32_e32 v60, v61, v88
	v_lshlrev_b32_e32 v61, 16, v93
	v_and_b32_e32 v89, 0xffff0000, v89
	v_fmac_f32_e32 v61, v62, v137
	v_and_b32_e32 v62, 0xffff0000, v93
	v_lshlrev_b32_e32 v138, 16, v90
	v_and_b32_e32 v90, 0xffff0000, v90
	v_fmac_f32_e32 v62, v63, v89
	v_lshlrev_b32_e32 v63, 16, v94
	v_and_b32_e32 v88, 0xffff0000, v94
	v_lshlrev_b32_e32 v139, 16, v91
	v_and_b32_e32 v91, 0xffff0000, v91
	v_fmac_f32_e32 v63, v56, v138
	v_fmac_f32_e32 v88, v57, v90
	v_lshlrev_b32_e32 v89, 16, v95
	v_and_b32_e32 v90, 0xffff0000, v95
	v_cvt_pk_bf16_f32 v56, v140, v60
	v_fmac_f32_e32 v89, v58, v139
	v_fmac_f32_e32 v90, v59, v91
	v_cvt_pk_bf16_f32 v57, v61, v62
	v_cvt_pk_bf16_f32 v58, v63, v88
	v_cvt_pk_bf16_f32 v59, v89, v90
	global_store_dwordx4 v[132:133], v[56:59], off
	v_lshlrev_b32_e32 v88, 16, v100
	v_lshlrev_b32_e32 v60, 16, v98
	v_lshlrev_b32_e32 v56, 16, v96
	v_and_b32_e32 v57, 0xffff0000, v96
	v_fmac_f32_e32 v88, v52, v56
	v_and_b32_e32 v52, 0xffff0000, v100
	v_lshlrev_b32_e32 v58, 16, v97
	v_fmac_f32_e32 v52, v53, v57
	v_lshlrev_b32_e32 v53, 16, v101
	v_and_b32_e32 v59, 0xffff0000, v97
	v_fmac_f32_e32 v53, v54, v58
	v_and_b32_e32 v54, 0xffff0000, v101
	v_and_b32_e32 v61, 0xffff0000, v98
	v_fmac_f32_e32 v54, v55, v59
	v_lshlrev_b32_e32 v55, 16, v102
	v_and_b32_e32 v56, 0xffff0000, v102
	v_lshlrev_b32_e32 v62, 16, v99
	v_and_b32_e32 v63, 0xffff0000, v99
	v_fmac_f32_e32 v55, v48, v60
	v_fmac_f32_e32 v56, v49, v61
	v_lshlrev_b32_e32 v57, 16, v103
	v_and_b32_e32 v58, 0xffff0000, v103
	v_cvt_pk_bf16_f32 v48, v88, v52
	v_fmac_f32_e32 v57, v50, v62
	v_fmac_f32_e32 v58, v51, v63
	v_cvt_pk_bf16_f32 v49, v53, v54
	v_cvt_pk_bf16_f32 v50, v55, v56
	v_cvt_pk_bf16_f32 v51, v57, v58
	global_store_dwordx4 v[132:133], v[48:51], off offset:256
	v_lshlrev_b32_e32 v56, 16, v112
	v_lshlrev_b32_e32 v52, 16, v106
	v_lshlrev_b32_e32 v48, 16, v104
	v_and_b32_e32 v49, 0xffff0000, v104
	v_fmac_f32_e32 v56, v44, v48
	v_and_b32_e32 v44, 0xffff0000, v112
	v_lshlrev_b32_e32 v50, 16, v105
	v_fmac_f32_e32 v44, v45, v49
	v_lshlrev_b32_e32 v45, 16, v113
	v_and_b32_e32 v51, 0xffff0000, v105
	v_fmac_f32_e32 v45, v46, v50
	v_and_b32_e32 v46, 0xffff0000, v113
	v_and_b32_e32 v53, 0xffff0000, v106
	v_fmac_f32_e32 v46, v47, v51
	v_lshlrev_b32_e32 v47, 16, v114
	v_and_b32_e32 v48, 0xffff0000, v114
	v_lshlrev_b32_e32 v54, 16, v107
	v_and_b32_e32 v55, 0xffff0000, v107
	v_fmac_f32_e32 v47, v40, v52
	v_fmac_f32_e32 v48, v41, v53
	v_lshlrev_b32_e32 v49, 16, v115
	v_and_b32_e32 v50, 0xffff0000, v115
	v_cvt_pk_bf16_f32 v40, v56, v44
	v_fmac_f32_e32 v49, v42, v54
	v_fmac_f32_e32 v50, v43, v55
	v_cvt_pk_bf16_f32 v41, v45, v46
	v_cvt_pk_bf16_f32 v42, v47, v48
	v_cvt_pk_bf16_f32 v43, v49, v50
	global_store_dwordx4 v[134:135], v[40:43], off
	v_lshlrev_b32_e32 v48, 16, v116
	v_lshlrev_b32_e32 v44, 16, v110
	v_lshlrev_b32_e32 v40, 16, v108
	v_and_b32_e32 v41, 0xffff0000, v108
	v_fmac_f32_e32 v48, v36, v40
	v_and_b32_e32 v36, 0xffff0000, v116
	v_lshlrev_b32_e32 v42, 16, v109
	v_fmac_f32_e32 v36, v37, v41
	v_lshlrev_b32_e32 v37, 16, v117
	v_and_b32_e32 v43, 0xffff0000, v109
	v_fmac_f32_e32 v37, v38, v42
	v_and_b32_e32 v38, 0xffff0000, v117
	v_and_b32_e32 v45, 0xffff0000, v110
	v_fmac_f32_e32 v38, v39, v43
	v_lshlrev_b32_e32 v39, 16, v118
	v_and_b32_e32 v40, 0xffff0000, v118
	v_lshlrev_b32_e32 v46, 16, v111
	v_and_b32_e32 v47, 0xffff0000, v111
	v_fmac_f32_e32 v39, v32, v44
	v_fmac_f32_e32 v40, v33, v45
	v_lshlrev_b32_e32 v41, 16, v119
	v_and_b32_e32 v42, 0xffff0000, v119
	v_cvt_pk_bf16_f32 v32, v48, v36
	v_fmac_f32_e32 v41, v34, v46
	v_fmac_f32_e32 v42, v35, v47
	v_cvt_pk_bf16_f32 v33, v37, v38
	v_cvt_pk_bf16_f32 v34, v39, v40
	v_cvt_pk_bf16_f32 v35, v41, v42
	global_store_dwordx4 v[134:135], v[32:35], off offset:256
; __device__ __forceinline__ unsigned cvt_pk_bf16(float lo, float hi) { unsigned r; asm volatile("v_cvt_pk_bf16_f32 %0, %1, %2" : "=v"(r) : "v"(lo), "v"(hi)); return r; }
; __device__ __forceinline__ float bflo(unsigned u) { return __uint_as_float(u << 16); }
; __device__ __forceinline__ float bfhi(unsigned u) { return __uint_as_float(u & 0xffff0000u); }
; #define PG8_WAIT_V(n) asm volatile("s_waitcnt vmcnt(" #n ")" ::: "memory")
; #define PG8_BAR __builtin_amdgcn_s_barrier()
; template <class Epi, class Sched>
; __device__ __forceinline__ void gemm_phase(const int wv, LAS unsigned char* lds, const Gemm g, const Sched& S, const Epi& E) {
;     ...
;     PG8_WAIT_V(0);
;     if (wr == 0) PG8_BAR;
;     PG8_BAR;
;     __device__ __forceinline__ void operator()(const f32x4 (&acc)[2][2][4][2], const Unit& u, int wr, int wc, int fr, int fq) const {
;     ...
; #pragma unroll
;             for (int m = 0; m < 4; ++m)
; #pragma unroll
;                 for (int bj = 0; bj < 2; ++bj) {
;                     const int row = row0 + ai * 128 + m * 16, col = col0 + bj * 128;
;                     const u32x4 g = gv[m][bj];
;                     const f32x4 a0 = acc[ai][bj][m][0], a1 = acc[ai][bj][m][1];
;                     float r[8] = {a0[0] * bflo(g.x), a0[1] * bfhi(g.x), a0[2] * bflo(g.y), a0[3] * bfhi(g.y), a1[0] * bflo(g.z), a1[1] * bfhi(g.z), a1[2] * bflo(g.w), a1[3] * bfhi(g.w)};
;                     if (SECOND) { const u32x4 y = yv[m][bj];
;                         r[0] += bflo(y.x); r[1] += bfhi(y.x); r[2] += bflo(y.y); r[3] += bfhi(y.y); r[4] += bflo(y.z); r[5] += bfhi(y.z); r[6] += bflo(y.w); r[7] += bfhi(y.w); }
;                     u32x4 w; w.x = cvt_pk_bf16(r[0], r[1]); w.y = cvt_pk_bf16(r[2], r[3]); w.z = cvt_pk_bf16(r[4], r[5]); w.w = cvt_pk_bf16(r[6], r[7]);
;                     *(u32x4*)(Y + (size_t)row * 1024 + col) = w;
;                 }
	v_lshlrev_b32_e32 v40, 16, v128
	v_lshlrev_b32_e32 v36, 16, v122
	v_lshlrev_b32_e32 v32, 16, v120
	v_and_b32_e32 v33, 0xffff0000, v120
	v_fmac_f32_e32 v40, v28, v32
	v_and_b32_e32 v28, 0xffff0000, v128
	v_lshlrev_b32_e32 v34, 16, v121
	v_fmac_f32_e32 v28, v29, v33
	v_lshlrev_b32_e32 v29, 16, v129
	v_and_b32_e32 v35, 0xffff0000, v121
	v_fmac_f32_e32 v29, v30, v34
	v_and_b32_e32 v30, 0xffff0000, v129
	v_and_b32_e32 v37, 0xffff0000, v122
	v_fmac_f32_e32 v30, v31, v35
	v_lshlrev_b32_e32 v31, 16, v130
	v_and_b32_e32 v32, 0xffff0000, v130
	v_lshlrev_b32_e32 v38, 16, v123
	v_and_b32_e32 v39, 0xffff0000, v123
	v_fmac_f32_e32 v31, v24, v36
	v_fmac_f32_e32 v32, v25, v37
	v_lshlrev_b32_e32 v33, 16, v131
	v_and_b32_e32 v34, 0xffff0000, v131
	v_cvt_pk_bf16_f32 v24, v40, v28
	v_fmac_f32_e32 v33, v26, v38
	v_fmac_f32_e32 v34, v27, v39
	v_cvt_pk_bf16_f32 v25, v29, v30
	v_cvt_pk_bf16_f32 v26, v31, v32
	v_cvt_pk_bf16_f32 v27, v33, v34
	global_store_dwordx4 v[86:87], v[24:27], off
	v_lshlrev_b32_e32 v32, 16, v80
	v_lshlrev_b32_e32 v28, 16, v126
	v_lshlrev_b32_e32 v24, 16, v124
	v_and_b32_e32 v25, 0xffff0000, v124
	v_fmac_f32_e32 v32, v20, v24
	v_and_b32_e32 v20, 0xffff0000, v80
	v_lshlrev_b32_e32 v26, 16, v125
	v_fmac_f32_e32 v20, v21, v25
	v_lshlrev_b32_e32 v21, 16, v81
	v_and_b32_e32 v27, 0xffff0000, v125
	v_fmac_f32_e32 v21, v22, v26
	v_and_b32_e32 v22, 0xffff0000, v81
	v_and_b32_e32 v29, 0xffff0000, v126
	v_fmac_f32_e32 v22, v23, v27
	v_lshlrev_b32_e32 v23, 16, v82
	v_and_b32_e32 v24, 0xffff0000, v82
	v_lshlrev_b32_e32 v30, 16, v127
	v_and_b32_e32 v31, 0xffff0000, v127
	v_fmac_f32_e32 v23, v16, v28
	v_fmac_f32_e32 v24, v17, v29
	v_lshlrev_b32_e32 v25, 16, v83
	v_and_b32_e32 v26, 0xffff0000, v83
	v_cvt_pk_bf16_f32 v16, v32, v20
	v_fmac_f32_e32 v25, v18, v30
	v_fmac_f32_e32 v26, v19, v31
	v_cvt_pk_bf16_f32 v17, v21, v22
	v_cvt_pk_bf16_f32 v18, v23, v24
	v_cvt_pk_bf16_f32 v19, v25, v26
	global_store_dwordx4 v[86:87], v[16:19], off offset:256
	v_lshlrev_b32_e32 v24, 16, v72
	v_lshlrev_b32_e32 v20, 16, v78
	v_lshlrev_b32_e32 v16, 16, v76
	v_and_b32_e32 v17, 0xffff0000, v76
	v_fmac_f32_e32 v24, v12, v16
	v_and_b32_e32 v12, 0xffff0000, v72
	v_lshlrev_b32_e32 v18, 16, v77
	v_fmac_f32_e32 v12, v13, v17
	v_lshlrev_b32_e32 v13, 16, v73
	v_and_b32_e32 v19, 0xffff0000, v77
	v_fmac_f32_e32 v13, v14, v18
	v_and_b32_e32 v14, 0xffff0000, v73
	v_and_b32_e32 v21, 0xffff0000, v78
	v_fmac_f32_e32 v14, v15, v19
	v_lshlrev_b32_e32 v15, 16, v74
	v_and_b32_e32 v16, 0xffff0000, v74
	v_lshlrev_b32_e32 v22, 16, v79
	v_and_b32_e32 v23, 0xffff0000, v79
	v_fmac_f32_e32 v15, v8, v20
	v_fmac_f32_e32 v16, v9, v21
	v_lshlrev_b32_e32 v17, 16, v75
	v_and_b32_e32 v18, 0xffff0000, v75
	v_cvt_pk_bf16_f32 v8, v24, v12
	v_fmac_f32_e32 v17, v10, v22
	v_fmac_f32_e32 v18, v11, v23
	v_cvt_pk_bf16_f32 v9, v13, v14
	v_cvt_pk_bf16_f32 v10, v15, v16
	v_cvt_pk_bf16_f32 v11, v17, v18
	global_store_dwordx4 v[84:85], v[8:11], off
	v_lshlrev_b32_e32 v16, 16, v64
	v_lshlrev_b32_e32 v12, 16, v70
	v_lshlrev_b32_e32 v8, 16, v68
	v_and_b32_e32 v9, 0xffff0000, v68
	v_fmac_f32_e32 v16, v4, v8
	v_and_b32_e32 v4, 0xffff0000, v64
	v_lshlrev_b32_e32 v10, 16, v69
	v_fmac_f32_e32 v4, v5, v9
	v_lshlrev_b32_e32 v5, 16, v65
	v_and_b32_e32 v11, 0xffff0000, v69
	v_fmac_f32_e32 v5, v6, v10
	v_and_b32_e32 v6, 0xffff0000, v65
	v_and_b32_e32 v13, 0xffff0000, v70
	v_lshlrev_b32_e32 v14, 16, v71
	v_and_b32_e32 v15, 0xffff0000, v71
	v_fmac_f32_e32 v6, v7, v11
	v_lshlrev_b32_e32 v7, 16, v66
	v_and_b32_e32 v8, 0xffff0000, v66
	v_lshlrev_b32_e32 v9, 16, v67
	v_and_b32_e32 v10, 0xffff0000, v67
	v_fmac_f32_e32 v7, v0, v12
	v_fmac_f32_e32 v8, v1, v13
	v_fmac_f32_e32 v9, v2, v14
	v_fmac_f32_e32 v10, v3, v15
	v_cvt_pk_bf16_f32 v0, v16, v4
	v_cvt_pk_bf16_f32 v1, v5, v6
	v_cvt_pk_bf16_f32 v2, v7, v8
	v_cvt_pk_bf16_f32 v3, v9, v10
	global_store_dwordx4 v[84:85], v[0:3], off offset:256
	s_cbranch_vccz .LBB0_590
	s_waitcnt vmcnt(0)
	s_cmpk_gt_u32 s24, 0xff
	s_cbranch_scc1 .LBB0_601
	s_barrier

; __device__ __forceinline__ void xcd_barrier(const int wv, const XcdBarrier& b) {
;     asm volatile("s_waitcnt vmcnt(0)" ::: "memory");
;     __syncthreads();
;     if (TIDX == 0) {
;         unsigned long long barq = (unsigned long long)b.bar; asm volatile("" : "+s"(barq));
;         unsigned* bar = (unsigned*)barq;
;         __builtin_amdgcn_s_waitcnt(0);
;         unsigned nloc = b.st[0], nx = b.st[1];
;         if (nloc == 0u) { xcd_barrier_complete(bar, b.x, nloc, nx); b.st[0] = nloc; b.st[1] = nx; }
.LBB0_602:
	s_setprio 0
	s_waitcnt vmcnt(0)
	s_waitcnt lgkmcnt(0)
	s_barrier
	v_mbcnt_lo_u32_b32 v0, -1, 0
	v_mbcnt_hi_u32_b32 v0, -1, v0
	s_nop 0
	v_sub_u32_e32 v0, 0, v0
	v_cmp_eq_u32_e32 vcc, s53, v0
	s_and_saveexec_b64 s[0:1], vcc
	s_cbranch_execz .LBB0_646
	s_add_i32 s4, 0, 0x21ff0
	s_mov_b64 s[2:3], s[58:59]
	v_mov_b32_e32 v0, s4
	s_waitcnt vmcnt(0) expcnt(0) lgkmcnt(0)
	ds_read_b32 v4, v0
	s_add_i32 s4, 0, 0x21ff4
	v_mov_b32_e32 v0, s4
	ds_read_b32 v2, v0
	s_waitcnt lgkmcnt(1)
	v_cmp_ne_u32_e32 vcc, 0, v4
	s_cbranch_vccnz .LBB0_617
	s_add_u32 s6, s2, 0x1000
	s_addc_u32 s7, s3, 0
	s_add_u32 s8, s2, 0x1100
	s_addc_u32 s9, s3, 0
	s_add_u32 s10, s2, 0x1200
	s_addc_u32 s11, s3, 0
	s_add_u32 s12, s2, 0x1300
	s_addc_u32 s13, s3, 0
	s_mov_b32 s22, 1
	s_mov_b64 s[4:5], 0
	v_mov_b64_e32 v[0:1], s[2:3]
	s_waitcnt lgkmcnt(0)
	v_mov_b64_e32 v[2:3], s[6:7]
	v_mov_b64_e32 v[4:5], s[8:9]
	v_mov_b64_e32 v[6:7], s[10:11]
	v_mov_b64_e32 v[8:9], s[12:13]
	s_branch .LBB0_607

;     __device__ void init(int b_, int G_, int c_) { so.init(TB, 42 * 256, G_, c_); G = G_; c = c_; b = b_; gstart = b_ == 0 ? 0 : 256 + 192 * b_; ng = b_ == 0 ? 448 : 192; }
; __device__ __forceinline__ KParams kparams() { unsigned long long a = (unsigned long long)__builtin_amdgcn_kernarg_segment_ptr(); asm volatile("" : "+s"(a)); return (KParams)a; }
; template <class Epi, class Sched>
; __device__ __forceinline__ void gemm_phase(const int wv, LAS unsigned char* lds, const Gemm g, const Sched& S, const Epi& E) {
;     int tid_ = TIDX; asm volatile("" : "+v"(tid_));
;     const int tid = tid_, wid = __builtin_amdgcn_readfirstlane(tid >> 6), lane = tid & 63, wr = wid >> 2, wc = wid & 3, fr = lane & 15, fq = lane >> 4;
;     const int K = g.K, nt = K / BK;
; __global__ void __launch_bounds__(512, 2) mega(Params p_unused) {
;     ...
;         KParams kp = kparams(); unsigned char* ws = kp->ws;
;         pg8::StaticOrder S; S.init(MT, DM, (int)gridDim.x, (int)blockIdx.x);
;         pg8::Gemm gm{WSP(bf16_t, WS_Y), WSP(bf16_t, WS_WOUT), MT, DM, DM, DM, DM}; EpiOut E{kp->x, WSP(bf16_t, WS_X1B), WSP(float, WS_SS2)};
;         pg8::gemm_phase<EpiOut, pg8::StaticOrder>(wv, lds, gm, S, E);
.LBB0_646:
	s_or_b64 exec, exec, s[0:1]
	s_mov_b64 s[2:3], s[56:57]
	s_waitcnt lgkmcnt(0)
	s_barrier
	s_cmpk_lt_u32 s53, 0x100
	s_cbranch_scc1 .Lgprio_out
	s_setprio 1
.Lgprio_out:
	v_mbcnt_lo_u32_b32 v0, -1, 0
	v_mbcnt_hi_u32_b32 v0, -1, v0
	s_and_b64 vcc, exec, s[64:65]
	v_add_u32_e32 v8, s53, v0
	s_nop 0
	v_readfirstlane_b32 s28, v8
	s_cbranch_vccnz .LBB0_666
	s_load_dwordx2 s[0:1], s[2:3], 0x70
	s_and_b64 vcc, exec, s[62:63]
	s_cbranch_vccz .LBB0_649
	s_lshl_b32 s6, s60, 6
	s_cbranch_execz .LBB0_650
	s_branch .LBB0_651

; #define PG8_STAGE(bufoff, gbase, voff) do { _Pragma("unroll") for (int _i = 0; _i < 2; ++_i) \
;         __builtin_amdgcn_global_load_lds((const unsigned*)((const char*)(gbase) + (voff)[_i]), (LAS unsigned*)(lds + (bufoff) + ldsw + _i * 8192), 16, 0, 0); } while (0)
; #define PG8_LDA(dst, b, h) do { _Pragma("unroll") for (int m = 0; m < 4; ++m) _Pragma("unroll") for (int k = 0; k < 2; ++k) dst[m][k] = *(const LAS bf16x8*)(lds + PG8_SA(b, h) + aoff + m * 2048 + k * 1024); } while (0)
; #define PG8_LDB(dst, b, h) do { _Pragma("unroll") for (int n = 0; n < 2; ++n) _Pragma("unroll") for (int k = 0; k < 2; ++k) dst[n][k] = *(const LAS bf16x8*)(lds + PG8_SB(b, h) + boff + n * 2048 + k * 1024); } while (0)
; #define PG8_MMA(ai, bj, At, Bt) do { __builtin_amdgcn_s_setprio(1); _Pragma("unroll") for (int m = 0; m < 4; ++m) _Pragma("unroll") for (int n = 0; n < 2; ++n) _Pragma("unroll") for (int k = 0; k < 2; ++k) \
;         acc[ai][bj][m][n] = __builtin_amdgcn_mfma_f32_16x16x32_bf16(Bt[n][k], At[m][k], acc[ai][bj][m][n], 0, 0, 0); __builtin_amdgcn_s_setprio(0); } while (0)
; #define PG8_WAIT_L(n) asm volatile("s_waitcnt lgkmcnt(" #n ")" ::: "memory")
; #define PG8_BAR __builtin_amdgcn_s_barrier()
; #define PG8_SCHED __builtin_amdgcn_sched_barrier(0)
; template <class Epi, class Sched>
; __device__ __forceinline__ void gemm_phase(const int wv, LAS unsigned char* lds, const Gemm g, const Sched& S, const Epi& E) {
;     ...
;             PG8_LDB(B0, 0, 0); PG8_SCHED; PG8_LDA(At, 0, 0); PG8_STAGE(PG8_SA(1, 1), a1 + hstepA, voffA);
;             PG8_WAIT_L(8); PG8_BAR; PG8_WAIT_L(0); PG8_MMA(0, 0, At, B0); PG8_BAR; PG8_SCHED;
;             PG8_LDB(B1, 0, 1); PG8_STAGE(PG8_SB(0, 0), b2, voffB);
;             PG8_BAR; PG8_WAIT_L(0); PG8_MMA(0, 1, At, B1); PG8_BAR;
;             PG8_LDA(At, 0, 1); PG8_STAGE(PG8_SA(0, 0), a2, voffA);
;             PG8_BAR; PG8_WAIT_L(0); PG8_MMA(1, 0, At, B0); PG8_BAR; PG8_SCHED;
.LBB0_661:
	ds_read_b128 v[128:131], v177
	ds_read_b128 v[132:135], v177 offset:1024
	ds_read_b128 v[136:139], v177 offset:2048
	ds_read_b128 v[140:143], v177 offset:3072
	s_add_u32 s24, s22, 0xfffc0080
	s_addc_u32 s25, s23, -1
	s_cmp_eq_u32 s48, 12
	s_cselect_b32 s27, s15, s25
	s_cselect_b32 s26, s44, s24
	s_cselect_b32 s25, s13, s47
	s_cselect_b32 s24, s45, s46
	v_lshl_add_u64 v[202:203], s[22:23], 0, v[152:153]
	s_add_i32 m0, s35, 0xc000
	ds_read_b128 v[160:163], v180
	ds_read_b128 v[164:167], v180 offset:1024
	ds_read_b128 v[168:171], v180 offset:2048
	ds_read_b128 v[182:185], v180 offset:3072
	ds_read_b128 v[186:189], v180 offset:4096
	ds_read_b128 v[190:193], v180 offset:5120
	ds_read_b128 v[194:197], v180 offset:6144
	ds_read_b128 v[198:201], v180 offset:7168
	global_load_lds_dwordx4 v[202:203], off
	v_lshl_add_u64 v[202:203], s[22:23], 0, v[154:155]
	s_add_i32 m0, s35, 0xe000
	s_nop 0
	global_load_lds_dwordx4 v[202:203], off
	s_waitcnt lgkmcnt(8)
	s_barrier
	s_waitcnt lgkmcnt(0)
	s_waitcnt lgkmcnt(0)
	v_mfma_f32_16x16x32_bf16 v[124:127], v[128:131], v[160:163], v[124:127]
	v_mfma_f32_16x16x32_bf16 v[120:123], v[136:139], v[160:163], v[120:123]
	v_mfma_f32_16x16x32_bf16 v[116:119], v[128:131], v[168:171], v[116:119]
	v_mfma_f32_16x16x32_bf16 v[104:107], v[136:139], v[168:171], v[104:107]
	v_mfma_f32_16x16x32_bf16 v[92:95], v[128:131], v[186:189], v[92:95]
	v_mfma_f32_16x16x32_bf16 v[88:91], v[136:139], v[186:189], v[88:91]
	v_mfma_f32_16x16x32_bf16 v[76:79], v[128:131], v[194:197], v[76:79]
	v_mfma_f32_16x16x32_bf16 v[72:75], v[136:139], v[194:197], v[72:75]
	v_mfma_f32_16x16x32_bf16 v[124:127], v[132:135], v[164:167], v[124:127]
	v_mfma_f32_16x16x32_bf16 v[120:123], v[140:143], v[164:167], v[120:123]
	v_mfma_f32_16x16x32_bf16 v[116:119], v[132:135], v[182:185], v[116:119]
	v_mfma_f32_16x16x32_bf16 v[104:107], v[140:143], v[182:185], v[104:107]
	v_mfma_f32_16x16x32_bf16 v[92:95], v[132:135], v[190:193], v[92:95]
	v_mfma_f32_16x16x32_bf16 v[88:91], v[140:143], v[190:193], v[88:91]
	v_mfma_f32_16x16x32_bf16 v[76:79], v[132:135], v[198:201], v[76:79]
	v_mfma_f32_16x16x32_bf16 v[72:75], v[140:143], v[198:201], v[72:75]
	s_barrier
	s_add_i32 s49, s41, s34
	v_lshl_add_u64 v[218:219], s[24:25], 0, v[146:147]
	s_mov_b32 m0, s49
	ds_read_b128 v[202:205], v181
	ds_read_b128 v[206:209], v181 offset:1024
	ds_read_b128 v[210:213], v181 offset:2048
	ds_read_b128 v[214:217], v181 offset:3072
	global_load_lds_dwordx4 v[218:219], off
	v_lshl_add_u64 v[220:221], s[24:25], 0, v[150:151]
	s_add_i32 m0, s49, 0x2000
	s_nop 0
	global_load_lds_dwordx4 v[220:221], off
	s_barrier
	s_waitcnt lgkmcnt(0)
	s_waitcnt lgkmcnt(0)
	v_mfma_f32_16x16x32_bf16 v[112:115], v[202:205], v[160:163], v[112:115]
	v_mfma_f32_16x16x32_bf16 v[108:111], v[210:213], v[160:163], v[108:111]
	v_mfma_f32_16x16x32_bf16 v[100:103], v[202:205], v[168:171], v[100:103]
	v_mfma_f32_16x16x32_bf16 v[96:99], v[210:213], v[168:171], v[96:99]
	v_mfma_f32_16x16x32_bf16 v[84:87], v[202:205], v[186:189], v[84:87]
	v_mfma_f32_16x16x32_bf16 v[80:83], v[210:213], v[186:189], v[80:83]
	v_mfma_f32_16x16x32_bf16 v[68:71], v[202:205], v[194:197], v[68:71]
	v_mfma_f32_16x16x32_bf16 v[64:67], v[210:213], v[194:197], v[64:67]
	v_mfma_f32_16x16x32_bf16 v[112:115], v[206:209], v[164:167], v[112:115]
	v_mfma_f32_16x16x32_bf16 v[108:111], v[214:217], v[164:167], v[108:111]
	v_mfma_f32_16x16x32_bf16 v[100:103], v[206:209], v[182:185], v[100:103]
	v_mfma_f32_16x16x32_bf16 v[96:99], v[214:217], v[182:185], v[96:99]
	v_mfma_f32_16x16x32_bf16 v[84:87], v[206:209], v[190:193], v[84:87]
	v_mfma_f32_16x16x32_bf16 v[80:83], v[214:217], v[190:193], v[80:83]
	v_mfma_f32_16x16x32_bf16 v[68:71], v[206:209], v[198:201], v[68:71]
	v_mfma_f32_16x16x32_bf16 v[64:67], v[214:217], v[198:201], v[64:67]
	s_mov_b32 m0, s35
	v_lshl_add_u64 v[222:223], s[26:27], 0, v[144:145]
	s_barrier
	ds_read_b128 v[160:163], v180 offset:16384
	ds_read_b128 v[164:167], v180 offset:17408
	ds_read_b128 v[168:171], v180 offset:18432
	ds_read_b128 v[182:185], v180 offset:19456
	ds_read_b128 v[186:189], v180 offset:20480
	ds_read_b128 v[190:193], v180 offset:21504
	ds_read_b128 v[194:197], v180 offset:22528
	ds_read_b128 v[198:201], v180 offset:23552
	global_load_lds_dwordx4 v[222:223], off
	v_lshl_add_u64 v[224:225], s[26:27], 0, v[148:149]
	s_mov_b32 m0, s36
	s_nop 0
	global_load_lds_dwordx4 v[224:225], off
	s_barrier
	s_waitcnt lgkmcnt(0)
	s_waitcnt lgkmcnt(0)
	v_mfma_f32_16x16x32_bf16 v[60:63], v[128:131], v[160:163], v[60:63]
	v_mfma_f32_16x16x32_bf16 v[56:59], v[136:139], v[160:163], v[56:59]
	v_mfma_f32_16x16x32_bf16 v[44:47], v[128:131], v[168:171], v[44:47]
	v_mfma_f32_16x16x32_bf16 v[40:43], v[136:139], v[168:171], v[40:43]
	v_mfma_f32_16x16x32_bf16 v[28:31], v[128:131], v[186:189], v[28:31]
	v_mfma_f32_16x16x32_bf16 v[24:27], v[136:139], v[186:189], v[24:27]
	v_mfma_f32_16x16x32_bf16 v[12:15], v[128:131], v[194:197], v[12:15]
	v_mfma_f32_16x16x32_bf16 v[8:11], v[136:139], v[194:197], v[8:11]
	v_mfma_f32_16x16x32_bf16 v[60:63], v[132:135], v[164:167], v[60:63]
	v_mfma_f32_16x16x32_bf16 v[56:59], v[140:143], v[164:167], v[56:59]
	v_mfma_f32_16x16x32_bf16 v[44:47], v[132:135], v[182:185], v[44:47]
	v_mfma_f32_16x16x32_bf16 v[40:43], v[140:143], v[182:185], v[40:43]
	v_mfma_f32_16x16x32_bf16 v[28:31], v[132:135], v[190:193], v[28:31]
	v_mfma_f32_16x16x32_bf16 v[24:27], v[140:143], v[190:193], v[24:27]
	v_mfma_f32_16x16x32_bf16 v[12:15], v[132:135], v[198:201], v[12:15]
	v_mfma_f32_16x16x32_bf16 v[8:11], v[140:143], v[198:201], v[8:11]
	s_barrier
; #define PG8_STAGE(bufoff, gbase, voff) do { _Pragma("unroll") for (int _i = 0; _i < 2; ++_i) \
;         __builtin_amdgcn_global_load_lds((const unsigned*)((const char*)(gbase) + (voff)[_i]), (LAS unsigned*)(lds + (bufoff) + ldsw + _i * 8192), 16, 0, 0); } while (0)
; #define PG8_LDA(dst, b, h) do { _Pragma("unroll") for (int m = 0; m < 4; ++m) _Pragma("unroll") for (int k = 0; k < 2; ++k) dst[m][k] = *(const LAS bf16x8*)(lds + PG8_SA(b, h) + aoff + m * 2048 + k * 1024); } while (0)
; #define PG8_LDB(dst, b, h) do { _Pragma("unroll") for (int n = 0; n < 2; ++n) _Pragma("unroll") for (int k = 0; k < 2; ++k) dst[n][k] = *(const LAS bf16x8*)(lds + PG8_SB(b, h) + boff + n * 2048 + k * 1024); } while (0)
; #define PG8_MMA(ai, bj, At, Bt) do { __builtin_amdgcn_s_setprio(1); _Pragma("unroll") for (int m = 0; m < 4; ++m) _Pragma("unroll") for (int n = 0; n < 2; ++n) _Pragma("unroll") for (int k = 0; k < 2; ++k) \
;         acc[ai][bj][m][n] = __builtin_amdgcn_mfma_f32_16x16x32_bf16(Bt[n][k], At[m][k], acc[ai][bj][m][n], 0, 0, 0); __builtin_amdgcn_s_setprio(0); } while (0)
; #define PG8_WAIT_V(n) asm volatile("s_waitcnt vmcnt(" #n ")" ::: "memory")
; #define PG8_WAIT_L(n) asm volatile("s_waitcnt lgkmcnt(" #n ")" ::: "memory")
; #define PG8_BAR __builtin_amdgcn_s_barrier()
; #define PG8_SCHED __builtin_amdgcn_sched_barrier(0)
; template <class Epi, class Sched>
; __device__ __forceinline__ void gemm_phase(const int wv, LAS unsigned char* lds, const Gemm g, const Sched& S, const Epi& E) {
;     ...
;             PG8_BAR; PG8_WAIT_L(0); PG8_MMA(1, 0, At, B0); PG8_BAR; PG8_SCHED;
;             PG8_STAGE(PG8_SB(0, 1), b2 + hstepB, voffB);
;             PG8_WAIT_V(6); PG8_BAR; PG8_MMA(1, 1, At, B1); PG8_BAR;
;             PG8_LDB(B0, 1, 0); PG8_SCHED; PG8_LDA(At, 1, 0); PG8_STAGE(PG8_SA(0, 1), a2 + hstepA, voffA);
;             PG8_WAIT_L(8); PG8_BAR; PG8_WAIT_L(0); PG8_MMA(0, 0, At, B0); PG8_BAR; PG8_SCHED;
;             PG8_LDB(B1, 1, 1); PG8_STAGE(PG8_SB(1, 0), b3, voffB);
;             PG8_BAR; PG8_WAIT_L(0); PG8_MMA(0, 1, At, B1); PG8_BAR;
;             PG8_LDA(At, 1, 1); PG8_STAGE(PG8_SA(1, 0), a3, voffA);
	s_add_u32 s50, s24, 0x40000
	s_addc_u32 s51, s25, 0
	s_add_i32 s49, s42, s34
	v_lshl_add_u64 v[128:129], s[50:51], 0, v[146:147]
	s_mov_b32 m0, s49
	s_nop 0
	global_load_lds_dwordx4 v[128:129], off
	v_lshl_add_u64 v[128:129], s[50:51], 0, v[150:151]
	s_add_i32 m0, s49, 0x2000
	s_nop 0
	global_load_lds_dwordx4 v[128:129], off
	s_waitcnt vmcnt(6)
	s_barrier
	v_mfma_f32_16x16x32_bf16 v[52:55], v[202:205], v[160:163], v[52:55]
	v_mfma_f32_16x16x32_bf16 v[48:51], v[210:213], v[160:163], v[48:51]
	v_mfma_f32_16x16x32_bf16 v[36:39], v[202:205], v[168:171], v[36:39]
	v_mfma_f32_16x16x32_bf16 v[32:35], v[210:213], v[168:171], v[32:35]
	v_mfma_f32_16x16x32_bf16 v[20:23], v[202:205], v[186:189], v[20:23]
	v_mfma_f32_16x16x32_bf16 v[16:19], v[210:213], v[186:189], v[16:19]
	v_mfma_f32_16x16x32_bf16 v[4:7], v[202:205], v[194:197], v[4:7]
	v_mfma_f32_16x16x32_bf16 v[0:3], v[210:213], v[194:197], v[0:3]
	v_mfma_f32_16x16x32_bf16 v[52:55], v[206:209], v[164:167], v[52:55]
	v_mfma_f32_16x16x32_bf16 v[48:51], v[214:217], v[164:167], v[48:51]
	v_mfma_f32_16x16x32_bf16 v[36:39], v[206:209], v[182:185], v[36:39]
	v_mfma_f32_16x16x32_bf16 v[32:35], v[214:217], v[182:185], v[32:35]
	v_mfma_f32_16x16x32_bf16 v[20:23], v[206:209], v[190:193], v[20:23]
	v_mfma_f32_16x16x32_bf16 v[16:19], v[214:217], v[190:193], v[16:19]
	v_mfma_f32_16x16x32_bf16 v[4:7], v[206:209], v[198:201], v[4:7]
	v_mfma_f32_16x16x32_bf16 v[0:3], v[214:217], v[198:201], v[0:3]
	s_add_i32 s49, 0, 0x18000
	v_add_u32_e32 v140, s49, v173
	s_barrier
	ds_read_b128 v[128:131], v140
	ds_read_b128 v[132:135], v140 offset:1024
	ds_read_b128 v[136:139], v140 offset:2048
	ds_read_b128 v[140:143], v140 offset:3072
	s_add_u32 s26, s26, 0x40000
	s_addc_u32 s27, s27, 0
	s_mov_b32 m0, s37
	v_lshl_add_u64 v[202:203], s[26:27], 0, v[144:145]
	ds_read_b128 v[160:163], v180 offset:32768
	ds_read_b128 v[164:167], v180 offset:33792
	ds_read_b128 v[168:171], v180 offset:34816
	ds_read_b128 v[182:185], v180 offset:35840
	ds_read_b128 v[186:189], v180 offset:36864
	ds_read_b128 v[190:193], v180 offset:37888
	ds_read_b128 v[194:197], v180 offset:38912
	ds_read_b128 v[198:201], v180 offset:39936
	global_load_lds_dwordx4 v[202:203], off
	v_lshl_add_u64 v[202:203], s[26:27], 0, v[148:149]
	s_mov_b32 m0, s38
	s_nop 0
	global_load_lds_dwordx4 v[202:203], off
	s_waitcnt lgkmcnt(8)
	s_barrier
	s_waitcnt lgkmcnt(0)
	s_waitcnt lgkmcnt(0)
	v_mfma_f32_16x16x32_bf16 v[124:127], v[128:131], v[160:163], v[124:127]
	v_mfma_f32_16x16x32_bf16 v[120:123], v[136:139], v[160:163], v[120:123]
	v_mfma_f32_16x16x32_bf16 v[116:119], v[128:131], v[168:171], v[116:119]
	v_mfma_f32_16x16x32_bf16 v[104:107], v[136:139], v[168:171], v[104:107]
	v_mfma_f32_16x16x32_bf16 v[92:95], v[128:131], v[186:189], v[92:95]
	v_mfma_f32_16x16x32_bf16 v[88:91], v[136:139], v[186:189], v[88:91]
	v_mfma_f32_16x16x32_bf16 v[76:79], v[128:131], v[194:197], v[76:79]
	v_mfma_f32_16x16x32_bf16 v[72:75], v[136:139], v[194:197], v[72:75]
	v_mfma_f32_16x16x32_bf16 v[124:127], v[132:135], v[164:167], v[124:127]
	v_mfma_f32_16x16x32_bf16 v[120:123], v[140:143], v[164:167], v[120:123]
	v_mfma_f32_16x16x32_bf16 v[116:119], v[132:135], v[182:185], v[116:119]
	v_mfma_f32_16x16x32_bf16 v[104:107], v[140:143], v[182:185], v[104:107]
	v_mfma_f32_16x16x32_bf16 v[92:95], v[132:135], v[190:193], v[92:95]
	v_mfma_f32_16x16x32_bf16 v[88:91], v[140:143], v[190:193], v[88:91]
	v_mfma_f32_16x16x32_bf16 v[76:79], v[132:135], v[198:201], v[76:79]
	v_mfma_f32_16x16x32_bf16 v[72:75], v[140:143], v[198:201], v[72:75]
	s_barrier
	s_add_i32 s26, 0, 0x1c000
	s_add_i32 s27, s49, s34
	v_add_u32_e32 v214, s26, v173
	v_lshl_add_u64 v[218:219], v[218:219], 0, s[10:11]
	s_mov_b32 m0, s27
	ds_read_b128 v[202:205], v214
	ds_read_b128 v[206:209], v214 offset:1024
	ds_read_b128 v[210:213], v214 offset:2048
	ds_read_b128 v[214:217], v214 offset:3072
	global_load_lds_dwordx4 v[218:219], off
	v_lshl_add_u64 v[218:219], v[220:221], 0, s[10:11]
	s_add_i32 m0, s27, 0x2000
	s_nop 0
	global_load_lds_dwordx4 v[218:219], off
	s_barrier
	s_waitcnt lgkmcnt(0)
	s_waitcnt lgkmcnt(0)
	v_mfma_f32_16x16x32_bf16 v[112:115], v[202:205], v[160:163], v[112:115]
	v_mfma_f32_16x16x32_bf16 v[108:111], v[210:213], v[160:163], v[108:111]
	v_mfma_f32_16x16x32_bf16 v[100:103], v[202:205], v[168:171], v[100:103]
	v_mfma_f32_16x16x32_bf16 v[96:99], v[210:213], v[168:171], v[96:99]
	v_mfma_f32_16x16x32_bf16 v[84:87], v[202:205], v[186:189], v[84:87]
	v_mfma_f32_16x16x32_bf16 v[80:83], v[210:213], v[186:189], v[80:83]
	v_mfma_f32_16x16x32_bf16 v[68:71], v[202:205], v[194:197], v[68:71]
	v_mfma_f32_16x16x32_bf16 v[64:67], v[210:213], v[194:197], v[64:67]
	v_mfma_f32_16x16x32_bf16 v[112:115], v[206:209], v[164:167], v[112:115]
	v_mfma_f32_16x16x32_bf16 v[108:111], v[214:217], v[164:167], v[108:111]
	v_mfma_f32_16x16x32_bf16 v[100:103], v[206:209], v[182:185], v[100:103]
	v_mfma_f32_16x16x32_bf16 v[96:99], v[214:217], v[182:185], v[96:99]
	v_mfma_f32_16x16x32_bf16 v[84:87], v[206:209], v[190:193], v[84:87]
	v_mfma_f32_16x16x32_bf16 v[80:83], v[214:217], v[190:193], v[80:83]
	v_mfma_f32_16x16x32_bf16 v[68:71], v[206:209], v[198:201], v[68:71]
	v_mfma_f32_16x16x32_bf16 v[64:67], v[214:217], v[198:201], v[64:67]
	s_mov_b32 m0, s39
	v_lshl_add_u64 v[218:219], v[222:223], 0, s[10:11]
	s_barrier
	ds_read_b128 v[160:163], v180 offset:49152
	ds_read_b128 v[164:167], v180 offset:50176
	ds_read_b128 v[168:171], v180 offset:51200
	ds_read_b128 v[182:185], v180 offset:52224
	ds_read_b128 v[186:189], v180 offset:53248
	ds_read_b128 v[190:193], v180 offset:54272
	ds_read_b128 v[194:197], v180 offset:55296
	ds_read_b128 v[198:201], v180 offset:56320
	global_load_lds_dwordx4 v[218:219], off
	v_lshl_add_u64 v[218:219], v[224:225], 0, s[10:11]
	s_mov_b32 m0, s40
	s_nop 0
	global_load_lds_dwordx4 v[218:219], off
	s_barrier
; #define PG8_STAGE(bufoff, gbase, voff) do { _Pragma("unroll") for (int _i = 0; _i < 2; ++_i) \
;         __builtin_amdgcn_global_load_lds((const unsigned*)((const char*)(gbase) + (voff)[_i]), (LAS unsigned*)(lds + (bufoff) + ldsw + _i * 8192), 16, 0, 0); } while (0)
; #define PG8_LDA(dst, b, h) do { _Pragma("unroll") for (int m = 0; m < 4; ++m) _Pragma("unroll") for (int k = 0; k < 2; ++k) dst[m][k] = *(const LAS bf16x8*)(lds + PG8_SA(b, h) + aoff + m * 2048 + k * 1024); } while (0)
; #define PG8_MMA(ai, bj, At, Bt) do { __builtin_amdgcn_s_setprio(1); _Pragma("unroll") for (int m = 0; m < 4; ++m) _Pragma("unroll") for (int n = 0; n < 2; ++n) _Pragma("unroll") for (int k = 0; k < 2; ++k) \
;         acc[ai][bj][m][n] = __builtin_amdgcn_mfma_f32_16x16x32_bf16(Bt[n][k], At[m][k], acc[ai][bj][m][n], 0, 0, 0); __builtin_amdgcn_s_setprio(0); } while (0)
; #define PG8_WAIT_V(n) asm volatile("s_waitcnt vmcnt(" #n ")" ::: "memory")
; #define PG8_WAIT_L(n) asm volatile("s_waitcnt lgkmcnt(" #n ")" ::: "memory")
; #define PG8_BAR __builtin_amdgcn_s_barrier()
; #define PG8_SCHED __builtin_amdgcn_sched_barrier(0)
; template <class Epi, class Sched>
; __device__ __forceinline__ void gemm_phase(const int wv, LAS unsigned char* lds, const Gemm g, const Sched& S, const Epi& E) {
;     ...
;             PG8_LDA(At, 1, 1); PG8_STAGE(PG8_SA(1, 0), a3, voffA);
;             PG8_BAR; PG8_WAIT_L(0); PG8_MMA(1, 0, At, B0); PG8_BAR; PG8_SCHED;
;             PG8_STAGE(PG8_SB(1, 1), b3 + hstepB, voffB);
;             PG8_WAIT_V(6); PG8_BAR; PG8_MMA(1, 1, At, B1); PG8_BAR;
;         }
;     __device__ __forceinline__ void operator()(const f32x4 (&acc)[2][2][4][2], const Unit& u, int wr, int wc, int fr, int fq) const {
;         const int row0 = u.pm * 256 + wr * 64 + fr; const int col0 = u.pn * 256 + wc * 32 + 8 * fq;
; #pragma unroll
;         for (int ai = 0; ai < 2; ++ai) {
;             f32x4 xv[4][2][2];
; #pragma unroll
;             for (int m = 0; m < 4; ++m)
; #pragma unroll
;                 for (int bj = 0; bj < 2; ++bj) {
;                     const size_t o = (size_t)(row0 + ai * 128 + m * 16) * 1024 + col0 + bj * 128;
;                     xv[m][bj][0] = *(const f32x4*)(x + o); xv[m][bj][1] = *(const f32x4*)(x + o + 4);
;                 }
	s_waitcnt lgkmcnt(0)
	s_waitcnt lgkmcnt(0)
	v_mfma_f32_16x16x32_bf16 v[60:63], v[128:131], v[160:163], v[60:63]
	v_mfma_f32_16x16x32_bf16 v[56:59], v[136:139], v[160:163], v[56:59]
	v_mfma_f32_16x16x32_bf16 v[44:47], v[128:131], v[168:171], v[44:47]
	v_mfma_f32_16x16x32_bf16 v[40:43], v[136:139], v[168:171], v[40:43]
	v_mfma_f32_16x16x32_bf16 v[28:31], v[128:131], v[186:189], v[28:31]
	v_mfma_f32_16x16x32_bf16 v[24:27], v[136:139], v[186:189], v[24:27]
	v_mfma_f32_16x16x32_bf16 v[12:15], v[128:131], v[194:197], v[12:15]
	v_mfma_f32_16x16x32_bf16 v[8:11], v[136:139], v[194:197], v[8:11]
	v_mfma_f32_16x16x32_bf16 v[60:63], v[132:135], v[164:167], v[60:63]
	v_mfma_f32_16x16x32_bf16 v[56:59], v[140:143], v[164:167], v[56:59]
	v_mfma_f32_16x16x32_bf16 v[44:47], v[132:135], v[182:185], v[44:47]
	v_mfma_f32_16x16x32_bf16 v[40:43], v[140:143], v[182:185], v[40:43]
	v_mfma_f32_16x16x32_bf16 v[28:31], v[132:135], v[190:193], v[28:31]
	v_mfma_f32_16x16x32_bf16 v[24:27], v[140:143], v[190:193], v[24:27]
	v_mfma_f32_16x16x32_bf16 v[12:15], v[132:135], v[198:201], v[12:15]
	v_mfma_f32_16x16x32_bf16 v[8:11], v[140:143], v[198:201], v[8:11]
	s_barrier
	s_add_u32 s24, s24, 0x40080
	s_addc_u32 s25, s25, 0
	s_add_i32 s26, s26, s34
	v_lshl_add_u64 v[128:129], s[24:25], 0, v[146:147]
	s_mov_b32 m0, s26
	s_nop 0
	global_load_lds_dwordx4 v[128:129], off
	v_lshl_add_u64 v[128:129], s[24:25], 0, v[150:151]
	s_add_i32 m0, s26, 0x2000
	s_nop 0
	global_load_lds_dwordx4 v[128:129], off
	s_waitcnt vmcnt(6)
	s_barrier
	v_mfma_f32_16x16x32_bf16 v[52:55], v[202:205], v[160:163], v[52:55]
	v_mfma_f32_16x16x32_bf16 v[48:51], v[210:213], v[160:163], v[48:51]
	v_mfma_f32_16x16x32_bf16 v[36:39], v[202:205], v[168:171], v[36:39]
	v_mfma_f32_16x16x32_bf16 v[32:35], v[210:213], v[168:171], v[32:35]
	v_mfma_f32_16x16x32_bf16 v[20:23], v[202:205], v[186:189], v[20:23]
	v_mfma_f32_16x16x32_bf16 v[16:19], v[210:213], v[186:189], v[16:19]
	v_mfma_f32_16x16x32_bf16 v[4:7], v[202:205], v[194:197], v[4:7]
	v_mfma_f32_16x16x32_bf16 v[0:3], v[210:213], v[194:197], v[0:3]
	v_mfma_f32_16x16x32_bf16 v[52:55], v[206:209], v[164:167], v[52:55]
	v_mfma_f32_16x16x32_bf16 v[48:51], v[214:217], v[164:167], v[48:51]
	v_mfma_f32_16x16x32_bf16 v[36:39], v[206:209], v[182:185], v[36:39]
	v_mfma_f32_16x16x32_bf16 v[32:35], v[214:217], v[182:185], v[32:35]
	v_mfma_f32_16x16x32_bf16 v[20:23], v[206:209], v[190:193], v[20:23]
	v_mfma_f32_16x16x32_bf16 v[16:19], v[214:217], v[190:193], v[16:19]
	v_mfma_f32_16x16x32_bf16 v[4:7], v[206:209], v[198:201], v[4:7]
	v_mfma_f32_16x16x32_bf16 v[0:3], v[214:217], v[198:201], v[0:3]
	s_add_i32 s48, s48, 2
	s_add_u32 s22, s22, 0x100
	s_addc_u32 s23, s23, 0
	s_add_u32 s46, s46, 0x100
	s_addc_u32 s47, s47, 0
	s_cmp_gt_u32 s48, 13
	s_barrier
	s_cbranch_scc0 .LBB0_661
	v_lshl_add_u32 v162, s20, 8, v172
	v_lshl_or_b32 v128, s21, 8, v174
	v_ashrrev_i32_e32 v129, 31, v128
	v_ashrrev_i32_e32 v163, 31, v162
	v_lshl_add_u64 v[164:165], v[128:129], 2, s[2:3]
	v_lshlrev_b64 v[130:131], 12, v[162:163]
	v_lshl_add_u64 v[130:131], v[164:165], 0, v[130:131]
	global_load_dwordx4 v[182:185], v[130:131], off
	global_load_dwordx4 v[186:189], v[130:131], off offset:16
	global_load_dwordx4 v[190:193], v[130:131], off offset:512
	global_load_dwordx4 v[194:197], v[130:131], off offset:528
	v_or_b32_e32 v170, 16, v162
	v_ashrrev_i32_e32 v171, 31, v170
	v_lshlrev_b64 v[130:131], 12, v[170:171]
	v_lshl_add_u64 v[130:131], v[164:165], 0, v[130:131]
	global_load_dwordx4 v[198:201], v[130:131], off
	global_load_dwordx4 v[202:205], v[130:131], off offset:16
	global_load_dwordx4 v[206:209], v[130:131], off offset:528
	global_load_dwordx4 v[210:213], v[130:131], off offset:512
	v_or_b32_e32 v168, 32, v162
	v_or_b32_e32 v166, 48, v162
	s_lshl_b32 s20, s21, 2
	v_ashrrev_i32_e32 v169, 31, v168
	v_ashrrev_i32_e32 v167, 31, v166
	s_ashr_i32 s21, s20, 31
	v_lshlrev_b64 v[132:133], 11, v[162:163]
	v_lshlrev_b64 v[160:161], 1, v[128:129]
	v_lshlrev_b64 v[128:129], 6, v[162:163]
	v_lshlrev_b64 v[134:135], 12, v[168:169]
	v_lshlrev_b64 v[136:137], 12, v[166:167]
	s_lshl_b64 s[20:21], s[20:21], 2
	v_lshl_add_u64 v[132:133], s[6:7], 0, v[132:133]
	v_lshl_add_u64 v[128:129], s[8:9], 0, v[128:129]
	v_lshl_add_u64 v[130:131], v[164:165], 0, v[134:135]
	v_lshl_add_u64 v[134:135], v[164:165], 0, v[136:137]
	v_lshl_add_u64 v[232:233], v[132:133], 0, v[160:161]
	v_lshl_add_u64 v[234:235], v[128:129], 0, s[20:21]
	global_load_dwordx4 v[214:217], v[130:131], off offset:16
	global_load_dwordx4 v[218:221], v[130:131], off
	global_load_dwordx4 v[222:225], v[130:131], off offset:528
	global_load_dwordx4 v[226:229], v[130:131], off offset:512
	global_load_dwordx4 v[136:139], v[134:135], off offset:16
	global_load_dwordx4 v[140:143], v[134:135], off
	s_nop 0
	global_load_dwordx4 v[128:131], v[134:135], off offset:528
	s_nop 0
	global_load_dwordx4 v[132:135], v[134:135], off offset:512
	v_lshl_add_u64 v[234:235], v[234:235], 0, s[4:5]
	v_lshlrev_b64 v[230:231], 11, v[170:171]
	s_and_b64 vcc, exec, s[0:1]
	s_mov_b64 s[24:25], s[18:19]
	s_mov_b64 s[22:23], s[16:17]
	s_waitcnt vmcnt(0)
; __device__ __forceinline__ float shx(float v, int lane, int mask) { return __int_as_float(__builtin_amdgcn_ds_bpermute((lane ^ mask) << 2, __float_as_int(v))); }
; __device__ __forceinline__ unsigned cvt_pk_bf16(float lo, float hi) { unsigned r; asm volatile("v_cvt_pk_bf16_f32 %0, %1, %2" : "=v"(r) : "v"(lo), "v"(hi)); return r; }
;     __device__ __forceinline__ void operator()(const f32x4 (&acc)[2][2][4][2], const Unit& u, int wr, int wc, int fr, int fq) const {
;     ...
; #pragma unroll
;             for (int m = 0; m < 4; ++m) {
;                 const int row = row0 + ai * 128 + m * 16; float ss = 0.f;
; #pragma unroll
;                 for (int bj = 0; bj < 2; ++bj) {
;                     const size_t o = (size_t)row * 1024 + col0 + bj * 128;
;                     const f32x4 v0 = xv[m][bj][0] + acc[ai][bj][m][0], v1 = xv[m][bj][1] + acc[ai][bj][m][1];
;                     ss += (v0[0] * v0[0] + v0[1] * v0[1]) + (v0[2] * v0[2] + v0[3] * v0[3]) + (v1[0] * v1[0] + v1[1] * v1[1]) + (v1[2] * v1[2] + v1[3] * v1[3]);
;                     u32x4 w; w.x = cvt_pk_bf16(v0[0], v0[1]); w.y = cvt_pk_bf16(v0[2], v0[3]); w.z = cvt_pk_bf16(v1[0], v1[1]); w.w = cvt_pk_bf16(v1[2], v1[3]);
;                     *(u32x4*)(x1b + o) = w;
;                 }
;                 ss += shx(ss, fq * 16 + fr, 16); ss += shx(ss, fq * 16 + fr, 32);
;                 ss2[(size_t)row * 16 + u.pn * 4 + wc] = ss;
;             }
	v_pk_add_f32 v[126:127], v[126:127], v[184:185]
	v_pk_add_f32 v[124:125], v[124:125], v[182:183]
	v_pk_add_f32 v[122:123], v[122:123], v[188:189]
	v_pk_add_f32 v[120:121], v[120:121], v[186:187]
	v_pk_add_f32 v[114:115], v[114:115], v[192:193]
	v_pk_add_f32 v[112:113], v[112:113], v[190:191]
	v_pk_add_f32 v[182:183], v[110:111], v[196:197]
	v_pk_add_f32 v[184:185], v[108:109], v[194:195]
	v_mul_f32_e32 v163, v125, v125
	v_mul_f32_e32 v190, v127, v127
	v_mul_f32_e32 v191, v121, v121
	v_mul_f32_e32 v192, v123, v123
	v_cvt_pk_bf16_f32 v108, v124, v125
	v_cvt_pk_bf16_f32 v109, v126, v127
	v_cvt_pk_bf16_f32 v110, v120, v121
	v_cvt_pk_bf16_f32 v111, v122, v123
	v_mul_f32_e32 v121, v113, v113
	v_mul_f32_e32 v123, v115, v115
	v_mul_f32_e32 v125, v185, v185
	v_fmac_f32_e32 v163, v124, v124
	v_fmac_f32_e32 v190, v126, v126
	v_fmac_f32_e32 v121, v112, v112
	v_fmac_f32_e32 v123, v114, v114
	v_mul_f32_e32 v127, v183, v183
	v_fmac_f32_e32 v191, v120, v120
	global_store_dwordx4 v[232:233], v[108:111], off
	v_fmac_f32_e32 v125, v184, v184
	v_fmac_f32_e32 v192, v122, v122
	v_add_f32_e32 v108, v163, v190
	v_add_f32_e32 v109, v121, v123
	v_fmac_f32_e32 v127, v182, v182
	v_add_f32_e32 v108, v108, v191
	v_add_f32_e32 v109, v109, v125
	v_add_f32_e32 v108, v192, v108
	v_add_f32_e32 v109, v127, v109
	v_add_f32_e32 v108, v108, v109
	ds_bpermute_b32 v109, v175, v108
	v_pk_add_f32 v[188:189], v[104:105], v[202:203]
	v_cvt_pk_bf16_f32 v104, v112, v113
	v_pk_add_f32 v[186:187], v[106:107], v[204:205]
	v_cvt_pk_bf16_f32 v105, v114, v115
	v_cvt_pk_bf16_f32 v106, v184, v185
	v_cvt_pk_bf16_f32 v107, v182, v183
	global_store_dwordx4 v[232:233], v[104:107], off offset:256
	v_pk_add_f32 v[102:103], v[102:103], v[212:213]
	v_pk_add_f32 v[100:101], v[100:101], v[210:211]
	s_waitcnt lgkmcnt(0)
	v_add_f32_e32 v104, v108, v109
	ds_bpermute_b32 v105, v176, v104
	v_pk_add_f32 v[108:109], v[98:99], v[208:209]
	v_pk_add_f32 v[98:99], v[96:97], v[206:207]
	v_mul_f32_e32 v96, v101, v101
	v_mul_f32_e32 v97, v103, v103
	v_pk_add_f32 v[118:119], v[118:119], v[200:201]
	v_pk_add_f32 v[116:117], v[116:117], v[198:199]
	v_fmac_f32_e32 v96, v100, v100
	v_fmac_f32_e32 v97, v102, v102
	v_mul_f32_e32 v110, v117, v117
	v_mul_f32_e32 v111, v119, v119
	v_add_f32_e32 v96, v96, v97
	v_mul_f32_e32 v97, v99, v99
	v_mul_f32_e32 v112, v189, v189
	v_fmac_f32_e32 v110, v116, v116
	v_fmac_f32_e32 v111, v118, v118
	v_fmac_f32_e32 v97, v98, v98
	v_fmac_f32_e32 v112, v188, v188
	v_add_f32_e32 v106, v110, v111
	s_waitcnt lgkmcnt(0)
	v_add_f32_e32 v104, v104, v105
	v_mul_f32_e32 v105, v187, v187
	v_add_f32_e32 v96, v96, v97
	v_mul_f32_e32 v97, v109, v109
	global_store_dword v[234:235], v104, off
	v_add_f32_e32 v104, v106, v112
	v_fmac_f32_e32 v105, v186, v186
	v_fmac_f32_e32 v97, v108, v108
	v_add_f32_e32 v110, v105, v104
	v_add_f32_e32 v96, v97, v96
	v_add_f32_e32 v112, v110, v96
	ds_bpermute_b32 v113, v175, v112
	v_lshl_add_u64 v[96:97], s[6:7], 0, v[230:231]
	v_lshl_add_u64 v[110:111], v[96:97], 0, v[160:161]
	v_cvt_pk_bf16_f32 v104, v116, v117
	v_cvt_pk_bf16_f32 v105, v118, v119
	v_cvt_pk_bf16_f32 v106, v188, v189
	v_cvt_pk_bf16_f32 v107, v186, v187
	global_store_dwordx4 v[110:111], v[104:107], off
	v_cvt_pk_bf16_f32 v96, v100, v101
	s_waitcnt lgkmcnt(0)
	v_add_f32_e32 v100, v112, v113
	ds_bpermute_b32 v101, v176, v100
	v_cvt_pk_bf16_f32 v97, v102, v103
	v_cvt_pk_bf16_f32 v98, v98, v99
	v_cvt_pk_bf16_f32 v99, v108, v109
	global_store_dwordx4 v[110:111], v[96:99], off offset:256
	v_pk_add_f32 v[94:95], v[94:95], v[220:221]
	v_pk_add_f32 v[92:93], v[92:93], v[218:219]
	v_lshlrev_b64 v[96:97], 6, v[170:171]
	v_lshl_add_u64 v[96:97], s[8:9], 0, v[96:97]
	v_lshl_add_u64 v[96:97], v[96:97], 0, s[20:21]
	s_waitcnt lgkmcnt(0)
	v_add_f32_e32 v98, v100, v101
	v_lshl_add_u64 v[96:97], v[96:97], 0, s[4:5]
	global_store_dword v[96:97], v98, off
	v_pk_add_f32 v[98:99], v[90:91], v[216:217]
	v_pk_add_f32 v[90:91], v[88:89], v[214:215]
	v_mul_f32_e32 v88, v93, v93
	v_mul_f32_e32 v89, v95, v95
	v_fmac_f32_e32 v88, v92, v92
	v_fmac_f32_e32 v89, v94, v94
	v_add_f32_e32 v88, v88, v89
	v_mul_f32_e32 v89, v91, v91
	v_fmac_f32_e32 v89, v90, v90
	v_add_f32_e32 v88, v88, v89
	v_mul_f32_e32 v89, v99, v99
	v_fmac_f32_e32 v89, v98, v98
	v_pk_add_f32 v[86:87], v[86:87], v[228:229]
	v_pk_add_f32 v[84:85], v[84:85], v[226:227]
	v_add_f32_e32 v100, v89, v88
	v_cvt_pk_bf16_f32 v88, v92, v93
	v_pk_add_f32 v[92:93], v[82:83], v[224:225]
	v_pk_add_f32 v[82:83], v[80:81], v[222:223]
	v_mul_f32_e32 v80, v85, v85
	v_mul_f32_e32 v81, v87, v87
	v_fmac_f32_e32 v80, v84, v84
	v_fmac_f32_e32 v81, v86, v86
	v_add_f32_e32 v80, v80, v81
	v_mul_f32_e32 v81, v83, v83
	v_fmac_f32_e32 v81, v82, v82
	v_add_f32_e32 v80, v80, v81
	v_mul_f32_e32 v81, v93, v93
	v_fmac_f32_e32 v81, v92, v92
	v_add_f32_e32 v80, v81, v80
	v_cvt_pk_bf16_f32 v89, v94, v95
	v_cvt_pk_bf16_f32 v90, v90, v91
	v_cvt_pk_bf16_f32 v91, v98, v99
	v_add_f32_e32 v98, v100, v80
	ds_bpermute_b32 v99, v175, v98
	v_lshlrev_b64 v[96:97], 11, v[168:169]
	v_lshl_add_u64 v[80:81], s[6:7], 0, v[96:97]
	v_lshl_add_u64 v[94:95], v[80:81], 0, v[160:161]
	global_store_dwordx4 v[94:95], v[88:91], off
	v_cvt_pk_bf16_f32 v80, v84, v85
	s_waitcnt lgkmcnt(0)
	v_add_f32_e32 v84, v98, v99
	ds_bpermute_b32 v85, v176, v84
	v_cvt_pk_bf16_f32 v81, v86, v87
	v_cvt_pk_bf16_f32 v82, v82, v83
	v_cvt_pk_bf16_f32 v83, v92, v93
	global_store_dwordx4 v[94:95], v[80:83], off offset:256
	v_pk_add_f32 v[78:79], v[78:79], v[142:143]
	v_pk_add_f32 v[76:77], v[76:77], v[140:141]
	v_lshlrev_b64 v[80:81], 6, v[168:169]
	v_lshl_add_u64 v[80:81], s[8:9], 0, v[80:81]
	v_lshl_add_u64 v[80:81], v[80:81], 0, s[20:21]
	s_waitcnt lgkmcnt(0)
; __device__ __forceinline__ float shx(float v, int lane, int mask) { return __int_as_float(__builtin_amdgcn_ds_bpermute((lane ^ mask) << 2, __float_as_int(v))); }
; __device__ __forceinline__ unsigned cvt_pk_bf16(float lo, float hi) { unsigned r; asm volatile("v_cvt_pk_bf16_f32 %0, %1, %2" : "=v"(r) : "v"(lo), "v"(hi)); return r; }
;     __device__ __forceinline__ void operator()(const f32x4 (&acc)[2][2][4][2], const Unit& u, int wr, int wc, int fr, int fq) const {
;     ...
; #pragma unroll
;             for (int m = 0; m < 4; ++m)
; #pragma unroll
;                 for (int bj = 0; bj < 2; ++bj) {
;                     const size_t o = (size_t)(row0 + ai * 128 + m * 16) * 1024 + col0 + bj * 128;
;                     xv[m][bj][0] = *(const f32x4*)(x + o); xv[m][bj][1] = *(const f32x4*)(x + o + 4);
;                 }
; #pragma unroll
;             for (int m = 0; m < 4; ++m) {
;                 const int row = row0 + ai * 128 + m * 16; float ss = 0.f;
; #pragma unroll
;                 for (int bj = 0; bj < 2; ++bj) {
;                     const size_t o = (size_t)row * 1024 + col0 + bj * 128;
;                     const f32x4 v0 = xv[m][bj][0] + acc[ai][bj][m][0], v1 = xv[m][bj][1] + acc[ai][bj][m][1];
;                     ss += (v0[0] * v0[0] + v0[1] * v0[1]) + (v0[2] * v0[2] + v0[3] * v0[3]) + (v1[0] * v1[0] + v1[1] * v1[1]) + (v1[2] * v1[2] + v1[3] * v1[3]);
;                     u32x4 w; w.x = cvt_pk_bf16(v0[0], v0[1]); w.y = cvt_pk_bf16(v0[2], v0[3]); w.z = cvt_pk_bf16(v1[0], v1[1]); w.w = cvt_pk_bf16(v1[2], v1[3]);
;                     *(u32x4*)(x1b + o) = w;
;                 }
;                 ss += shx(ss, fq * 16 + fr, 16); ss += shx(ss, fq * 16 + fr, 32);
;                 ss2[(size_t)row * 16 + u.pn * 4 + wc] = ss;
;             }
	v_add_f32_e32 v82, v84, v85
	v_lshl_add_u64 v[80:81], v[80:81], 0, s[4:5]
	global_store_dword v[80:81], v82, off
	v_pk_add_f32 v[82:83], v[74:75], v[138:139]
	v_pk_add_f32 v[74:75], v[72:73], v[136:137]
	v_mul_f32_e32 v72, v77, v77
	v_mul_f32_e32 v73, v79, v79
	v_fmac_f32_e32 v72, v76, v76
	v_fmac_f32_e32 v73, v78, v78
	v_add_f32_e32 v72, v72, v73
	v_mul_f32_e32 v73, v75, v75
	v_fmac_f32_e32 v73, v74, v74
	v_add_f32_e32 v72, v72, v73
	v_mul_f32_e32 v73, v83, v83
	v_fmac_f32_e32 v73, v82, v82
	v_pk_add_f32 v[70:71], v[70:71], v[134:135]
	v_pk_add_f32 v[68:69], v[68:69], v[132:133]
	v_add_f32_e32 v84, v73, v72
	v_cvt_pk_bf16_f32 v72, v76, v77
	v_pk_add_f32 v[76:77], v[66:67], v[130:131]
	v_pk_add_f32 v[66:67], v[64:65], v[128:129]
	v_mul_f32_e32 v64, v69, v69
	v_mul_f32_e32 v65, v71, v71
	v_fmac_f32_e32 v64, v68, v68
	v_fmac_f32_e32 v65, v70, v70
	v_add_f32_e32 v64, v64, v65
	v_mul_f32_e32 v65, v67, v67
	v_fmac_f32_e32 v65, v66, v66
	v_add_f32_e32 v64, v64, v65
	v_mul_f32_e32 v65, v77, v77
	v_fmac_f32_e32 v65, v76, v76
	v_add_f32_e32 v64, v65, v64
	v_cvt_pk_bf16_f32 v73, v78, v79
	v_cvt_pk_bf16_f32 v74, v74, v75
	v_cvt_pk_bf16_f32 v75, v82, v83
	v_add_f32_e32 v82, v84, v64
	ds_bpermute_b32 v83, v175, v82
	v_lshlrev_b64 v[80:81], 11, v[166:167]
	v_lshl_add_u64 v[64:65], s[6:7], 0, v[80:81]
	v_lshl_add_u64 v[78:79], v[64:65], 0, v[160:161]
	global_store_dwordx4 v[78:79], v[72:75], off
	v_cvt_pk_bf16_f32 v64, v68, v69
	s_waitcnt lgkmcnt(0)
	v_add_f32_e32 v68, v82, v83
	ds_bpermute_b32 v69, v176, v68
	v_cvt_pk_bf16_f32 v65, v70, v71
	v_cvt_pk_bf16_f32 v66, v66, v67
	v_cvt_pk_bf16_f32 v67, v76, v77
	global_store_dwordx4 v[78:79], v[64:67], off offset:256
	v_add_u32_e32 v132, 0x80, v162
	v_ashrrev_i32_e32 v133, 31, v132
	v_lshlrev_b64 v[64:65], 6, v[166:167]
	v_lshl_add_u64 v[64:65], s[8:9], 0, v[64:65]
	v_lshl_add_u64 v[64:65], v[64:65], 0, s[20:21]
	s_waitcnt lgkmcnt(0)
	v_add_f32_e32 v66, v68, v69
	v_lshl_add_u64 v[64:65], v[64:65], 0, s[4:5]
	global_store_dword v[64:65], v66, off
	v_lshlrev_b64 v[64:65], 12, v[132:133]
	v_lshl_add_u64 v[64:65], v[164:165], 0, v[64:65]
	global_load_dwordx4 v[92:95], v[64:65], off
	global_load_dwordx4 v[96:99], v[64:65], off offset:16
	global_load_dwordx4 v[100:103], v[64:65], off offset:512
	global_load_dwordx4 v[104:107], v[64:65], off offset:528
	v_add_u32_e32 v134, 0x90, v162
	v_ashrrev_i32_e32 v135, 31, v134
	v_lshlrev_b64 v[64:65], 12, v[134:135]
	v_lshl_add_u64 v[64:65], v[164:165], 0, v[64:65]
	global_load_dwordx4 v[108:111], v[64:65], off
	global_load_dwordx4 v[112:115], v[64:65], off offset:16
	global_load_dwordx4 v[116:119], v[64:65], off offset:528
	global_load_dwordx4 v[120:123], v[64:65], off offset:512
	v_add_u32_e32 v90, 0xa0, v162
	v_ashrrev_i32_e32 v91, 31, v90
	v_lshlrev_b64 v[64:65], 12, v[90:91]
	v_lshl_add_u64 v[64:65], v[164:165], 0, v[64:65]
	global_load_dwordx4 v[124:127], v[64:65], off offset:16
	global_load_dwordx4 v[128:131], v[64:65], off
	global_load_dwordx4 v[80:83], v[64:65], off offset:528
	global_load_dwordx4 v[84:87], v[64:65], off offset:512
	v_add_u32_e32 v88, 0xb0, v162
	v_ashrrev_i32_e32 v89, 31, v88
	v_lshlrev_b64 v[64:65], 12, v[88:89]
	v_lshl_add_u64 v[68:69], v[164:165], 0, v[64:65]
	global_load_dwordx4 v[72:75], v[68:69], off offset:16
	global_load_dwordx4 v[76:79], v[68:69], off
	global_load_dwordx4 v[64:67], v[68:69], off offset:528
	s_nop 0
	global_load_dwordx4 v[68:71], v[68:69], off offset:512
	v_lshlrev_b64 v[136:137], 11, v[132:133]
	s_waitcnt vmcnt(15)
	v_pk_add_f32 v[62:63], v[62:63], v[94:95]
	v_pk_add_f32 v[60:61], v[60:61], v[92:93]
	s_waitcnt vmcnt(14)
	v_pk_add_f32 v[92:93], v[58:59], v[98:99]
	v_pk_add_f32 v[58:59], v[56:57], v[96:97]
	v_mul_f32_e32 v56, v61, v61
	v_mul_f32_e32 v57, v63, v63
	v_fmac_f32_e32 v56, v60, v60
	v_fmac_f32_e32 v57, v62, v62
	v_add_f32_e32 v56, v56, v57
	v_mul_f32_e32 v57, v59, v59
	v_fmac_f32_e32 v57, v58, v58
	v_add_f32_e32 v56, v56, v57
	v_mul_f32_e32 v57, v93, v93
	v_fmac_f32_e32 v57, v92, v92
	s_waitcnt vmcnt(13)
	v_pk_add_f32 v[54:55], v[54:55], v[102:103]
	v_pk_add_f32 v[52:53], v[52:53], v[100:101]
	v_add_f32_e32 v94, v57, v56
	v_cvt_pk_bf16_f32 v56, v60, v61
	s_waitcnt vmcnt(12)
	v_pk_add_f32 v[60:61], v[50:51], v[106:107]
	v_pk_add_f32 v[50:51], v[48:49], v[104:105]
	v_mul_f32_e32 v48, v53, v53
	v_mul_f32_e32 v49, v55, v55
	v_fmac_f32_e32 v48, v52, v52
	v_fmac_f32_e32 v49, v54, v54
	v_add_f32_e32 v48, v48, v49
	v_mul_f32_e32 v49, v51, v51
	v_fmac_f32_e32 v49, v50, v50
	v_add_f32_e32 v48, v48, v49
	v_mul_f32_e32 v49, v61, v61
	v_fmac_f32_e32 v49, v60, v60
	v_add_f32_e32 v48, v49, v48
	v_cvt_pk_bf16_f32 v57, v62, v63
	v_cvt_pk_bf16_f32 v58, v58, v59
	v_cvt_pk_bf16_f32 v59, v92, v93
	v_add_f32_e32 v92, v94, v48
	ds_bpermute_b32 v93, v175, v92
	v_lshl_add_u64 v[48:49], s[6:7], 0, v[136:137]
	v_lshl_add_u64 v[62:63], v[48:49], 0, v[160:161]
	global_store_dwordx4 v[62:63], v[56:59], off
	v_cvt_pk_bf16_f32 v48, v52, v53
	s_waitcnt lgkmcnt(0)
	v_add_f32_e32 v52, v92, v93
	ds_bpermute_b32 v53, v176, v52
	v_cvt_pk_bf16_f32 v49, v54, v55
	v_cvt_pk_bf16_f32 v50, v50, v51
	v_cvt_pk_bf16_f32 v51, v60, v61
	global_store_dwordx4 v[62:63], v[48:51], off offset:256
	s_waitcnt vmcnt(13)
	v_pk_add_f32 v[46:47], v[46:47], v[110:111]
	v_pk_add_f32 v[44:45], v[44:45], v[108:109]
	v_lshlrev_b64 v[48:49], 6, v[132:133]
	v_lshl_add_u64 v[48:49], s[8:9], 0, v[48:49]
	v_lshl_add_u64 v[48:49], v[48:49], 0, s[20:21]
	s_waitcnt lgkmcnt(0)
	v_add_f32_e32 v50, v52, v53
	v_lshl_add_u64 v[48:49], v[48:49], 0, s[4:5]
	global_store_dword v[48:49], v50, off
	s_waitcnt vmcnt(13)
; __device__ __forceinline__ float shx(float v, int lane, int mask) { return __int_as_float(__builtin_amdgcn_ds_bpermute((lane ^ mask) << 2, __float_as_int(v))); }
; __device__ __forceinline__ unsigned cvt_pk_bf16(float lo, float hi) { unsigned r; asm volatile("v_cvt_pk_bf16_f32 %0, %1, %2" : "=v"(r) : "v"(lo), "v"(hi)); return r; }
; #define PG8_WAIT_V(n) asm volatile("s_waitcnt vmcnt(" #n ")" ::: "memory")
; #define PG8_BAR __builtin_amdgcn_s_barrier()
; template <class Epi, class Sched>
; __device__ __forceinline__ void gemm_phase(const int wv, LAS unsigned char* lds, const Gemm g, const Sched& S, const Epi& E) {
;     ...
;     PG8_WAIT_V(0);
;     if (wr == 0) PG8_BAR;
;     PG8_BAR;
;     __device__ __forceinline__ void operator()(const f32x4 (&acc)[2][2][4][2], const Unit& u, int wr, int wc, int fr, int fq) const {
;     ...
; #pragma unroll
;             for (int m = 0; m < 4; ++m) {
;                 const int row = row0 + ai * 128 + m * 16; float ss = 0.f;
; #pragma unroll
;                 for (int bj = 0; bj < 2; ++bj) {
;                     const size_t o = (size_t)row * 1024 + col0 + bj * 128;
;                     const f32x4 v0 = xv[m][bj][0] + acc[ai][bj][m][0], v1 = xv[m][bj][1] + acc[ai][bj][m][1];
;                     ss += (v0[0] * v0[0] + v0[1] * v0[1]) + (v0[2] * v0[2] + v0[3] * v0[3]) + (v1[0] * v1[0] + v1[1] * v1[1]) + (v1[2] * v1[2] + v1[3] * v1[3]);
;                     u32x4 w; w.x = cvt_pk_bf16(v0[0], v0[1]); w.y = cvt_pk_bf16(v0[2], v0[3]); w.z = cvt_pk_bf16(v1[0], v1[1]); w.w = cvt_pk_bf16(v1[2], v1[3]);
;                     *(u32x4*)(x1b + o) = w;
;                 }
;                 ss += shx(ss, fq * 16 + fr, 16); ss += shx(ss, fq * 16 + fr, 32);
;                 ss2[(size_t)row * 16 + u.pn * 4 + wc] = ss;
;             }
	v_pk_add_f32 v[50:51], v[42:43], v[114:115]
	v_pk_add_f32 v[42:43], v[40:41], v[112:113]
	v_mul_f32_e32 v40, v45, v45
	v_mul_f32_e32 v41, v47, v47
	v_fmac_f32_e32 v40, v44, v44
	v_fmac_f32_e32 v41, v46, v46
	v_add_f32_e32 v40, v40, v41
	v_mul_f32_e32 v41, v43, v43
	v_fmac_f32_e32 v41, v42, v42
	v_add_f32_e32 v40, v40, v41
	v_mul_f32_e32 v41, v51, v51
	v_fmac_f32_e32 v41, v50, v50
	s_waitcnt vmcnt(11)
	v_pk_add_f32 v[38:39], v[38:39], v[122:123]
	v_pk_add_f32 v[36:37], v[36:37], v[120:121]
	v_add_f32_e32 v52, v41, v40
	v_cvt_pk_bf16_f32 v40, v44, v45
	v_pk_add_f32 v[44:45], v[34:35], v[118:119]
	v_pk_add_f32 v[34:35], v[32:33], v[116:117]
	v_mul_f32_e32 v32, v37, v37
	v_mul_f32_e32 v33, v39, v39
	v_fmac_f32_e32 v32, v36, v36
	v_fmac_f32_e32 v33, v38, v38
	v_add_f32_e32 v32, v32, v33
	v_mul_f32_e32 v33, v35, v35
	v_fmac_f32_e32 v33, v34, v34
	v_add_f32_e32 v32, v32, v33
	v_mul_f32_e32 v33, v45, v45
	v_fmac_f32_e32 v33, v44, v44
	v_add_f32_e32 v32, v33, v32
	v_cvt_pk_bf16_f32 v41, v46, v47
	v_cvt_pk_bf16_f32 v42, v42, v43
	v_cvt_pk_bf16_f32 v43, v50, v51
	v_add_f32_e32 v50, v52, v32
	ds_bpermute_b32 v51, v175, v50
	v_lshlrev_b64 v[48:49], 11, v[134:135]
	v_lshl_add_u64 v[32:33], s[6:7], 0, v[48:49]
	v_lshl_add_u64 v[46:47], v[32:33], 0, v[160:161]
	global_store_dwordx4 v[46:47], v[40:43], off
	v_cvt_pk_bf16_f32 v32, v36, v37
	s_waitcnt lgkmcnt(0)
	v_add_f32_e32 v36, v50, v51
	ds_bpermute_b32 v37, v176, v36
	v_cvt_pk_bf16_f32 v33, v38, v39
	v_cvt_pk_bf16_f32 v34, v34, v35
	v_cvt_pk_bf16_f32 v35, v44, v45
	global_store_dwordx4 v[46:47], v[32:35], off offset:256
	s_waitcnt vmcnt(11)
	v_pk_add_f32 v[30:31], v[30:31], v[130:131]
	v_pk_add_f32 v[28:29], v[28:29], v[128:129]
	v_lshlrev_b64 v[32:33], 6, v[134:135]
	v_lshl_add_u64 v[32:33], s[8:9], 0, v[32:33]
	v_lshl_add_u64 v[32:33], v[32:33], 0, s[20:21]
	s_waitcnt lgkmcnt(0)
	v_add_f32_e32 v34, v36, v37
	v_lshl_add_u64 v[32:33], v[32:33], 0, s[4:5]
	global_store_dword v[32:33], v34, off
	v_pk_add_f32 v[34:35], v[26:27], v[126:127]
	v_pk_add_f32 v[26:27], v[24:25], v[124:125]
	v_mul_f32_e32 v24, v29, v29
	v_mul_f32_e32 v25, v31, v31
	v_fmac_f32_e32 v24, v28, v28
	v_fmac_f32_e32 v25, v30, v30
	v_add_f32_e32 v24, v24, v25
	v_mul_f32_e32 v25, v27, v27
	v_fmac_f32_e32 v25, v26, v26
	v_add_f32_e32 v24, v24, v25
	v_mul_f32_e32 v25, v35, v35
	v_fmac_f32_e32 v25, v34, v34
	s_waitcnt vmcnt(10)
	v_pk_add_f32 v[22:23], v[22:23], v[86:87]
	v_pk_add_f32 v[20:21], v[20:21], v[84:85]
	v_add_f32_e32 v36, v25, v24
	v_cvt_pk_bf16_f32 v24, v28, v29
	v_pk_add_f32 v[28:29], v[18:19], v[82:83]
	v_pk_add_f32 v[18:19], v[16:17], v[80:81]
	v_mul_f32_e32 v16, v21, v21
	v_mul_f32_e32 v17, v23, v23
	v_fmac_f32_e32 v16, v20, v20
	v_fmac_f32_e32 v17, v22, v22
	v_add_f32_e32 v16, v16, v17
	v_mul_f32_e32 v17, v19, v19
	v_fmac_f32_e32 v17, v18, v18
	v_add_f32_e32 v16, v16, v17
	v_mul_f32_e32 v17, v29, v29
	v_fmac_f32_e32 v17, v28, v28
	v_add_f32_e32 v16, v17, v16
	v_cvt_pk_bf16_f32 v25, v30, v31
	v_cvt_pk_bf16_f32 v26, v26, v27
	v_cvt_pk_bf16_f32 v27, v34, v35
	v_add_f32_e32 v34, v36, v16
	ds_bpermute_b32 v35, v175, v34
	v_lshlrev_b64 v[32:33], 11, v[90:91]
	v_lshl_add_u64 v[16:17], s[6:7], 0, v[32:33]
	v_lshl_add_u64 v[30:31], v[16:17], 0, v[160:161]
	global_store_dwordx4 v[30:31], v[24:27], off
	v_cvt_pk_bf16_f32 v16, v20, v21
	s_waitcnt lgkmcnt(0)
	v_add_f32_e32 v20, v34, v35
	ds_bpermute_b32 v21, v176, v20
	v_cvt_pk_bf16_f32 v17, v22, v23
	v_cvt_pk_bf16_f32 v18, v18, v19
	v_cvt_pk_bf16_f32 v19, v28, v29
	global_store_dwordx4 v[30:31], v[16:19], off offset:256
	s_waitcnt vmcnt(10)
	v_pk_add_f32 v[14:15], v[14:15], v[78:79]
	v_pk_add_f32 v[12:13], v[12:13], v[76:77]
	v_lshlrev_b64 v[16:17], 6, v[90:91]
	v_lshl_add_u64 v[16:17], s[8:9], 0, v[16:17]
	v_lshl_add_u64 v[16:17], v[16:17], 0, s[20:21]
	s_waitcnt lgkmcnt(0)
	v_add_f32_e32 v18, v20, v21
	v_lshl_add_u64 v[16:17], v[16:17], 0, s[4:5]
	global_store_dword v[16:17], v18, off
	v_pk_add_f32 v[18:19], v[10:11], v[74:75]
	v_pk_add_f32 v[10:11], v[8:9], v[72:73]
	v_mul_f32_e32 v8, v13, v13
	v_mul_f32_e32 v9, v15, v15
	v_fmac_f32_e32 v8, v12, v12
	v_fmac_f32_e32 v9, v14, v14
	v_add_f32_e32 v8, v8, v9
	v_mul_f32_e32 v9, v11, v11
	v_fmac_f32_e32 v9, v10, v10
	v_add_f32_e32 v8, v8, v9
	v_mul_f32_e32 v9, v19, v19
	v_fmac_f32_e32 v9, v18, v18
	s_waitcnt vmcnt(9)
	v_pk_add_f32 v[6:7], v[6:7], v[70:71]
	v_pk_add_f32 v[4:5], v[4:5], v[68:69]
	v_add_f32_e32 v20, v9, v8
	v_cvt_pk_bf16_f32 v8, v12, v13
	v_pk_add_f32 v[12:13], v[2:3], v[66:67]
	v_pk_add_f32 v[2:3], v[0:1], v[64:65]
	v_mul_f32_e32 v0, v5, v5
	v_mul_f32_e32 v1, v7, v7
	v_fmac_f32_e32 v0, v4, v4
	v_fmac_f32_e32 v1, v6, v6
	v_add_f32_e32 v0, v0, v1
	v_mul_f32_e32 v1, v3, v3
	v_fmac_f32_e32 v1, v2, v2
	v_add_f32_e32 v0, v0, v1
	v_mul_f32_e32 v1, v13, v13
	v_fmac_f32_e32 v1, v12, v12
	v_add_f32_e32 v0, v1, v0
	v_cvt_pk_bf16_f32 v9, v14, v15
	v_cvt_pk_bf16_f32 v10, v10, v11
	v_cvt_pk_bf16_f32 v11, v18, v19
	v_add_f32_e32 v18, v20, v0
	ds_bpermute_b32 v19, v175, v18
	v_lshlrev_b64 v[16:17], 11, v[88:89]
	v_lshl_add_u64 v[0:1], s[6:7], 0, v[16:17]
	v_lshl_add_u64 v[14:15], v[0:1], 0, v[160:161]
	global_store_dwordx4 v[14:15], v[8:11], off
	v_cvt_pk_bf16_f32 v0, v4, v5
	s_waitcnt lgkmcnt(0)
	v_add_f32_e32 v4, v18, v19
	ds_bpermute_b32 v5, v176, v4
	v_cvt_pk_bf16_f32 v1, v6, v7
	v_cvt_pk_bf16_f32 v2, v2, v3
	v_cvt_pk_bf16_f32 v3, v12, v13
	global_store_dwordx4 v[14:15], v[0:3], off offset:256
	s_nop 1
	v_lshlrev_b64 v[0:1], 6, v[88:89]
	v_lshl_add_u64 v[0:1], s[8:9], 0, v[0:1]
	v_lshl_add_u64 v[0:1], v[0:1], 0, s[20:21]
	s_waitcnt lgkmcnt(0)
	v_add_f32_e32 v2, v4, v5
	v_lshl_add_u64 v[0:1], v[0:1], 0, s[4:5]
	s_mov_b32 s21, s12
	s_mov_b32 s20, s14
	global_store_dword v[0:1], v2, off
	s_cbranch_vccz .LBB0_654
	s_waitcnt vmcnt(0)
	s_cmpk_gt_u32 s28, 0xff
	s_cbranch_scc1 .LBB0_665
	s_barrier

; __device__ __forceinline__ void xcd_barrier(const int wv, const XcdBarrier& b) {
;     asm volatile("s_waitcnt vmcnt(0)" ::: "memory");
;     __syncthreads();
;     if (TIDX == 0) {
;         unsigned long long barq = (unsigned long long)b.bar; asm volatile("" : "+s"(barq));
;         unsigned* bar = (unsigned*)barq;
;         __builtin_amdgcn_s_waitcnt(0);
;         unsigned nloc = b.st[0], nx = b.st[1];
;         if (nloc == 0u) { xcd_barrier_complete(bar, b.x, nloc, nx); b.st[0] = nloc; b.st[1] = nx; }
.LBB0_666:
	s_setprio 0
	s_waitcnt vmcnt(0)
	s_barrier
	v_mbcnt_lo_u32_b32 v0, -1, 0
	v_mbcnt_hi_u32_b32 v0, -1, v0
	s_nop 0
	v_sub_u32_e32 v0, 0, v0
	v_cmp_eq_u32_e32 vcc, s53, v0
	s_and_saveexec_b64 s[0:1], vcc
	s_cbranch_execz .LBB0_710
	s_add_i32 s4, 0, 0x21ff0
	s_mov_b64 s[2:3], s[58:59]
	v_mov_b32_e32 v0, s4
	s_waitcnt vmcnt(0) expcnt(0) lgkmcnt(0)
	ds_read_b32 v4, v0
	s_add_i32 s4, 0, 0x21ff4
	v_mov_b32_e32 v0, s4
	ds_read_b32 v2, v0
	s_waitcnt lgkmcnt(1)
	v_cmp_ne_u32_e32 vcc, 0, v4
	s_cbranch_vccnz .LBB0_681
	s_add_u32 s6, s2, 0x1000
	s_addc_u32 s7, s3, 0
	s_add_u32 s8, s2, 0x1100
	s_addc_u32 s9, s3, 0
	s_add_u32 s10, s2, 0x1200
	s_addc_u32 s11, s3, 0
	s_add_u32 s12, s2, 0x1300
	s_addc_u32 s13, s3, 0
	s_mov_b32 s22, 1
	s_mov_b64 s[4:5], 0
	v_mov_b64_e32 v[0:1], s[2:3]
	s_waitcnt lgkmcnt(0)
	v_mov_b64_e32 v[2:3], s[6:7]
	v_mov_b64_e32 v[4:5], s[8:9]
	v_mov_b64_e32 v[6:7], s[10:11]
	v_mov_b64_e32 v[8:9], s[12:13]
	s_branch .LBB0_671

;     __device__ void init(int b_, int G_, int c_) { so.init(TB, 42 * 256, G_, c_); G = G_; c = c_; b = b_; gstart = b_ == 0 ? 0 : 256 + 192 * b_; ng = b_ == 0 ? 448 : 192; }
; __device__ __forceinline__ KParams kparams() { unsigned long long a = (unsigned long long)__builtin_amdgcn_kernarg_segment_ptr(); asm volatile("" : "+s"(a)); return (KParams)a; }
; template <class Epi, class Sched>
; __device__ __forceinline__ void gemm_phase(const int wv, LAS unsigned char* lds, const Gemm g, const Sched& S, const Epi& E) {
;     int tid_ = TIDX; asm volatile("" : "+v"(tid_));
;     const int tid = tid_, wid = __builtin_amdgcn_readfirstlane(tid >> 6), lane = tid & 63, wr = wid >> 2, wc = wid & 3, fr = lane & 15, fq = lane >> 4;
;     const int K = g.K, nt = K / BK;
; __global__ void __launch_bounds__(512, 2) mega(Params p_unused) {
;     ...
;         KParams kp = kparams(); unsigned char* ws = kp->ws;
;         pg8::StaticOrder S; S.init(MT, DFF, (int)gridDim.x, (int)blockIdx.x);
;         pg8::Gemm gm{WSP(bf16_t, WS_X1B), WSP(bf16_t, WS_WUP), MT, DFF, DM, DM, DM}; EpiUp E{WSP(float, WS_SS2), WSP(bf16_t, WS_H)};
;         pg8::gemm_phase<EpiUp, pg8::StaticOrder>(wv, lds, gm, S, E);
.LBB0_710:
	s_or_b64 exec, exec, s[0:1]
	s_mov_b64 s[0:1], s[56:57]
	s_waitcnt lgkmcnt(0)
	s_barrier
	s_cmpk_lt_u32 s53, 0x100
	s_cbranch_scc1 .Lgprio_up
	s_setprio 1
.Lgprio_up:
	v_mbcnt_lo_u32_b32 v0, -1, 0
	v_mbcnt_hi_u32_b32 v0, -1, v0
	s_cmpk_gt_i32 s66, 0x7ff
	v_add_u32_e32 v8, s53, v0
	s_nop 0
	v_readfirstlane_b32 s22, v8
	s_cbranch_scc1 .LBB0_730
	s_load_dwordx2 s[0:1], s[0:1], 0x70
	s_and_b64 vcc, exec, s[62:63]
	s_cbranch_vccz .LBB0_713
	s_lshl_b32 s6, s60, 8
	s_cbranch_execz .LBB0_714
	s_branch .LBB0_715

; #define PG8_STAGE(bufoff, gbase, voff) do { _Pragma("unroll") for (int _i = 0; _i < 2; ++_i) \
;         __builtin_amdgcn_global_load_lds((const unsigned*)((const char*)(gbase) + (voff)[_i]), (LAS unsigned*)(lds + (bufoff) + ldsw + _i * 8192), 16, 0, 0); } while (0)
; #define PG8_LDA(dst, b, h) do { _Pragma("unroll") for (int m = 0; m < 4; ++m) _Pragma("unroll") for (int k = 0; k < 2; ++k) dst[m][k] = *(const LAS bf16x8*)(lds + PG8_SA(b, h) + aoff + m * 2048 + k * 1024); } while (0)
; #define PG8_LDB(dst, b, h) do { _Pragma("unroll") for (int n = 0; n < 2; ++n) _Pragma("unroll") for (int k = 0; k < 2; ++k) dst[n][k] = *(const LAS bf16x8*)(lds + PG8_SB(b, h) + boff + n * 2048 + k * 1024); } while (0)
; #define PG8_MMA(ai, bj, At, Bt) do { __builtin_amdgcn_s_setprio(1); _Pragma("unroll") for (int m = 0; m < 4; ++m) _Pragma("unroll") for (int n = 0; n < 2; ++n) _Pragma("unroll") for (int k = 0; k < 2; ++k) \
;         acc[ai][bj][m][n] = __builtin_amdgcn_mfma_f32_16x16x32_bf16(Bt[n][k], At[m][k], acc[ai][bj][m][n], 0, 0, 0); __builtin_amdgcn_s_setprio(0); } while (0)
; #define PG8_WAIT_L(n) asm volatile("s_waitcnt lgkmcnt(" #n ")" ::: "memory")
; #define PG8_BAR __builtin_amdgcn_s_barrier()
; #define PG8_SCHED __builtin_amdgcn_sched_barrier(0)
; template <class Epi, class Sched>
; __device__ __forceinline__ void gemm_phase(const int wv, LAS unsigned char* lds, const Gemm g, const Sched& S, const Epi& E) {
;     ...
;             PG8_LDB(B0, 0, 0); PG8_SCHED; PG8_LDA(At, 0, 0); PG8_STAGE(PG8_SA(1, 1), a1 + hstepA, voffA);
;             PG8_WAIT_L(8); PG8_BAR; PG8_WAIT_L(0); PG8_MMA(0, 0, At, B0); PG8_BAR; PG8_SCHED;
;             PG8_LDB(B1, 0, 1); PG8_STAGE(PG8_SB(0, 0), b2, voffB);
;             PG8_BAR; PG8_WAIT_L(0); PG8_MMA(0, 1, At, B1); PG8_BAR;
;             PG8_LDA(At, 0, 1); PG8_STAGE(PG8_SA(0, 0), a2, voffA);
;             PG8_BAR; PG8_WAIT_L(0); PG8_MMA(1, 0, At, B0); PG8_BAR; PG8_SCHED;
.LBB0_725:
	ds_read_b128 v[128:131], v176
	ds_read_b128 v[132:135], v176 offset:1024
	ds_read_b128 v[136:139], v176 offset:2048
	ds_read_b128 v[140:143], v176 offset:3072
	s_add_u32 s18, s16, 0xfffc0080
	s_addc_u32 s19, s17, -1
	s_cmp_eq_u32 s46, 12
	s_cselect_b32 s21, s9, s19
	s_cselect_b32 s20, s42, s18
	s_cselect_b32 s19, s7, s45
	s_cselect_b32 s18, s43, s44
	v_lshl_add_u64 v[170:171], s[16:17], 0, v[160:161]
	s_add_i32 m0, s28, 0xc000
	ds_read_b128 v[144:147], v177
	ds_read_b128 v[182:185], v177 offset:1024
	ds_read_b128 v[186:189], v177 offset:2048
	ds_read_b128 v[190:193], v177 offset:3072
	ds_read_b128 v[194:197], v177 offset:4096
	ds_read_b128 v[198:201], v177 offset:5120
	ds_read_b128 v[202:205], v177 offset:6144
	ds_read_b128 v[206:209], v177 offset:7168
	global_load_lds_dwordx4 v[170:171], off
	v_lshl_add_u64 v[170:171], s[16:17], 0, v[162:163]
	s_add_i32 m0, s28, 0xe000
	s_nop 0
	global_load_lds_dwordx4 v[170:171], off
	s_waitcnt lgkmcnt(8)
	s_barrier
	s_waitcnt lgkmcnt(0)
	s_waitcnt lgkmcnt(0)
	v_mfma_f32_16x16x32_bf16 v[124:127], v[128:131], v[144:147], v[124:127]
	v_mfma_f32_16x16x32_bf16 v[120:123], v[136:139], v[144:147], v[120:123]
	v_mfma_f32_16x16x32_bf16 v[108:111], v[128:131], v[186:189], v[108:111]
	v_mfma_f32_16x16x32_bf16 v[104:107], v[136:139], v[186:189], v[104:107]
	v_mfma_f32_16x16x32_bf16 v[92:95], v[128:131], v[194:197], v[92:95]
	v_mfma_f32_16x16x32_bf16 v[88:91], v[136:139], v[194:197], v[88:91]
	v_mfma_f32_16x16x32_bf16 v[76:79], v[128:131], v[202:205], v[76:79]
	v_mfma_f32_16x16x32_bf16 v[72:75], v[136:139], v[202:205], v[72:75]
	v_mfma_f32_16x16x32_bf16 v[124:127], v[132:135], v[182:185], v[124:127]
	v_mfma_f32_16x16x32_bf16 v[120:123], v[140:143], v[182:185], v[120:123]
	v_mfma_f32_16x16x32_bf16 v[108:111], v[132:135], v[190:193], v[108:111]
	v_mfma_f32_16x16x32_bf16 v[104:107], v[140:143], v[190:193], v[104:107]
	v_mfma_f32_16x16x32_bf16 v[92:95], v[132:135], v[198:201], v[92:95]
	v_mfma_f32_16x16x32_bf16 v[88:91], v[140:143], v[198:201], v[88:91]
	v_mfma_f32_16x16x32_bf16 v[76:79], v[132:135], v[206:209], v[76:79]
	v_mfma_f32_16x16x32_bf16 v[72:75], v[140:143], v[206:209], v[72:75]
	s_barrier
	s_add_i32 s47, s39, s27
	v_lshl_add_u64 v[170:171], s[18:19], 0, v[150:151]
	s_mov_b32 m0, s47
	ds_read_b128 v[210:213], v180
	ds_read_b128 v[214:217], v180 offset:1024
	ds_read_b128 v[218:221], v180 offset:2048
	ds_read_b128 v[222:225], v180 offset:3072
	global_load_lds_dwordx4 v[170:171], off
	v_lshl_add_u64 v[226:227], s[18:19], 0, v[154:155]
	s_add_i32 m0, s47, 0x2000
	s_nop 0
	global_load_lds_dwordx4 v[226:227], off
	s_barrier
	s_waitcnt lgkmcnt(0)
	s_waitcnt lgkmcnt(0)
	v_mfma_f32_16x16x32_bf16 v[116:119], v[210:213], v[144:147], v[116:119]
	v_mfma_f32_16x16x32_bf16 v[112:115], v[218:221], v[144:147], v[112:115]
	v_mfma_f32_16x16x32_bf16 v[100:103], v[210:213], v[186:189], v[100:103]
	v_mfma_f32_16x16x32_bf16 v[96:99], v[218:221], v[186:189], v[96:99]
	v_mfma_f32_16x16x32_bf16 v[84:87], v[210:213], v[194:197], v[84:87]
	v_mfma_f32_16x16x32_bf16 v[80:83], v[218:221], v[194:197], v[80:83]
	v_mfma_f32_16x16x32_bf16 v[68:71], v[210:213], v[202:205], v[68:71]
	v_mfma_f32_16x16x32_bf16 v[64:67], v[218:221], v[202:205], v[64:67]
	v_mfma_f32_16x16x32_bf16 v[116:119], v[214:217], v[182:185], v[116:119]
	v_mfma_f32_16x16x32_bf16 v[112:115], v[222:225], v[182:185], v[112:115]
	v_mfma_f32_16x16x32_bf16 v[100:103], v[214:217], v[190:193], v[100:103]
	v_mfma_f32_16x16x32_bf16 v[96:99], v[222:225], v[190:193], v[96:99]
	v_mfma_f32_16x16x32_bf16 v[84:87], v[214:217], v[198:201], v[84:87]
	v_mfma_f32_16x16x32_bf16 v[80:83], v[222:225], v[198:201], v[80:83]
	v_mfma_f32_16x16x32_bf16 v[68:71], v[214:217], v[206:209], v[68:71]
	v_mfma_f32_16x16x32_bf16 v[64:67], v[222:225], v[206:209], v[64:67]
	s_mov_b32 m0, s28
	v_lshl_add_u64 v[228:229], s[20:21], 0, v[148:149]
	s_barrier
	ds_read_b128 v[144:147], v177 offset:16384
	ds_read_b128 v[182:185], v177 offset:17408
	ds_read_b128 v[186:189], v177 offset:18432
	ds_read_b128 v[190:193], v177 offset:19456
	ds_read_b128 v[194:197], v177 offset:20480
	ds_read_b128 v[198:201], v177 offset:21504
	ds_read_b128 v[202:205], v177 offset:22528
	ds_read_b128 v[206:209], v177 offset:23552
	global_load_lds_dwordx4 v[228:229], off
	v_lshl_add_u64 v[230:231], s[20:21], 0, v[152:153]
	s_mov_b32 m0, s29
	s_nop 0
	global_load_lds_dwordx4 v[230:231], off
	s_barrier
	s_waitcnt lgkmcnt(0)
	s_waitcnt lgkmcnt(0)
	v_mfma_f32_16x16x32_bf16 v[60:63], v[128:131], v[144:147], v[60:63]
	v_mfma_f32_16x16x32_bf16 v[56:59], v[136:139], v[144:147], v[56:59]
	v_mfma_f32_16x16x32_bf16 v[44:47], v[128:131], v[186:189], v[44:47]
	v_mfma_f32_16x16x32_bf16 v[40:43], v[136:139], v[186:189], v[40:43]
	v_mfma_f32_16x16x32_bf16 v[28:31], v[128:131], v[194:197], v[28:31]
	v_mfma_f32_16x16x32_bf16 v[24:27], v[136:139], v[194:197], v[24:27]
	v_mfma_f32_16x16x32_bf16 v[12:15], v[128:131], v[202:205], v[12:15]
	v_mfma_f32_16x16x32_bf16 v[8:11], v[136:139], v[202:205], v[8:11]
	v_mfma_f32_16x16x32_bf16 v[60:63], v[132:135], v[182:185], v[60:63]
	v_mfma_f32_16x16x32_bf16 v[56:59], v[140:143], v[182:185], v[56:59]
	v_mfma_f32_16x16x32_bf16 v[44:47], v[132:135], v[190:193], v[44:47]
	v_mfma_f32_16x16x32_bf16 v[40:43], v[140:143], v[190:193], v[40:43]
	v_mfma_f32_16x16x32_bf16 v[28:31], v[132:135], v[198:201], v[28:31]
	v_mfma_f32_16x16x32_bf16 v[24:27], v[140:143], v[198:201], v[24:27]
	v_mfma_f32_16x16x32_bf16 v[12:15], v[132:135], v[206:209], v[12:15]
	v_mfma_f32_16x16x32_bf16 v[8:11], v[140:143], v[206:209], v[8:11]
	s_barrier
; #define PG8_STAGE(bufoff, gbase, voff) do { _Pragma("unroll") for (int _i = 0; _i < 2; ++_i) \
;         __builtin_amdgcn_global_load_lds((const unsigned*)((const char*)(gbase) + (voff)[_i]), (LAS unsigned*)(lds + (bufoff) + ldsw + _i * 8192), 16, 0, 0); } while (0)
; #define PG8_LDA(dst, b, h) do { _Pragma("unroll") for (int m = 0; m < 4; ++m) _Pragma("unroll") for (int k = 0; k < 2; ++k) dst[m][k] = *(const LAS bf16x8*)(lds + PG8_SA(b, h) + aoff + m * 2048 + k * 1024); } while (0)
; #define PG8_LDB(dst, b, h) do { _Pragma("unroll") for (int n = 0; n < 2; ++n) _Pragma("unroll") for (int k = 0; k < 2; ++k) dst[n][k] = *(const LAS bf16x8*)(lds + PG8_SB(b, h) + boff + n * 2048 + k * 1024); } while (0)
; #define PG8_MMA(ai, bj, At, Bt) do { __builtin_amdgcn_s_setprio(1); _Pragma("unroll") for (int m = 0; m < 4; ++m) _Pragma("unroll") for (int n = 0; n < 2; ++n) _Pragma("unroll") for (int k = 0; k < 2; ++k) \
;         acc[ai][bj][m][n] = __builtin_amdgcn_mfma_f32_16x16x32_bf16(Bt[n][k], At[m][k], acc[ai][bj][m][n], 0, 0, 0); __builtin_amdgcn_s_setprio(0); } while (0)
; #define PG8_WAIT_V(n) asm volatile("s_waitcnt vmcnt(" #n ")" ::: "memory")
; #define PG8_WAIT_L(n) asm volatile("s_waitcnt lgkmcnt(" #n ")" ::: "memory")
; #define PG8_BAR __builtin_amdgcn_s_barrier()
; #define PG8_SCHED __builtin_amdgcn_sched_barrier(0)
; template <class Epi, class Sched>
; __device__ __forceinline__ void gemm_phase(const int wv, LAS unsigned char* lds, const Gemm g, const Sched& S, const Epi& E) {
;     ...
;             PG8_BAR; PG8_WAIT_L(0); PG8_MMA(1, 0, At, B0); PG8_BAR; PG8_SCHED;
;             PG8_STAGE(PG8_SB(0, 1), b2 + hstepB, voffB);
;             PG8_WAIT_V(6); PG8_BAR; PG8_MMA(1, 1, At, B1); PG8_BAR;
;             PG8_LDB(B0, 1, 0); PG8_SCHED; PG8_LDA(At, 1, 0); PG8_STAGE(PG8_SA(0, 1), a2 + hstepA, voffA);
;             PG8_WAIT_L(8); PG8_BAR; PG8_WAIT_L(0); PG8_MMA(0, 0, At, B0); PG8_BAR; PG8_SCHED;
;             PG8_LDB(B1, 1, 1); PG8_STAGE(PG8_SB(1, 0), b3, voffB);
;             PG8_BAR; PG8_WAIT_L(0); PG8_MMA(0, 1, At, B1); PG8_BAR;
;             PG8_LDA(At, 1, 1); PG8_STAGE(PG8_SA(1, 0), a3, voffA);
	s_add_u32 s48, s18, 0x40000
	s_addc_u32 s49, s19, 0
	s_add_i32 s47, s40, s27
	v_lshl_add_u64 v[128:129], s[48:49], 0, v[150:151]
	s_mov_b32 m0, s47
	s_nop 0
	global_load_lds_dwordx4 v[128:129], off
	v_lshl_add_u64 v[128:129], s[48:49], 0, v[154:155]
	s_add_i32 m0, s47, 0x2000
	s_nop 0
	global_load_lds_dwordx4 v[128:129], off
	s_waitcnt vmcnt(6)
	s_barrier
	v_mfma_f32_16x16x32_bf16 v[52:55], v[210:213], v[144:147], v[52:55]
	v_mfma_f32_16x16x32_bf16 v[48:51], v[218:221], v[144:147], v[48:51]
	v_mfma_f32_16x16x32_bf16 v[36:39], v[210:213], v[186:189], v[36:39]
	v_mfma_f32_16x16x32_bf16 v[32:35], v[218:221], v[186:189], v[32:35]
	v_mfma_f32_16x16x32_bf16 v[20:23], v[210:213], v[194:197], v[20:23]
	v_mfma_f32_16x16x32_bf16 v[16:19], v[218:221], v[194:197], v[16:19]
	v_mfma_f32_16x16x32_bf16 v[4:7], v[210:213], v[202:205], v[4:7]
	v_mfma_f32_16x16x32_bf16 v[0:3], v[218:221], v[202:205], v[0:3]
	v_mfma_f32_16x16x32_bf16 v[52:55], v[214:217], v[182:185], v[52:55]
	v_mfma_f32_16x16x32_bf16 v[48:51], v[222:225], v[182:185], v[48:51]
	v_mfma_f32_16x16x32_bf16 v[36:39], v[214:217], v[190:193], v[36:39]
	v_mfma_f32_16x16x32_bf16 v[32:35], v[222:225], v[190:193], v[32:35]
	v_mfma_f32_16x16x32_bf16 v[20:23], v[214:217], v[198:201], v[20:23]
	v_mfma_f32_16x16x32_bf16 v[16:19], v[222:225], v[198:201], v[16:19]
	v_mfma_f32_16x16x32_bf16 v[4:7], v[214:217], v[206:209], v[4:7]
	v_mfma_f32_16x16x32_bf16 v[0:3], v[222:225], v[206:209], v[0:3]
	s_add_i32 s47, 0, 0x18000
	v_add_u32_e32 v140, s47, v173
	s_barrier
	ds_read_b128 v[128:131], v140
	ds_read_b128 v[132:135], v140 offset:1024
	ds_read_b128 v[136:139], v140 offset:2048
	ds_read_b128 v[140:143], v140 offset:3072
	s_add_u32 s20, s20, 0x40000
	s_addc_u32 s21, s21, 0
	s_mov_b32 m0, s30
	v_lshl_add_u64 v[210:211], s[20:21], 0, v[148:149]
	ds_read_b128 v[144:147], v177 offset:32768
	ds_read_b128 v[182:185], v177 offset:33792
	ds_read_b128 v[186:189], v177 offset:34816
	ds_read_b128 v[190:193], v177 offset:35840
	ds_read_b128 v[194:197], v177 offset:36864
	ds_read_b128 v[198:201], v177 offset:37888
	ds_read_b128 v[202:205], v177 offset:38912
	ds_read_b128 v[206:209], v177 offset:39936
	global_load_lds_dwordx4 v[210:211], off
	v_lshl_add_u64 v[210:211], s[20:21], 0, v[152:153]
	s_mov_b32 m0, s31
	s_nop 0
	global_load_lds_dwordx4 v[210:211], off
	s_waitcnt lgkmcnt(8)
	s_barrier
	s_waitcnt lgkmcnt(0)
	s_waitcnt lgkmcnt(0)
	v_mfma_f32_16x16x32_bf16 v[124:127], v[128:131], v[144:147], v[124:127]
	v_mfma_f32_16x16x32_bf16 v[120:123], v[136:139], v[144:147], v[120:123]
	v_mfma_f32_16x16x32_bf16 v[108:111], v[128:131], v[186:189], v[108:111]
	v_mfma_f32_16x16x32_bf16 v[104:107], v[136:139], v[186:189], v[104:107]
	v_mfma_f32_16x16x32_bf16 v[92:95], v[128:131], v[194:197], v[92:95]
	v_mfma_f32_16x16x32_bf16 v[88:91], v[136:139], v[194:197], v[88:91]
	v_mfma_f32_16x16x32_bf16 v[76:79], v[128:131], v[202:205], v[76:79]
	v_mfma_f32_16x16x32_bf16 v[72:75], v[136:139], v[202:205], v[72:75]
	v_mfma_f32_16x16x32_bf16 v[124:127], v[132:135], v[182:185], v[124:127]
	v_mfma_f32_16x16x32_bf16 v[120:123], v[140:143], v[182:185], v[120:123]
	v_mfma_f32_16x16x32_bf16 v[108:111], v[132:135], v[190:193], v[108:111]
	v_mfma_f32_16x16x32_bf16 v[104:107], v[140:143], v[190:193], v[104:107]
	v_mfma_f32_16x16x32_bf16 v[92:95], v[132:135], v[198:201], v[92:95]
	v_mfma_f32_16x16x32_bf16 v[88:91], v[140:143], v[198:201], v[88:91]
	v_mfma_f32_16x16x32_bf16 v[76:79], v[132:135], v[206:209], v[76:79]
	v_mfma_f32_16x16x32_bf16 v[72:75], v[140:143], v[206:209], v[72:75]
	s_barrier
	s_add_i32 s20, 0, 0x1c000
	s_add_i32 s21, s47, s27
	v_add_u32_e32 v156, s20, v173
	v_lshl_add_u64 v[170:171], v[170:171], 0, s[4:5]
	s_mov_b32 m0, s21
	ds_read_b128 v[210:213], v156
	ds_read_b128 v[214:217], v156 offset:1024
	ds_read_b128 v[218:221], v156 offset:2048
	ds_read_b128 v[222:225], v156 offset:3072
	global_load_lds_dwordx4 v[170:171], off
	v_lshl_add_u64 v[170:171], v[226:227], 0, s[4:5]
	s_add_i32 m0, s21, 0x2000
	s_nop 0
	global_load_lds_dwordx4 v[170:171], off
	s_barrier
	s_waitcnt lgkmcnt(0)
	s_waitcnt lgkmcnt(0)
	v_mfma_f32_16x16x32_bf16 v[116:119], v[210:213], v[144:147], v[116:119]
	v_mfma_f32_16x16x32_bf16 v[112:115], v[218:221], v[144:147], v[112:115]
	v_mfma_f32_16x16x32_bf16 v[100:103], v[210:213], v[186:189], v[100:103]
	v_mfma_f32_16x16x32_bf16 v[96:99], v[218:221], v[186:189], v[96:99]
	v_mfma_f32_16x16x32_bf16 v[84:87], v[210:213], v[194:197], v[84:87]
	v_mfma_f32_16x16x32_bf16 v[80:83], v[218:221], v[194:197], v[80:83]
	v_mfma_f32_16x16x32_bf16 v[68:71], v[210:213], v[202:205], v[68:71]
	v_mfma_f32_16x16x32_bf16 v[64:67], v[218:221], v[202:205], v[64:67]
	v_mfma_f32_16x16x32_bf16 v[116:119], v[214:217], v[182:185], v[116:119]
	v_mfma_f32_16x16x32_bf16 v[112:115], v[222:225], v[182:185], v[112:115]
	v_mfma_f32_16x16x32_bf16 v[100:103], v[214:217], v[190:193], v[100:103]
	v_mfma_f32_16x16x32_bf16 v[96:99], v[222:225], v[190:193], v[96:99]
	v_mfma_f32_16x16x32_bf16 v[84:87], v[214:217], v[198:201], v[84:87]
	v_mfma_f32_16x16x32_bf16 v[80:83], v[222:225], v[198:201], v[80:83]
	v_mfma_f32_16x16x32_bf16 v[68:71], v[214:217], v[206:209], v[68:71]
	v_mfma_f32_16x16x32_bf16 v[64:67], v[222:225], v[206:209], v[64:67]
	s_mov_b32 m0, s37
	v_lshl_add_u64 v[170:171], v[228:229], 0, s[4:5]
	s_barrier
	ds_read_b128 v[144:147], v177 offset:49152
	ds_read_b128 v[182:185], v177 offset:50176
	ds_read_b128 v[186:189], v177 offset:51200
	ds_read_b128 v[190:193], v177 offset:52224
	ds_read_b128 v[194:197], v177 offset:53248
	ds_read_b128 v[198:201], v177 offset:54272
	ds_read_b128 v[202:205], v177 offset:55296
	ds_read_b128 v[206:209], v177 offset:56320
	global_load_lds_dwordx4 v[170:171], off
	v_lshl_add_u64 v[170:171], v[230:231], 0, s[4:5]
	s_mov_b32 m0, s38
	s_nop 0
	global_load_lds_dwordx4 v[170:171], off
	s_barrier
; #define PG8_STAGE(bufoff, gbase, voff) do { _Pragma("unroll") for (int _i = 0; _i < 2; ++_i) \
;         __builtin_amdgcn_global_load_lds((const unsigned*)((const char*)(gbase) + (voff)[_i]), (LAS unsigned*)(lds + (bufoff) + ldsw + _i * 8192), 16, 0, 0); } while (0)
; #define PG8_LDA(dst, b, h) do { _Pragma("unroll") for (int m = 0; m < 4; ++m) _Pragma("unroll") for (int k = 0; k < 2; ++k) dst[m][k] = *(const LAS bf16x8*)(lds + PG8_SA(b, h) + aoff + m * 2048 + k * 1024); } while (0)
; #define PG8_MMA(ai, bj, At, Bt) do { __builtin_amdgcn_s_setprio(1); _Pragma("unroll") for (int m = 0; m < 4; ++m) _Pragma("unroll") for (int n = 0; n < 2; ++n) _Pragma("unroll") for (int k = 0; k < 2; ++k) \
;         acc[ai][bj][m][n] = __builtin_amdgcn_mfma_f32_16x16x32_bf16(Bt[n][k], At[m][k], acc[ai][bj][m][n], 0, 0, 0); __builtin_amdgcn_s_setprio(0); } while (0)
; #define PG8_WAIT_V(n) asm volatile("s_waitcnt vmcnt(" #n ")" ::: "memory")
; #define PG8_WAIT_L(n) asm volatile("s_waitcnt lgkmcnt(" #n ")" ::: "memory")
; #define PG8_BAR __builtin_amdgcn_s_barrier()
; #define PG8_SCHED __builtin_amdgcn_sched_barrier(0)
; template <class Epi, class Sched>
; __device__ __forceinline__ void gemm_phase(const int wv, LAS unsigned char* lds, const Gemm g, const Sched& S, const Epi& E) {
;     ...
;             PG8_LDA(At, 1, 1); PG8_STAGE(PG8_SA(1, 0), a3, voffA);
;             PG8_BAR; PG8_WAIT_L(0); PG8_MMA(1, 0, At, B0); PG8_BAR; PG8_SCHED;
;             PG8_STAGE(PG8_SB(1, 1), b3 + hstepB, voffB);
;             PG8_WAIT_V(6); PG8_BAR; PG8_MMA(1, 1, At, B1); PG8_BAR;
;         }
;     __device__ __forceinline__ void operator()(const f32x4 (&acc)[2][2][4][2], const Unit& u, int wr, int wc, int fr, int fq) const {
;         const int row0 = u.pm * 256 + wr * 64 + fr; const int col0 = u.pn * 256 + wc * 32 + 8 * fq;
;         f32x4 sq[2][4];
; #pragma unroll
;         for (int ai = 0; ai < 2; ++ai)
; #pragma unroll
;             for (int m = 0; m < 4; ++m) sq[ai][m] = *(const f32x4*)(ss2 + (size_t)(row0 + ai * 128 + m * 16) * 16 + 4 * fq);
	s_waitcnt lgkmcnt(0)
	s_waitcnt lgkmcnt(0)
	v_mfma_f32_16x16x32_bf16 v[60:63], v[128:131], v[144:147], v[60:63]
	v_mfma_f32_16x16x32_bf16 v[56:59], v[136:139], v[144:147], v[56:59]
	v_mfma_f32_16x16x32_bf16 v[44:47], v[128:131], v[186:189], v[44:47]
	v_mfma_f32_16x16x32_bf16 v[40:43], v[136:139], v[186:189], v[40:43]
	v_mfma_f32_16x16x32_bf16 v[28:31], v[128:131], v[194:197], v[28:31]
	v_mfma_f32_16x16x32_bf16 v[24:27], v[136:139], v[194:197], v[24:27]
	v_mfma_f32_16x16x32_bf16 v[12:15], v[128:131], v[202:205], v[12:15]
	v_mfma_f32_16x16x32_bf16 v[8:11], v[136:139], v[202:205], v[8:11]
	v_mfma_f32_16x16x32_bf16 v[60:63], v[132:135], v[182:185], v[60:63]
	v_mfma_f32_16x16x32_bf16 v[56:59], v[140:143], v[182:185], v[56:59]
	v_mfma_f32_16x16x32_bf16 v[44:47], v[132:135], v[190:193], v[44:47]
	v_mfma_f32_16x16x32_bf16 v[40:43], v[140:143], v[190:193], v[40:43]
	v_mfma_f32_16x16x32_bf16 v[28:31], v[132:135], v[198:201], v[28:31]
	v_mfma_f32_16x16x32_bf16 v[24:27], v[140:143], v[198:201], v[24:27]
	v_mfma_f32_16x16x32_bf16 v[12:15], v[132:135], v[206:209], v[12:15]
	v_mfma_f32_16x16x32_bf16 v[8:11], v[140:143], v[206:209], v[8:11]
	s_barrier
	s_add_u32 s18, s18, 0x40080
	s_addc_u32 s19, s19, 0
	s_add_i32 s20, s20, s27
	v_lshl_add_u64 v[128:129], s[18:19], 0, v[150:151]
	s_mov_b32 m0, s20
	s_nop 0
	global_load_lds_dwordx4 v[128:129], off
	v_lshl_add_u64 v[128:129], s[18:19], 0, v[154:155]
	s_add_i32 m0, s20, 0x2000
	s_nop 0
	global_load_lds_dwordx4 v[128:129], off
	s_waitcnt vmcnt(6)
	s_barrier
	v_mfma_f32_16x16x32_bf16 v[52:55], v[210:213], v[144:147], v[52:55]
	v_mfma_f32_16x16x32_bf16 v[48:51], v[218:221], v[144:147], v[48:51]
	v_mfma_f32_16x16x32_bf16 v[36:39], v[210:213], v[186:189], v[36:39]
	v_mfma_f32_16x16x32_bf16 v[32:35], v[218:221], v[186:189], v[32:35]
	v_mfma_f32_16x16x32_bf16 v[20:23], v[210:213], v[194:197], v[20:23]
	v_mfma_f32_16x16x32_bf16 v[16:19], v[218:221], v[194:197], v[16:19]
	v_mfma_f32_16x16x32_bf16 v[4:7], v[210:213], v[202:205], v[4:7]
	v_mfma_f32_16x16x32_bf16 v[0:3], v[218:221], v[202:205], v[0:3]
	v_mfma_f32_16x16x32_bf16 v[52:55], v[214:217], v[182:185], v[52:55]
	v_mfma_f32_16x16x32_bf16 v[48:51], v[222:225], v[182:185], v[48:51]
	v_mfma_f32_16x16x32_bf16 v[36:39], v[214:217], v[190:193], v[36:39]
	v_mfma_f32_16x16x32_bf16 v[32:35], v[222:225], v[190:193], v[32:35]
	v_mfma_f32_16x16x32_bf16 v[20:23], v[214:217], v[198:201], v[20:23]
	v_mfma_f32_16x16x32_bf16 v[16:19], v[222:225], v[198:201], v[16:19]
	v_mfma_f32_16x16x32_bf16 v[4:7], v[214:217], v[206:209], v[4:7]
	v_mfma_f32_16x16x32_bf16 v[0:3], v[222:225], v[206:209], v[0:3]
	s_add_i32 s46, s46, 2
	s_add_u32 s16, s16, 0x100
	s_addc_u32 s17, s17, 0
	s_add_u32 s44, s44, 0x100
	s_addc_u32 s45, s45, 0
	s_cmp_gt_u32 s46, 13
	s_barrier
	s_cbranch_scc0 .LBB0_725
	s_lshl_b32 s7, s14, 8
	s_add_i32 s7, s7, s35
	v_or_b32_e32 v132, s7, v172
	v_ashrrev_i32_e32 v133, 31, v132
	v_lshlrev_b64 v[128:129], 6, v[132:133]
	v_lshl_add_u64 v[134:135], v[158:159], 0, v[128:129]
	global_load_dwordx4 v[128:131], v[134:135], off
	v_or_b32_e32 v136, 16, v132
	v_ashrrev_i32_e32 v137, 31, v136
	v_lshlrev_b64 v[136:137], 6, v[136:137]
	v_lshl_add_u64 v[136:137], v[158:159], 0, v[136:137]
	global_load_dwordx4 v[182:185], v[136:137], off
	v_or_b32_e32 v136, 32, v132
	v_or_b32_e32 v138, 48, v132
	v_add_u32_e32 v170, 0x80, v132
	v_lshlrev_b32_e32 v132, 7, v132
	v_ashrrev_i32_e32 v137, 31, v136
	v_ashrrev_i32_e32 v139, 31, v138
	v_and_b32_e32 v156, 0x6780, v132
	v_lshlrev_b64 v[132:133], 6, v[136:137]
	v_lshlrev_b64 v[136:137], 6, v[138:139]
	v_lshl_add_u64 v[132:133], v[158:159], 0, v[132:133]
	v_lshl_add_u64 v[136:137], v[158:159], 0, v[136:137]
	global_load_dwordx4 v[186:189], v[132:133], off
	global_load_dwordx4 v[144:147], v[136:137], off
	v_ashrrev_i32_e32 v171, 31, v170
	v_lshlrev_b64 v[138:139], 6, v[170:171]
	v_add_co_u32_e32 v190, vcc, s33, v134
	s_lshl_b32 s9, s15, 8
	s_nop 0
	v_addc_co_u32_e32 v191, vcc, 0, v135, vcc
	s_or_b32 s9, s9, s36
	s_ashr_i32 s14, s7, 2
	s_ashr_i32 s7, s9, 6
	s_and_b32 s16, s14, 0xffffffc0
	s_add_i32 s14, s16, s7
	s_ashr_i32 s15, s14, 31
	s_lshl_b64 s[14:15], s[14:15], 15
	s_add_u32 s14, s2, s14
	v_lshl_add_u64 v[138:139], v[158:159], 0, v[138:139]
	s_addc_u32 s15, s3, s15
	v_mov_b32_e32 v169, v157
	s_or_b32 s9, s7, 2
	s_add_i32 s16, s16, s9
	s_ashr_i32 s17, s16, 31
	s_lshl_b64 s[16:17], s[16:17], 15
	s_add_u32 s16, s2, s16
	s_addc_u32 s17, s3, s17
	s_mov_b64 s[18:19], s[12:13]
	s_waitcnt vmcnt(0)
	v_mov_b32_e32 v132, v129
	v_mov_b32_e32 v133, v130
	v_mov_b32_e32 v129, v131
	v_pk_add_f32 v[128:129], v[132:133], v[128:129]
	v_mov_b32_e32 v193, v184
	v_add_f32_e32 v171, v128, v129
	ds_bpermute_b32 v192, v174, v171
	global_load_dwordx4 v[140:143], v[138:139], off
	s_nop 0
	global_load_dwordx4 v[136:139], v[190:191], off offset:1024
	global_load_dwordx4 v[132:135], v[190:191], off offset:2048
	global_load_dwordx4 v[128:131], v[190:191], off offset:3072
	v_lshl_add_u64 v[190:191], s[14:15], 0, v[156:157]
	v_lshl_add_u64 v[190:191], v[190:191], 0, v[168:169]
	s_waitcnt lgkmcnt(0)
	v_add_f32_e32 v171, v171, v192
	ds_bpermute_b32 v192, v175, v171
	s_waitcnt lgkmcnt(0)
; __device__ __forceinline__ float shx(float v, int lane, int mask) { return __int_as_float(__builtin_amdgcn_ds_bpermute((lane ^ mask) << 2, __float_as_int(v))); }
; __device__ __forceinline__ unsigned cvt_pk_bf16(float lo, float hi) { unsigned r; asm volatile("v_cvt_pk_bf16_f32 %0, %1, %2" : "=v"(r) : "v"(lo), "v"(hi)); return r; }
;     __device__ __forceinline__ void operator()(const f32x4 (&acc)[2][2][4][2], const Unit& u, int wr, int wc, int fr, int fq) const {
;     ...
;             for (int m = 0; m < 4; ++m) {
;                 const int row = row0 + ai * 128 + m * 16;
;                 float ss = (sq[ai][m][0] + sq[ai][m][1]) + (sq[ai][m][2] + sq[ai][m][3]);
;                 ss += shx(ss, fq * 16 + fr, 16); ss += shx(ss, fq * 16 + fr, 32);
;                 const float rs = rsqrtf(ss * (1.0f / 1024.0f) + EPS);
; #pragma unroll
;                 for (int bj = 0; bj < 2; ++bj) {
;                     f32x4 v0 = acc[ai][bj][m][0] * rs, v1 = acc[ai][bj][m][1] * rs;
; #pragma unroll
;                     for (int j = 0; j < 4; ++j) { const float a = fmaxf(v0[j], 0.f), b = fmaxf(v1[j], 0.f); v0[j] = a * a; v1[j] = b * b; }
;                     u32x4 w; w.x = cvt_pk_bf16(v0[0], v0[1]); w.y = cvt_pk_bf16(v0[2], v0[3]); w.z = cvt_pk_bf16(v1[0], v1[1]); w.w = cvt_pk_bf16(v1[2], v1[3]);
;                     { const int col = col0 + bj * 128;
;                       *(u32x4*)(H + ((size_t)((row >> 8) * (DFF / 64) + (col >> 6)) * 256 + (row & 255)) * 64 + (col & 63)) = w; }
;                 }
	v_add_f32_e32 v171, v171, v192
	v_fmamk_f32 v171, v171, 0x3a800000, v181
	v_mul_f32_e32 v192, 0x4b800000, v171
	v_cmp_gt_f32_e32 vcc, s41, v171
	s_nop 1
	v_cndmask_b32_e32 v171, v171, v192, vcc
	v_rsq_f32_e32 v171, v171
	v_mov_b32_e32 v192, v183
	v_mov_b32_e32 v183, v185
	v_mul_f32_e32 v184, 0x45800000, v171
	v_cndmask_b32_e32 v184, v171, v184, vcc
	v_pk_mul_f32 v[126:127], v[126:127], v[184:185] op_sel_hi:[1,0]
	v_pk_mul_f32 v[124:125], v[124:125], v[184:185] op_sel_hi:[1,0]
	v_pk_mul_f32 v[122:123], v[122:123], v[184:185] op_sel_hi:[1,0]
	v_pk_mul_f32 v[120:121], v[120:121], v[184:185] op_sel_hi:[1,0]
	v_pk_mul_f32 v[114:115], v[114:115], v[184:185] op_sel_hi:[1,0]
	v_pk_mul_f32 v[112:113], v[112:113], v[184:185] op_sel_hi:[1,0]
	v_pk_mul_f32 v[116:117], v[116:117], v[184:185] op_sel_hi:[1,0]
	v_max_f32_e32 v124, 0, v124
	v_max_f32_e32 v120, 0, v120
	v_max_f32_e32 v125, 0, v125
	v_max_f32_e32 v121, 0, v121
	v_max_f32_e32 v126, 0, v126
	v_max_f32_e32 v122, 0, v122
	v_max_f32_e32 v127, 0, v127
	v_max_f32_e32 v123, 0, v123
	v_max_f32_e32 v112, 0, v112
	v_max_f32_e32 v113, 0, v113
	v_max_f32_e32 v114, 0, v114
	v_max_f32_e32 v115, 0, v115
	v_pk_mul_f32 v[118:119], v[118:119], v[184:185] op_sel_hi:[1,0]
	v_max_f32_e32 v116, 0, v116
	v_mul_f32_e32 v124, v124, v124
	v_mul_f32_e32 v120, v120, v120
	v_mul_f32_e32 v125, v125, v125
	v_mul_f32_e32 v121, v121, v121
	v_mul_f32_e32 v126, v126, v126
	v_mul_f32_e32 v122, v122, v122
	v_mul_f32_e32 v127, v127, v127
	v_mul_f32_e32 v123, v123, v123
	v_mul_f32_e32 v171, v112, v112
	v_mul_f32_e32 v184, v113, v113
	v_mul_f32_e32 v185, v114, v114
	v_mul_f32_e32 v194, v115, v115
	v_cvt_pk_bf16_f32 v112, v124, v125
	v_cvt_pk_bf16_f32 v113, v126, v127
	v_cvt_pk_bf16_f32 v114, v120, v121
	v_cvt_pk_bf16_f32 v115, v122, v123
	v_max_f32_e32 v117, 0, v117
	v_mul_f32_e32 v116, v116, v116
	global_store_dwordx4 v[190:191], v[112:115], off
	v_mul_f32_e32 v117, v117, v117
	v_max_f32_e32 v118, 0, v118
	v_pk_add_f32 v[114:115], v[192:193], v[182:183]
	v_cvt_pk_bf16_f32 v112, v116, v117
	v_max_f32_e32 v119, 0, v119
	v_add_f32_e32 v116, v114, v115
	ds_bpermute_b32 v117, v174, v116
	v_mul_f32_e32 v118, v118, v118
	v_mul_f32_e32 v119, v119, v119
	v_cvt_pk_bf16_f32 v113, v118, v119
	v_cvt_pk_bf16_f32 v114, v171, v184
	s_waitcnt lgkmcnt(0)
	v_add_f32_e32 v116, v116, v117
	ds_bpermute_b32 v117, v175, v116
	v_cvt_pk_bf16_f32 v115, v185, v194
	s_waitcnt lgkmcnt(0)
	v_add_f32_e32 v116, v116, v117
	v_fmamk_f32 v116, v116, 0x3a800000, v181
	v_mul_f32_e32 v117, 0x4b800000, v116
	v_cmp_gt_f32_e32 vcc, s41, v116
	s_nop 1
	v_cndmask_b32_e32 v116, v116, v117, vcc
	v_rsq_f32_e32 v118, v116
	v_lshl_add_u64 v[116:117], s[16:17], 0, v[156:157]
	v_lshl_add_u64 v[116:117], v[116:117], 0, v[168:169]
	global_store_dwordx4 v[116:117], v[112:115], off
	s_nop 1
	v_mul_f32_e32 v112, 0x45800000, v118
	v_cndmask_b32_e32 v112, v118, v112, vcc
	v_pk_mul_f32 v[104:105], v[104:105], v[112:113] op_sel_hi:[1,0]
	v_pk_mul_f32 v[108:109], v[108:109], v[112:113] op_sel_hi:[1,0]
	v_pk_mul_f32 v[106:107], v[106:107], v[112:113] op_sel_hi:[1,0]
	v_max_f32_e32 v104, 0, v104
	v_pk_mul_f32 v[110:111], v[110:111], v[112:113] op_sel_hi:[1,0]
	v_mul_f32_e32 v113, v104, v104
	v_max_f32_e32 v104, 0, v109
	v_max_f32_e32 v105, 0, v105
	v_max_f32_e32 v106, 0, v106
	v_max_f32_e32 v108, 0, v108
	v_mul_f32_e32 v104, v104, v104
	v_mul_f32_e32 v109, v105, v105
	v_max_f32_e32 v105, 0, v110
	v_mul_f32_e32 v110, v106, v106
	v_max_f32_e32 v106, 0, v111
	v_max_f32_e32 v107, 0, v107
	v_pk_mul_f32 v[96:97], v[96:97], v[112:113] op_sel_hi:[1,0]
	v_mul_f32_e32 v108, v108, v108
	v_mul_f32_e32 v105, v105, v105
	v_mul_f32_e32 v106, v106, v106
	v_mul_f32_e32 v107, v107, v107
	v_cvt_pk_bf16_f32 v104, v108, v104
	v_pk_mul_f32 v[100:101], v[100:101], v[112:113] op_sel_hi:[1,0]
	v_max_f32_e32 v96, 0, v96
	v_cvt_pk_bf16_f32 v105, v105, v106
	v_cvt_pk_bf16_f32 v106, v113, v109
	v_cvt_pk_bf16_f32 v107, v110, v107
	global_store_dwordx4 v[190:191], v[104:107], off offset:2048
	v_max_f32_e32 v97, 0, v97
	v_pk_mul_f32 v[98:99], v[98:99], v[112:113] op_sel_hi:[1,0]
	v_mul_f32_e32 v104, v96, v96
	v_max_f32_e32 v96, 0, v101
	v_mul_f32_e32 v101, v96, v96
	v_mul_f32_e32 v105, v97, v97
	v_mov_b32_e32 v96, v187
	v_mov_b32_e32 v97, v188
	v_mov_b32_e32 v187, v189
	v_pk_add_f32 v[96:97], v[96:97], v[186:187]
	v_pk_mul_f32 v[102:103], v[102:103], v[112:113] op_sel_hi:[1,0]
	v_add_f32_e32 v96, v96, v97
	ds_bpermute_b32 v97, v174, v96
	v_max_f32_e32 v98, 0, v98
	v_mul_f32_e32 v106, v98, v98
	v_max_f32_e32 v98, 0, v103
	v_max_f32_e32 v100, 0, v100
	s_waitcnt lgkmcnt(0)
	v_add_f32_e32 v103, v96, v97
	ds_bpermute_b32 v107, v175, v103
	v_mul_f32_e32 v97, v98, v98
	v_mul_f32_e32 v100, v100, v100
	v_cvt_pk_bf16_f32 v96, v100, v101
	v_max_f32_e32 v99, 0, v99
	s_waitcnt lgkmcnt(0)
; __device__ __forceinline__ float shx(float v, int lane, int mask) { return __int_as_float(__builtin_amdgcn_ds_bpermute((lane ^ mask) << 2, __float_as_int(v))); }
; __device__ __forceinline__ unsigned cvt_pk_bf16(float lo, float hi) { unsigned r; asm volatile("v_cvt_pk_bf16_f32 %0, %1, %2" : "=v"(r) : "v"(lo), "v"(hi)); return r; }
;     __device__ __forceinline__ void operator()(const f32x4 (&acc)[2][2][4][2], const Unit& u, int wr, int wc, int fr, int fq) const {
;     ...
;             for (int m = 0; m < 4; ++m) {
;                 const int row = row0 + ai * 128 + m * 16;
;                 float ss = (sq[ai][m][0] + sq[ai][m][1]) + (sq[ai][m][2] + sq[ai][m][3]);
;                 ss += shx(ss, fq * 16 + fr, 16); ss += shx(ss, fq * 16 + fr, 32);
;                 const float rs = rsqrtf(ss * (1.0f / 1024.0f) + EPS);
; #pragma unroll
;                 for (int bj = 0; bj < 2; ++bj) {
;                     f32x4 v0 = acc[ai][bj][m][0] * rs, v1 = acc[ai][bj][m][1] * rs;
; #pragma unroll
;                     for (int j = 0; j < 4; ++j) { const float a = fmaxf(v0[j], 0.f), b = fmaxf(v1[j], 0.f); v0[j] = a * a; v1[j] = b * b; }
;                     u32x4 w; w.x = cvt_pk_bf16(v0[0], v0[1]); w.y = cvt_pk_bf16(v0[2], v0[3]); w.z = cvt_pk_bf16(v1[0], v1[1]); w.w = cvt_pk_bf16(v1[2], v1[3]);
;                     { const int col = col0 + bj * 128;
;                       *(u32x4*)(H + ((size_t)((row >> 8) * (DFF / 64) + (col >> 6)) * 256 + (row & 255)) * 64 + (col & 63)) = w; }
;                 }
	v_add_f32_e32 v98, v103, v107
	v_fmamk_f32 v98, v98, 0x3a800000, v181
	v_mul_f32_e32 v100, 0x4b800000, v98
	v_cmp_gt_f32_e32 vcc, s41, v98
	v_max_f32_e32 v102, 0, v102
	v_mul_f32_e32 v99, v99, v99
	v_cndmask_b32_e32 v98, v98, v100, vcc
	v_rsq_f32_e32 v100, v98
	v_mul_f32_e32 v102, v102, v102
	v_cvt_pk_bf16_f32 v97, v102, v97
	v_cvt_pk_bf16_f32 v98, v104, v105
	v_cvt_pk_bf16_f32 v99, v106, v99
	global_store_dwordx4 v[116:117], v[96:99], off offset:2048
	s_nop 1
	v_mul_f32_e32 v96, 0x45800000, v100
	v_cndmask_b32_e32 v96, v100, v96, vcc
	v_pk_mul_f32 v[90:91], v[90:91], v[96:97] op_sel_hi:[1,0]
	v_pk_mul_f32 v[88:89], v[88:89], v[96:97] op_sel_hi:[1,0]
	v_pk_mul_f32 v[94:95], v[94:95], v[96:97] op_sel_hi:[1,0]
	v_pk_mul_f32 v[92:93], v[92:93], v[96:97] op_sel_hi:[1,0]
	v_max_f32_e32 v88, 0, v88
	v_max_f32_e32 v89, 0, v89
	v_max_f32_e32 v90, 0, v90
	v_max_f32_e32 v92, 0, v92
	v_mul_f32_e32 v97, v88, v88
	v_max_f32_e32 v88, 0, v93
	v_mul_f32_e32 v93, v89, v89
	v_max_f32_e32 v89, 0, v94
	v_mul_f32_e32 v94, v90, v90
	v_max_f32_e32 v90, 0, v95
	v_mul_f32_e32 v92, v92, v92
	v_mul_f32_e32 v88, v88, v88
	v_mul_f32_e32 v89, v89, v89
	v_max_f32_e32 v91, 0, v91
	v_mul_f32_e32 v90, v90, v90
	v_mul_f32_e32 v91, v91, v91
	v_cvt_pk_bf16_f32 v88, v92, v88
	v_cvt_pk_bf16_f32 v89, v89, v90
	v_cvt_pk_bf16_f32 v90, v97, v93
	v_or_b32_e32 v92, 0x1000, v156
	v_mov_b32_e32 v93, v157
	v_cvt_pk_bf16_f32 v91, v94, v91
	v_lshl_add_u64 v[94:95], s[14:15], 0, v[92:93]
	v_pk_mul_f32 v[80:81], v[80:81], v[96:97] op_sel_hi:[1,0]
	v_lshl_add_u64 v[94:95], v[94:95], 0, v[168:169]
	v_pk_mul_f32 v[84:85], v[84:85], v[96:97] op_sel_hi:[1,0]
	v_max_f32_e32 v80, 0, v80
	global_store_dwordx4 v[94:95], v[88:91], off
	v_pk_mul_f32 v[86:87], v[86:87], v[96:97] op_sel_hi:[1,0]
	v_pk_mul_f32 v[82:83], v[82:83], v[96:97] op_sel_hi:[1,0]
	v_mul_f32_e32 v88, v80, v80
	v_max_f32_e32 v80, 0, v85
	v_max_f32_e32 v81, 0, v81
	v_mul_f32_e32 v85, v80, v80
	v_mul_f32_e32 v89, v81, v81
	v_max_f32_e32 v80, 0, v86
	v_max_f32_e32 v81, 0, v82
	v_mul_f32_e32 v82, v80, v80
	v_mul_f32_e32 v86, v81, v81
	v_mov_b32_e32 v80, v145
	v_mov_b32_e32 v81, v146
	v_mov_b32_e32 v145, v147
	v_pk_add_f32 v[80:81], v[80:81], v[144:145]
	v_max_f32_e32 v84, 0, v84
	v_add_f32_e32 v80, v80, v81
	ds_bpermute_b32 v81, v174, v80
	v_mul_f32_e32 v84, v84, v84
	v_max_f32_e32 v83, 0, v83
	v_max_f32_e32 v87, 0, v87
	v_mul_f32_e32 v83, v83, v83
	s_waitcnt lgkmcnt(0)
	v_add_f32_e32 v90, v80, v81
	ds_bpermute_b32 v91, v175, v90
	v_cvt_pk_bf16_f32 v80, v84, v85
	v_mul_f32_e32 v87, v87, v87
	v_cvt_pk_bf16_f32 v81, v82, v87
	v_cvt_pk_bf16_f32 v82, v88, v89
	s_waitcnt lgkmcnt(0)
	v_add_f32_e32 v84, v90, v91
	v_fmamk_f32 v84, v84, 0x3a800000, v181
	v_mul_f32_e32 v85, 0x4b800000, v84
	v_cmp_gt_f32_e32 vcc, s41, v84
	v_cvt_pk_bf16_f32 v83, v86, v83
	v_or_b32_e32 v156, 0x1800, v156
	s_nop 0
	v_cndmask_b32_e32 v84, v84, v85, vcc
	v_rsq_f32_e32 v86, v84
	v_lshl_add_u64 v[84:85], s[16:17], 0, v[92:93]
	v_lshl_add_u64 v[84:85], v[84:85], 0, v[168:169]
	global_store_dwordx4 v[84:85], v[80:83], off
	s_nop 1
	v_mul_f32_e32 v80, 0x45800000, v86
	v_cndmask_b32_e32 v80, v86, v80, vcc
	v_pk_mul_f32 v[74:75], v[74:75], v[80:81] op_sel_hi:[1,0]
	v_pk_mul_f32 v[72:73], v[72:73], v[80:81] op_sel_hi:[1,0]
	v_pk_mul_f32 v[78:79], v[78:79], v[80:81] op_sel_hi:[1,0]
	v_pk_mul_f32 v[76:77], v[76:77], v[80:81] op_sel_hi:[1,0]
	v_max_f32_e32 v72, 0, v72
	v_max_f32_e32 v73, 0, v73
	v_max_f32_e32 v74, 0, v74
	v_max_f32_e32 v76, 0, v76
	v_mul_f32_e32 v81, v72, v72
	v_max_f32_e32 v72, 0, v77
	v_mul_f32_e32 v77, v73, v73
	v_max_f32_e32 v73, 0, v78
	v_mul_f32_e32 v78, v74, v74
	v_max_f32_e32 v74, 0, v79
	v_mul_f32_e32 v76, v76, v76
	v_mul_f32_e32 v72, v72, v72
	v_mul_f32_e32 v73, v73, v73
	v_mul_f32_e32 v74, v74, v74
	v_max_f32_e32 v75, 0, v75
	v_cvt_pk_bf16_f32 v72, v76, v72
	v_cvt_pk_bf16_f32 v73, v73, v74
	v_cvt_pk_bf16_f32 v74, v81, v77
	v_lshl_add_u64 v[76:77], s[14:15], 0, v[156:157]
	v_pk_mul_f32 v[64:65], v[64:65], v[80:81] op_sel_hi:[1,0]
	v_mul_f32_e32 v75, v75, v75
	v_lshl_add_u64 v[76:77], v[76:77], 0, v[168:169]
	v_pk_mul_f32 v[68:69], v[68:69], v[80:81] op_sel_hi:[1,0]
	v_max_f32_e32 v64, 0, v64
	v_cvt_pk_bf16_f32 v75, v78, v75
	global_store_dwordx4 v[76:77], v[72:75], off
	v_pk_mul_f32 v[70:71], v[70:71], v[80:81] op_sel_hi:[1,0]
	v_pk_mul_f32 v[66:67], v[66:67], v[80:81] op_sel_hi:[1,0]
	v_mul_f32_e32 v72, v64, v64
	v_max_f32_e32 v64, 0, v69
	v_max_f32_e32 v65, 0, v65
	v_mul_f32_e32 v69, v64, v64
	v_mul_f32_e32 v73, v65, v65
	v_max_f32_e32 v64, 0, v70
	v_max_f32_e32 v65, 0, v66
	v_mul_f32_e32 v66, v64, v64
	v_mul_f32_e32 v70, v65, v65
	s_waitcnt vmcnt(10)
	v_mov_b32_e32 v64, v141
	v_mov_b32_e32 v65, v142
	v_mov_b32_e32 v141, v143
	v_pk_add_f32 v[64:65], v[64:65], v[140:141]
	v_max_f32_e32 v71, 0, v71
	v_add_f32_e32 v74, v64, v65
	ds_bpermute_b32 v75, v174, v74
	v_mul_f32_e32 v65, v71, v71
	v_max_f32_e32 v67, 0, v67
	v_max_f32_e32 v68, 0, v68
	v_mul_f32_e32 v67, v67, v67
	s_waitcnt lgkmcnt(0)
	v_add_f32_e32 v71, v74, v75
	ds_bpermute_b32 v74, v175, v71
	v_mul_f32_e32 v68, v68, v68
	v_cvt_pk_bf16_f32 v64, v68, v69
	v_cvt_pk_bf16_f32 v65, v66, v65
	v_cvt_pk_bf16_f32 v66, v72, v73
	v_cvt_pk_bf16_f32 v67, v70, v67
	s_waitcnt lgkmcnt(0)
; __device__ __forceinline__ float shx(float v, int lane, int mask) { return __int_as_float(__builtin_amdgcn_ds_bpermute((lane ^ mask) << 2, __float_as_int(v))); }
; __device__ __forceinline__ unsigned cvt_pk_bf16(float lo, float hi) { unsigned r; asm volatile("v_cvt_pk_bf16_f32 %0, %1, %2" : "=v"(r) : "v"(lo), "v"(hi)); return r; }
;     __device__ __forceinline__ void operator()(const f32x4 (&acc)[2][2][4][2], const Unit& u, int wr, int wc, int fr, int fq) const {
;     ...
;             for (int m = 0; m < 4; ++m) {
;                 const int row = row0 + ai * 128 + m * 16;
;                 float ss = (sq[ai][m][0] + sq[ai][m][1]) + (sq[ai][m][2] + sq[ai][m][3]);
;                 ss += shx(ss, fq * 16 + fr, 16); ss += shx(ss, fq * 16 + fr, 32);
;                 const float rs = rsqrtf(ss * (1.0f / 1024.0f) + EPS);
; #pragma unroll
;                 for (int bj = 0; bj < 2; ++bj) {
;                     f32x4 v0 = acc[ai][bj][m][0] * rs, v1 = acc[ai][bj][m][1] * rs;
; #pragma unroll
;                     for (int j = 0; j < 4; ++j) { const float a = fmaxf(v0[j], 0.f), b = fmaxf(v1[j], 0.f); v0[j] = a * a; v1[j] = b * b; }
;                     u32x4 w; w.x = cvt_pk_bf16(v0[0], v0[1]); w.y = cvt_pk_bf16(v0[2], v0[3]); w.z = cvt_pk_bf16(v1[0], v1[1]); w.w = cvt_pk_bf16(v1[2], v1[3]);
;                     { const int col = col0 + bj * 128;
;                       *(u32x4*)(H + ((size_t)((row >> 8) * (DFF / 64) + (col >> 6)) * 256 + (row & 255)) * 64 + (col & 63)) = w; }
;                 }
	v_add_f32_e32 v70, v71, v74
	v_fmamk_f32 v70, v70, 0x3a800000, v181
	v_mul_f32_e32 v71, 0x4b800000, v70
	v_cmp_gt_f32_e32 vcc, s41, v70
	v_lshl_add_u64 v[68:69], s[16:17], 0, v[156:157]
	v_lshl_add_u64 v[68:69], v[68:69], 0, v[168:169]
	v_cndmask_b32_e32 v70, v70, v71, vcc
	v_rsq_f32_e32 v70, v70
	global_store_dwordx4 v[68:69], v[64:67], off
	s_mov_b32 s15, s6
	s_mov_b32 s14, s8
	v_ashrrev_i32_e32 v64, 2, v170
	v_and_b32_e32 v65, 0xffffffc0, v64
	v_mul_f32_e32 v64, 0x45800000, v70
	v_cndmask_b32_e32 v64, v70, v64, vcc
	v_pk_mul_f32 v[60:61], v[60:61], v[64:65] op_sel_hi:[1,0]
	v_pk_mul_f32 v[58:59], v[58:59], v[64:65] op_sel_hi:[1,0]
	v_pk_mul_f32 v[56:57], v[56:57], v[64:65] op_sel_hi:[1,0]
	v_pk_mul_f32 v[62:63], v[62:63], v[64:65] op_sel_hi:[1,0]
	v_max_f32_e32 v60, 0, v60
	v_max_f32_e32 v56, 0, v56
	v_max_f32_e32 v58, 0, v58
	v_mul_f32_e32 v60, v60, v60
	v_mul_f32_e32 v56, v56, v56
	v_max_f32_e32 v61, 0, v61
	v_max_f32_e32 v57, 0, v57
	v_max_f32_e32 v62, 0, v62
	v_mul_f32_e32 v66, v58, v58
	v_max_f32_e32 v58, 0, v63
	v_max_f32_e32 v59, 0, v59
	v_mul_f32_e32 v61, v61, v61
	v_mul_f32_e32 v57, v57, v57
	v_mul_f32_e32 v62, v62, v62
	v_mul_f32_e32 v63, v58, v58
	v_mul_f32_e32 v67, v59, v59
	v_cvt_pk_bf16_f32 v58, v60, v61
	v_cvt_pk_bf16_f32 v59, v62, v63
	v_cvt_pk_bf16_f32 v60, v56, v57
	v_add_u32_e32 v56, s7, v65
	v_ashrrev_i32_e32 v57, 31, v56
	v_lshlrev_b64 v[56:57], 15, v[56:57]
	v_lshlrev_b32_e32 v62, 7, v170
	v_lshl_add_u64 v[56:57], s[2:3], 0, v[56:57]
	v_and_b32_e32 v156, 0x6780, v62
	v_lshl_add_u64 v[62:63], v[56:57], 0, v[156:157]
	v_pk_mul_f32 v[48:49], v[48:49], v[64:65] op_sel_hi:[1,0]
	v_lshl_add_u64 v[62:63], v[62:63], 0, v[168:169]
	v_pk_mul_f32 v[52:53], v[52:53], v[64:65] op_sel_hi:[1,0]
	v_max_f32_e32 v48, 0, v48
	v_cvt_pk_bf16_f32 v61, v66, v67
	global_store_dwordx4 v[62:63], v[58:61], off
	v_pk_mul_f32 v[54:55], v[54:55], v[64:65] op_sel_hi:[1,0]
	v_pk_mul_f32 v[50:51], v[50:51], v[64:65] op_sel_hi:[1,0]
	v_mul_f32_e32 v58, v48, v48
	v_max_f32_e32 v48, 0, v53
	v_max_f32_e32 v49, 0, v49
	v_mul_f32_e32 v53, v48, v48
	v_mul_f32_e32 v59, v49, v49
	v_max_f32_e32 v48, 0, v54
	v_max_f32_e32 v49, 0, v50
	v_mul_f32_e32 v54, v48, v48
	v_mul_f32_e32 v60, v49, v49
	v_max_f32_e32 v48, 0, v55
	v_max_f32_e32 v49, 0, v51
	v_mul_f32_e32 v51, v48, v48
	v_mul_f32_e32 v55, v49, v49
	s_waitcnt vmcnt(11)
	v_mov_b32_e32 v48, v137
	v_mov_b32_e32 v49, v138
	v_mov_b32_e32 v137, v139
	v_pk_add_f32 v[48:49], v[48:49], v[136:137]
	v_max_f32_e32 v52, 0, v52
	v_add_f32_e32 v48, v48, v49
	ds_bpermute_b32 v49, v174, v48
	v_mul_f32_e32 v52, v52, v52
	v_cvt_pk_bf16_f32 v50, v52, v53
	v_cvt_pk_bf16_f32 v51, v54, v51
	v_cvt_pk_bf16_f32 v52, v58, v59
	s_waitcnt lgkmcnt(0)
	v_add_f32_e32 v54, v48, v49
	v_cvt_pk_bf16_f32 v53, v60, v55
	ds_bpermute_b32 v55, v175, v54
	v_add_u32_e32 v48, s9, v65
	v_ashrrev_i32_e32 v49, 31, v48
	v_lshlrev_b64 v[48:49], 15, v[48:49]
	v_lshl_add_u64 v[48:49], s[2:3], 0, v[48:49]
	s_waitcnt lgkmcnt(0)
	v_add_f32_e32 v54, v54, v55
	v_fmamk_f32 v54, v54, 0x3a800000, v181
	v_mul_f32_e32 v55, 0x4b800000, v54
	v_cmp_gt_f32_e32 vcc, s41, v54
	s_mov_b64 s[16:17], s[10:11]
	s_nop 0
	v_cndmask_b32_e32 v54, v54, v55, vcc
	v_rsq_f32_e32 v58, v54
	v_lshl_add_u64 v[54:55], v[48:49], 0, v[156:157]
	v_lshl_add_u64 v[54:55], v[54:55], 0, v[168:169]
	global_store_dwordx4 v[54:55], v[50:53], off
	s_nop 1
	v_mul_f32_e32 v50, 0x45800000, v58
	v_cndmask_b32_e32 v50, v58, v50, vcc
	v_pk_mul_f32 v[40:41], v[40:41], v[50:51] op_sel_hi:[1,0]
	v_pk_mul_f32 v[44:45], v[44:45], v[50:51] op_sel_hi:[1,0]
	v_pk_mul_f32 v[42:43], v[42:43], v[50:51] op_sel_hi:[1,0]
	v_max_f32_e32 v40, 0, v40
	v_pk_mul_f32 v[46:47], v[46:47], v[50:51] op_sel_hi:[1,0]
	v_mul_f32_e32 v51, v40, v40
	v_max_f32_e32 v40, 0, v45
	v_max_f32_e32 v41, 0, v41
	v_max_f32_e32 v42, 0, v42
	v_max_f32_e32 v44, 0, v44
	v_mul_f32_e32 v40, v40, v40
	v_mul_f32_e32 v45, v41, v41
	v_max_f32_e32 v41, 0, v46
	v_mul_f32_e32 v46, v42, v42
	v_max_f32_e32 v42, 0, v47
	v_max_f32_e32 v43, 0, v43
	v_pk_mul_f32 v[32:33], v[32:33], v[50:51] op_sel_hi:[1,0]
	v_mul_f32_e32 v44, v44, v44
	v_mul_f32_e32 v41, v41, v41
	v_mul_f32_e32 v42, v42, v42
	v_mul_f32_e32 v43, v43, v43
	v_cvt_pk_bf16_f32 v40, v44, v40
	v_pk_mul_f32 v[36:37], v[36:37], v[50:51] op_sel_hi:[1,0]
	v_max_f32_e32 v32, 0, v32
	v_cvt_pk_bf16_f32 v41, v41, v42
	v_cvt_pk_bf16_f32 v42, v51, v45
	v_cvt_pk_bf16_f32 v43, v46, v43
	global_store_dwordx4 v[62:63], v[40:43], off offset:2048
	v_max_f32_e32 v33, 0, v33
	v_pk_mul_f32 v[34:35], v[34:35], v[50:51] op_sel_hi:[1,0]
	v_mul_f32_e32 v40, v32, v32
	v_max_f32_e32 v32, 0, v37
	v_mul_f32_e32 v37, v32, v32
	v_mul_f32_e32 v41, v33, v33
	s_waitcnt vmcnt(12)
	v_mov_b32_e32 v32, v133
	v_mov_b32_e32 v33, v134
	v_mov_b32_e32 v133, v135
	v_pk_add_f32 v[32:33], v[32:33], v[132:133]
	v_pk_mul_f32 v[38:39], v[38:39], v[50:51] op_sel_hi:[1,0]
	v_add_f32_e32 v32, v32, v33
	ds_bpermute_b32 v33, v174, v32
	v_max_f32_e32 v34, 0, v34
	v_mul_f32_e32 v42, v34, v34
	v_max_f32_e32 v34, 0, v39
	v_max_f32_e32 v36, 0, v36
	s_waitcnt lgkmcnt(0)
	v_add_f32_e32 v39, v32, v33
	ds_bpermute_b32 v43, v175, v39
	v_mul_f32_e32 v33, v34, v34
	v_mul_f32_e32 v36, v36, v36
	v_cvt_pk_bf16_f32 v32, v36, v37
	v_max_f32_e32 v35, 0, v35
	s_waitcnt lgkmcnt(0)
; __device__ __forceinline__ float shx(float v, int lane, int mask) { return __int_as_float(__builtin_amdgcn_ds_bpermute((lane ^ mask) << 2, __float_as_int(v))); }
; __device__ __forceinline__ unsigned cvt_pk_bf16(float lo, float hi) { unsigned r; asm volatile("v_cvt_pk_bf16_f32 %0, %1, %2" : "=v"(r) : "v"(lo), "v"(hi)); return r; }
; #define PG8_WAIT_V(n) asm volatile("s_waitcnt vmcnt(" #n ")" ::: "memory")
; #define PG8_BAR __builtin_amdgcn_s_barrier()
; template <class Epi, class Sched>
; __device__ __forceinline__ void gemm_phase(const int wv, LAS unsigned char* lds, const Gemm g, const Sched& S, const Epi& E) {
;     ...
;     PG8_WAIT_V(0);
;     if (wr == 0) PG8_BAR;
;     PG8_BAR;
;     __device__ __forceinline__ void operator()(const f32x4 (&acc)[2][2][4][2], const Unit& u, int wr, int wc, int fr, int fq) const {
;     ...
;             for (int m = 0; m < 4; ++m) {
;                 const int row = row0 + ai * 128 + m * 16;
;                 float ss = (sq[ai][m][0] + sq[ai][m][1]) + (sq[ai][m][2] + sq[ai][m][3]);
;                 ss += shx(ss, fq * 16 + fr, 16); ss += shx(ss, fq * 16 + fr, 32);
;                 const float rs = rsqrtf(ss * (1.0f / 1024.0f) + EPS);
; #pragma unroll
;                 for (int bj = 0; bj < 2; ++bj) {
;                     f32x4 v0 = acc[ai][bj][m][0] * rs, v1 = acc[ai][bj][m][1] * rs;
; #pragma unroll
;                     for (int j = 0; j < 4; ++j) { const float a = fmaxf(v0[j], 0.f), b = fmaxf(v1[j], 0.f); v0[j] = a * a; v1[j] = b * b; }
;                     u32x4 w; w.x = cvt_pk_bf16(v0[0], v0[1]); w.y = cvt_pk_bf16(v0[2], v0[3]); w.z = cvt_pk_bf16(v1[0], v1[1]); w.w = cvt_pk_bf16(v1[2], v1[3]);
;                     { const int col = col0 + bj * 128;
;                       *(u32x4*)(H + ((size_t)((row >> 8) * (DFF / 64) + (col >> 6)) * 256 + (row & 255)) * 64 + (col & 63)) = w; }
;                 }
	v_add_f32_e32 v34, v39, v43
	v_fmamk_f32 v34, v34, 0x3a800000, v181
	v_mul_f32_e32 v36, 0x4b800000, v34
	v_cmp_gt_f32_e32 vcc, s41, v34
	v_max_f32_e32 v38, 0, v38
	v_mul_f32_e32 v35, v35, v35
	v_cndmask_b32_e32 v34, v34, v36, vcc
	v_rsq_f32_e32 v36, v34
	v_mul_f32_e32 v38, v38, v38
	v_cvt_pk_bf16_f32 v33, v38, v33
	v_cvt_pk_bf16_f32 v34, v40, v41
	v_cvt_pk_bf16_f32 v35, v42, v35
	global_store_dwordx4 v[54:55], v[32:35], off offset:2048
	s_nop 1
	v_mul_f32_e32 v32, 0x45800000, v36
	v_cndmask_b32_e32 v32, v36, v32, vcc
	v_pk_mul_f32 v[26:27], v[26:27], v[32:33] op_sel_hi:[1,0]
	v_pk_mul_f32 v[24:25], v[24:25], v[32:33] op_sel_hi:[1,0]
	v_pk_mul_f32 v[30:31], v[30:31], v[32:33] op_sel_hi:[1,0]
	v_pk_mul_f32 v[28:29], v[28:29], v[32:33] op_sel_hi:[1,0]
	v_max_f32_e32 v24, 0, v24
	v_max_f32_e32 v25, 0, v25
	v_max_f32_e32 v26, 0, v26
	v_max_f32_e32 v28, 0, v28
	v_mul_f32_e32 v33, v24, v24
	v_max_f32_e32 v24, 0, v29
	v_mul_f32_e32 v29, v25, v25
	v_max_f32_e32 v25, 0, v30
	v_mul_f32_e32 v30, v26, v26
	v_max_f32_e32 v26, 0, v31
	v_mul_f32_e32 v28, v28, v28
	v_mul_f32_e32 v24, v24, v24
	v_mul_f32_e32 v25, v25, v25
	v_max_f32_e32 v27, 0, v27
	v_mul_f32_e32 v26, v26, v26
	v_mul_f32_e32 v27, v27, v27
	v_cvt_pk_bf16_f32 v24, v28, v24
	v_cvt_pk_bf16_f32 v25, v25, v26
	v_cvt_pk_bf16_f32 v26, v33, v29
	v_or_b32_e32 v28, 0x1000, v156
	v_mov_b32_e32 v29, v157
	v_cvt_pk_bf16_f32 v27, v30, v27
	v_lshl_add_u64 v[30:31], v[56:57], 0, v[28:29]
	v_pk_mul_f32 v[16:17], v[16:17], v[32:33] op_sel_hi:[1,0]
	v_lshl_add_u64 v[30:31], v[30:31], 0, v[168:169]
	v_pk_mul_f32 v[20:21], v[20:21], v[32:33] op_sel_hi:[1,0]
	v_max_f32_e32 v16, 0, v16
	global_store_dwordx4 v[30:31], v[24:27], off
	v_pk_mul_f32 v[22:23], v[22:23], v[32:33] op_sel_hi:[1,0]
	v_pk_mul_f32 v[18:19], v[18:19], v[32:33] op_sel_hi:[1,0]
	v_mul_f32_e32 v24, v16, v16
	v_max_f32_e32 v16, 0, v21
	v_max_f32_e32 v17, 0, v17
	v_mul_f32_e32 v21, v16, v16
	v_mul_f32_e32 v25, v17, v17
	v_max_f32_e32 v16, 0, v22
	v_max_f32_e32 v17, 0, v18
	v_mul_f32_e32 v18, v16, v16
	v_mul_f32_e32 v22, v17, v17
	s_waitcnt vmcnt(13)
	v_mov_b32_e32 v16, v129
	v_mov_b32_e32 v17, v130
	v_mov_b32_e32 v129, v131
	v_pk_add_f32 v[16:17], v[16:17], v[128:129]
	v_max_f32_e32 v20, 0, v20
	v_add_f32_e32 v16, v16, v17
	ds_bpermute_b32 v17, v174, v16
	v_mul_f32_e32 v20, v20, v20
	v_max_f32_e32 v19, 0, v19
	v_max_f32_e32 v23, 0, v23
	v_mul_f32_e32 v19, v19, v19
	s_waitcnt lgkmcnt(0)
	v_add_f32_e32 v26, v16, v17
	ds_bpermute_b32 v27, v175, v26
	v_cvt_pk_bf16_f32 v16, v20, v21
	v_mul_f32_e32 v23, v23, v23
	v_cvt_pk_bf16_f32 v17, v18, v23
	v_cvt_pk_bf16_f32 v18, v24, v25
	s_waitcnt lgkmcnt(0)
	v_add_f32_e32 v20, v26, v27
	v_fmamk_f32 v20, v20, 0x3a800000, v181
	v_mul_f32_e32 v21, 0x4b800000, v20
	v_cmp_gt_f32_e32 vcc, s41, v20
	v_cvt_pk_bf16_f32 v19, v22, v19
	v_or_b32_e32 v156, 0x1800, v156
	s_nop 0
	v_cndmask_b32_e32 v20, v20, v21, vcc
	v_rsq_f32_e32 v22, v20
	v_lshl_add_u64 v[20:21], v[48:49], 0, v[28:29]
	v_lshl_add_u64 v[20:21], v[20:21], 0, v[168:169]
	global_store_dwordx4 v[20:21], v[16:19], off
	s_nop 1
	v_mul_f32_e32 v16, 0x45800000, v22
	v_cndmask_b32_e32 v16, v22, v16, vcc
	v_pk_mul_f32 v[10:11], v[10:11], v[16:17] op_sel_hi:[1,0]
	v_pk_mul_f32 v[8:9], v[8:9], v[16:17] op_sel_hi:[1,0]
	v_pk_mul_f32 v[14:15], v[14:15], v[16:17] op_sel_hi:[1,0]
	v_pk_mul_f32 v[12:13], v[12:13], v[16:17] op_sel_hi:[1,0]
	v_max_f32_e32 v8, 0, v8
	v_max_f32_e32 v9, 0, v9
	v_max_f32_e32 v10, 0, v10
	v_max_f32_e32 v12, 0, v12
	v_mul_f32_e32 v17, v8, v8
	v_max_f32_e32 v8, 0, v13
	v_mul_f32_e32 v13, v9, v9
	v_max_f32_e32 v9, 0, v14
	v_mul_f32_e32 v14, v10, v10
	v_max_f32_e32 v10, 0, v15
	v_mul_f32_e32 v12, v12, v12
	v_mul_f32_e32 v8, v8, v8
	v_mul_f32_e32 v9, v9, v9
	v_mul_f32_e32 v10, v10, v10
	v_max_f32_e32 v11, 0, v11
	v_cvt_pk_bf16_f32 v8, v12, v8
	v_cvt_pk_bf16_f32 v9, v9, v10
	v_cvt_pk_bf16_f32 v10, v17, v13
	v_lshl_add_u64 v[12:13], v[56:57], 0, v[156:157]
	v_pk_mul_f32 v[2:3], v[2:3], v[16:17] op_sel_hi:[1,0]
	v_pk_mul_f32 v[0:1], v[0:1], v[16:17] op_sel_hi:[1,0]
	v_mul_f32_e32 v11, v11, v11
	v_lshl_add_u64 v[12:13], v[12:13], 0, v[168:169]
	v_pk_mul_f32 v[6:7], v[6:7], v[16:17] op_sel_hi:[1,0]
	v_pk_mul_f32 v[4:5], v[4:5], v[16:17] op_sel_hi:[1,0]
	v_max_f32_e32 v0, 0, v0
	v_max_f32_e32 v1, 0, v1
	v_max_f32_e32 v2, 0, v2
	v_cvt_pk_bf16_f32 v11, v14, v11
	global_store_dwordx4 v[12:13], v[8:11], off
	v_max_f32_e32 v4, 0, v4
	v_mul_f32_e32 v4, v4, v4
	v_mul_f32_e32 v8, v0, v0
	v_max_f32_e32 v0, 0, v5
	v_mul_f32_e32 v5, v1, v1
	v_max_f32_e32 v1, 0, v6
	v_mul_f32_e32 v6, v2, v2
	v_max_f32_e32 v2, 0, v7
	v_mul_f32_e32 v0, v0, v0
	v_mul_f32_e32 v1, v1, v1
	v_mul_f32_e32 v2, v2, v2
	v_max_f32_e32 v3, 0, v3
	v_cvt_pk_bf16_f32 v0, v4, v0
	v_cvt_pk_bf16_f32 v1, v1, v2
	v_cvt_pk_bf16_f32 v2, v8, v5
	v_lshl_add_u64 v[4:5], v[48:49], 0, v[156:157]
	v_mul_f32_e32 v3, v3, v3
	v_lshl_add_u64 v[4:5], v[4:5], 0, v[168:169]
	s_and_b64 vcc, exec, s[0:1]
	v_cvt_pk_bf16_f32 v3, v6, v3
	global_store_dwordx4 v[4:5], v[0:3], off
	s_cbranch_vccz .LBB0_718
	s_waitcnt vmcnt(0)
	s_cmpk_gt_u32 s22, 0xff
	s_cbranch_scc1 .LBB0_729
	s_barrier

; __device__ __forceinline__ void xcd_barrier(const int wv, const XcdBarrier& b) {
;     asm volatile("s_waitcnt vmcnt(0)" ::: "memory");
;     __syncthreads();
;     if (TIDX == 0) {
;         unsigned long long barq = (unsigned long long)b.bar; asm volatile("" : "+s"(barq));
;         unsigned* bar = (unsigned*)barq;
;         __builtin_amdgcn_s_waitcnt(0);
;         unsigned nloc = b.st[0], nx = b.st[1];
;         if (nloc == 0u) { xcd_barrier_complete(bar, b.x, nloc, nx); b.st[0] = nloc; b.st[1] = nx; }
.LBB0_730:
	s_setprio 0
	s_waitcnt vmcnt(0)
	s_barrier
	v_mbcnt_lo_u32_b32 v0, -1, 0
	v_mbcnt_hi_u32_b32 v0, -1, v0
	s_nop 0
	v_sub_u32_e32 v0, 0, v0
	v_cmp_eq_u32_e32 vcc, s53, v0
	s_and_saveexec_b64 s[0:1], vcc
	s_cbranch_execz .LBB0_774
	s_add_i32 s2, 0, 0x21ff0
	v_mov_b32_e32 v0, s2
	s_waitcnt vmcnt(0) expcnt(0) lgkmcnt(0)
	ds_read_b32 v4, v0
	s_add_i32 s2, 0, 0x21ff4
	v_mov_b32_e32 v0, s2
	ds_read_b32 v2, v0
	s_waitcnt lgkmcnt(1)
	v_cmp_ne_u32_e32 vcc, 0, v4
	s_cbranch_vccnz .LBB0_745
	s_add_u32 s4, s58, 0x1000
	s_addc_u32 s5, s59, 0
	s_add_u32 s6, s58, 0x1100
	s_addc_u32 s7, s59, 0
	s_add_u32 s8, s58, 0x1200
	s_addc_u32 s9, s59, 0
	s_add_u32 s10, s58, 0x1300
	s_addc_u32 s11, s59, 0
	s_mov_b32 s20, 1
	s_mov_b64 s[2:3], 0
	v_mov_b64_e32 v[0:1], s[58:59]
	s_waitcnt lgkmcnt(0)
	v_mov_b64_e32 v[2:3], s[4:5]
	v_mov_b64_e32 v[4:5], s[6:7]
	v_mov_b64_e32 v[6:7], s[8:9]
	v_mov_b64_e32 v[8:9], s[10:11]
	s_branch .LBB0_735

;     __device__ void init(int b_, int G_, int c_) { so.init(TB, 42 * 256, G_, c_); G = G_; c = c_; b = b_; gstart = b_ == 0 ? 0 : 256 + 192 * b_; ng = b_ == 0 ? 448 : 192; }
; __device__ __forceinline__ KParams kparams() { unsigned long long a = (unsigned long long)__builtin_amdgcn_kernarg_segment_ptr(); asm volatile("" : "+s"(a)); return (KParams)a; }
; template <class Epi, class Sched>
; __device__ __forceinline__ void gemm_phase(const int wv, LAS unsigned char* lds, const Gemm g, const Sched& S, const Epi& E) {
;     int tid_ = TIDX; asm volatile("" : "+v"(tid_));
;     const int tid = tid_, wid = __builtin_amdgcn_readfirstlane(tid >> 6), lane = tid & 63, wr = wid >> 2, wc = wid & 3, fr = lane & 15, fq = lane >> 4;
;     const int K = g.K, nt = K / BK;
; __global__ void __launch_bounds__(512, 2) mega(Params p_unused) {
;     ...
;         KParams kp = kparams(); unsigned char* ws = kp->ws;
;         pg8::StaticOrder S; S.init(MT, DM, (int)gridDim.x, (int)blockIdx.x);
;         pg8::Gemm gm{WSP(bf16_t, WS_H), WSP(bf16_t, WS_WDN), MT, DM, DFF, DFF, DFF, 1}; EpiDown E{WSP(bf16_t, WS_X1B), kp->out};
;         pg8::gemm_phase<EpiDown, pg8::StaticOrder>(wv, lds, gm, S, E);
.LBB0_774:
	s_or_b64 exec, exec, s[0:1]
	s_waitcnt lgkmcnt(0)
	s_barrier
	s_cmpk_lt_u32 s53, 0x100
	s_cbranch_scc1 .Lgprio_dn
	s_setprio 1
.Lgprio_dn:
	v_mbcnt_lo_u32_b32 v0, -1, 0
	v_mbcnt_hi_u32_b32 v0, -1, v0
	s_and_b64 vcc, exec, s[64:65]
	v_add_u32_e32 v4, s53, v0
	s_nop 0
	v_readfirstlane_b32 s26, v4
	s_cbranch_vccnz .LBB0_794
	s_and_b64 vcc, exec, s[62:63]
	s_cbranch_vccz .LBB0_777
	s_lshl_b32 s2, s60, 6
	s_load_dwordx4 s[4:7], s[56:57], 0x68
	s_cbranch_execz .LBB0_778
	s_branch .LBB0_779

; #define PG8_STAGE(bufoff, gbase, voff) do { _Pragma("unroll") for (int _i = 0; _i < 2; ++_i) \
;         __builtin_amdgcn_global_load_lds((const unsigned*)((const char*)(gbase) + (voff)[_i]), (LAS unsigned*)(lds + (bufoff) + ldsw + _i * 8192), 16, 0, 0); } while (0)
; #define PG8_LDA(dst, b, h) do { _Pragma("unroll") for (int m = 0; m < 4; ++m) _Pragma("unroll") for (int k = 0; k < 2; ++k) dst[m][k] = *(const LAS bf16x8*)(lds + PG8_SA(b, h) + aoff + m * 2048 + k * 1024); } while (0)
; #define PG8_LDB(dst, b, h) do { _Pragma("unroll") for (int n = 0; n < 2; ++n) _Pragma("unroll") for (int k = 0; k < 2; ++k) dst[n][k] = *(const LAS bf16x8*)(lds + PG8_SB(b, h) + boff + n * 2048 + k * 1024); } while (0)
; #define PG8_MMA(ai, bj, At, Bt) do { __builtin_amdgcn_s_setprio(1); _Pragma("unroll") for (int m = 0; m < 4; ++m) _Pragma("unroll") for (int n = 0; n < 2; ++n) _Pragma("unroll") for (int k = 0; k < 2; ++k) \
;         acc[ai][bj][m][n] = __builtin_amdgcn_mfma_f32_16x16x32_bf16(Bt[n][k], At[m][k], acc[ai][bj][m][n], 0, 0, 0); __builtin_amdgcn_s_setprio(0); } while (0)
; #define PG8_WAIT_L(n) asm volatile("s_waitcnt lgkmcnt(" #n ")" ::: "memory")
; #define PG8_BAR __builtin_amdgcn_s_barrier()
; #define PG8_SCHED __builtin_amdgcn_sched_barrier(0)
; template <class Epi, class Sched>
; __device__ __forceinline__ void gemm_phase(const int wv, LAS unsigned char* lds, const Gemm g, const Sched& S, const Epi& E) {
;     ...
;             PG8_LDB(B0, 0, 0); PG8_SCHED; PG8_LDA(At, 0, 0); PG8_STAGE(PG8_SA(1, 1), a1 + hstepA, voffA);
;             PG8_WAIT_L(8); PG8_BAR; PG8_WAIT_L(0); PG8_MMA(0, 0, At, B0); PG8_BAR; PG8_SCHED;
;             PG8_LDB(B1, 0, 1); PG8_STAGE(PG8_SB(0, 0), b2, voffB);
;             PG8_BAR; PG8_WAIT_L(0); PG8_MMA(0, 1, At, B1); PG8_BAR;
;             PG8_LDA(At, 0, 1); PG8_STAGE(PG8_SA(0, 0), a2, voffA);
;             PG8_BAR; PG8_WAIT_L(0); PG8_MMA(1, 0, At, B0); PG8_BAR; PG8_SCHED;
.LBB0_789:
	ds_read_b128 v[144:147], v199
	ds_read_b128 v[148:151], v199 offset:1024
	ds_read_b128 v[152:155], v199 offset:2048
	ds_read_b128 v[156:159], v199 offset:3072
	s_add_u32 s20, s18, 0x4000
	s_addc_u32 s21, s19, 0
	s_cmp_eq_u32 s46, 60
	s_cselect_b32 s24, s42, s20
	s_cselect_b32 s25, s11, s21
	s_cselect_b32 s20, s43, s44
	s_cselect_b32 s21, s9, s45
	s_add_u32 s22, s24, 0x8000
	s_addc_u32 s23, s25, 0
	v_lshl_add_u64 v[192:193], s[18:19], 0, v[136:137]
	s_add_i32 m0, s17, 0xc000
	ds_read_b128 v[160:163], v200
	ds_read_b128 v[164:167], v200 offset:1024
	ds_read_b128 v[168:171], v200 offset:2048
	ds_read_b128 v[172:175], v200 offset:3072
	ds_read_b128 v[176:179], v200 offset:4096
	ds_read_b128 v[180:183], v200 offset:5120
	ds_read_b128 v[184:187], v200 offset:6144
	ds_read_b128 v[188:191], v200 offset:7168
	global_load_lds_dwordx4 v[192:193], off
	v_lshl_add_u64 v[192:193], s[18:19], 0, v[138:139]
	s_add_i32 m0, s17, 0xe000
	s_nop 0
	global_load_lds_dwordx4 v[192:193], off
	s_waitcnt lgkmcnt(8)
	s_barrier
	s_waitcnt lgkmcnt(0)
	s_waitcnt lgkmcnt(0)
	v_mfma_f32_16x16x32_bf16 v[124:127], v[144:147], v[160:163], v[124:127]
	v_mfma_f32_16x16x32_bf16 v[120:123], v[152:155], v[160:163], v[120:123]
	v_mfma_f32_16x16x32_bf16 v[112:115], v[144:147], v[168:171], v[112:115]
	v_mfma_f32_16x16x32_bf16 v[104:107], v[152:155], v[168:171], v[104:107]
	v_mfma_f32_16x16x32_bf16 v[96:99], v[144:147], v[176:179], v[96:99]
	v_mfma_f32_16x16x32_bf16 v[88:91], v[152:155], v[176:179], v[88:91]
	v_mfma_f32_16x16x32_bf16 v[80:83], v[144:147], v[184:187], v[80:83]
	v_mfma_f32_16x16x32_bf16 v[72:75], v[152:155], v[184:187], v[72:75]
	v_mfma_f32_16x16x32_bf16 v[124:127], v[148:151], v[164:167], v[124:127]
	v_mfma_f32_16x16x32_bf16 v[120:123], v[156:159], v[164:167], v[120:123]
	v_mfma_f32_16x16x32_bf16 v[112:115], v[148:151], v[172:175], v[112:115]
	v_mfma_f32_16x16x32_bf16 v[104:107], v[156:159], v[172:175], v[104:107]
	v_mfma_f32_16x16x32_bf16 v[96:99], v[148:151], v[180:183], v[96:99]
	v_mfma_f32_16x16x32_bf16 v[88:91], v[156:159], v[180:183], v[88:91]
	v_mfma_f32_16x16x32_bf16 v[80:83], v[148:151], v[188:191], v[80:83]
	v_mfma_f32_16x16x32_bf16 v[72:75], v[156:159], v[188:191], v[72:75]
	s_barrier
	s_add_i32 s47, s39, s31
	v_lshl_add_u64 v[214:215], s[20:21], 0, v[130:131]
	s_mov_b32 m0, s47
	ds_read_b128 v[192:195], v201
	ds_read_b128 v[202:205], v201 offset:1024
	ds_read_b128 v[206:209], v201 offset:2048
	ds_read_b128 v[210:213], v201 offset:3072
	global_load_lds_dwordx4 v[214:215], off
	v_lshl_add_u64 v[216:217], s[20:21], 0, v[134:135]
	s_add_i32 m0, s47, 0x2000
	s_nop 0
	global_load_lds_dwordx4 v[216:217], off
	s_barrier
	s_waitcnt lgkmcnt(0)
	s_waitcnt lgkmcnt(0)
	v_mfma_f32_16x16x32_bf16 v[116:119], v[192:195], v[160:163], v[116:119]
	v_mfma_f32_16x16x32_bf16 v[108:111], v[206:209], v[160:163], v[108:111]
	v_mfma_f32_16x16x32_bf16 v[100:103], v[192:195], v[168:171], v[100:103]
	v_mfma_f32_16x16x32_bf16 v[92:95], v[206:209], v[168:171], v[92:95]
	v_mfma_f32_16x16x32_bf16 v[84:87], v[192:195], v[176:179], v[84:87]
	v_mfma_f32_16x16x32_bf16 v[76:79], v[206:209], v[176:179], v[76:79]
	v_mfma_f32_16x16x32_bf16 v[68:71], v[192:195], v[184:187], v[68:71]
	v_mfma_f32_16x16x32_bf16 v[64:67], v[206:209], v[184:187], v[64:67]
	v_mfma_f32_16x16x32_bf16 v[116:119], v[202:205], v[164:167], v[116:119]
	v_mfma_f32_16x16x32_bf16 v[108:111], v[210:213], v[164:167], v[108:111]
	v_mfma_f32_16x16x32_bf16 v[100:103], v[202:205], v[172:175], v[100:103]
	v_mfma_f32_16x16x32_bf16 v[92:95], v[210:213], v[172:175], v[92:95]
	v_mfma_f32_16x16x32_bf16 v[84:87], v[202:205], v[180:183], v[84:87]
	v_mfma_f32_16x16x32_bf16 v[76:79], v[210:213], v[180:183], v[76:79]
	v_mfma_f32_16x16x32_bf16 v[68:71], v[202:205], v[188:191], v[68:71]
	v_mfma_f32_16x16x32_bf16 v[64:67], v[210:213], v[188:191], v[64:67]
	s_mov_b32 m0, s17
	v_lshl_add_u64 v[218:219], s[24:25], 0, v[128:129]
	s_barrier
	ds_read_b128 v[160:163], v200 offset:16384
	ds_read_b128 v[164:167], v200 offset:17408
	ds_read_b128 v[168:171], v200 offset:18432
	ds_read_b128 v[172:175], v200 offset:19456
	ds_read_b128 v[176:179], v200 offset:20480
	ds_read_b128 v[180:183], v200 offset:21504
	ds_read_b128 v[184:187], v200 offset:22528
	ds_read_b128 v[188:191], v200 offset:23552
	global_load_lds_dwordx4 v[218:219], off
	v_lshl_add_u64 v[218:219], s[24:25], 0, v[132:133]
	s_mov_b32 m0, s33
	s_nop 0
	global_load_lds_dwordx4 v[218:219], off
	s_barrier
	s_waitcnt lgkmcnt(0)
	s_waitcnt lgkmcnt(0)
	v_mfma_f32_16x16x32_bf16 v[60:63], v[144:147], v[160:163], v[60:63]
	v_mfma_f32_16x16x32_bf16 v[56:59], v[152:155], v[160:163], v[56:59]
	v_mfma_f32_16x16x32_bf16 v[48:51], v[144:147], v[168:171], v[48:51]
	v_mfma_f32_16x16x32_bf16 v[40:43], v[152:155], v[168:171], v[40:43]
	v_mfma_f32_16x16x32_bf16 v[32:35], v[144:147], v[176:179], v[32:35]
	v_mfma_f32_16x16x32_bf16 v[24:27], v[152:155], v[176:179], v[24:27]
	v_mfma_f32_16x16x32_bf16 v[16:19], v[144:147], v[184:187], v[16:19]
	v_mfma_f32_16x16x32_bf16 v[8:11], v[152:155], v[184:187], v[8:11]
	v_mfma_f32_16x16x32_bf16 v[60:63], v[148:151], v[164:167], v[60:63]
	v_mfma_f32_16x16x32_bf16 v[56:59], v[156:159], v[164:167], v[56:59]
	v_mfma_f32_16x16x32_bf16 v[48:51], v[148:151], v[172:175], v[48:51]
	v_mfma_f32_16x16x32_bf16 v[40:43], v[156:159], v[172:175], v[40:43]
	v_mfma_f32_16x16x32_bf16 v[32:35], v[148:151], v[180:183], v[32:35]
	v_mfma_f32_16x16x32_bf16 v[24:27], v[156:159], v[180:183], v[24:27]
	v_mfma_f32_16x16x32_bf16 v[16:19], v[148:151], v[188:191], v[16:19]
	v_mfma_f32_16x16x32_bf16 v[8:11], v[156:159], v[188:191], v[8:11]
	s_barrier
; #define PG8_STAGE(bufoff, gbase, voff) do { _Pragma("unroll") for (int _i = 0; _i < 2; ++_i) \
;         __builtin_amdgcn_global_load_lds((const unsigned*)((const char*)(gbase) + (voff)[_i]), (LAS unsigned*)(lds + (bufoff) + ldsw + _i * 8192), 16, 0, 0); } while (0)
; #define PG8_LDA(dst, b, h) do { _Pragma("unroll") for (int m = 0; m < 4; ++m) _Pragma("unroll") for (int k = 0; k < 2; ++k) dst[m][k] = *(const LAS bf16x8*)(lds + PG8_SA(b, h) + aoff + m * 2048 + k * 1024); } while (0)
; #define PG8_LDB(dst, b, h) do { _Pragma("unroll") for (int n = 0; n < 2; ++n) _Pragma("unroll") for (int k = 0; k < 2; ++k) dst[n][k] = *(const LAS bf16x8*)(lds + PG8_SB(b, h) + boff + n * 2048 + k * 1024); } while (0)
; #define PG8_MMA(ai, bj, At, Bt) do { __builtin_amdgcn_s_setprio(1); _Pragma("unroll") for (int m = 0; m < 4; ++m) _Pragma("unroll") for (int n = 0; n < 2; ++n) _Pragma("unroll") for (int k = 0; k < 2; ++k) \
;         acc[ai][bj][m][n] = __builtin_amdgcn_mfma_f32_16x16x32_bf16(Bt[n][k], At[m][k], acc[ai][bj][m][n], 0, 0, 0); __builtin_amdgcn_s_setprio(0); } while (0)
; #define PG8_WAIT_V(n) asm volatile("s_waitcnt vmcnt(" #n ")" ::: "memory")
; #define PG8_WAIT_L(n) asm volatile("s_waitcnt lgkmcnt(" #n ")" ::: "memory")
; #define PG8_BAR __builtin_amdgcn_s_barrier()
; #define PG8_SCHED __builtin_amdgcn_sched_barrier(0)
; template <class Epi, class Sched>
; __device__ __forceinline__ void gemm_phase(const int wv, LAS unsigned char* lds, const Gemm g, const Sched& S, const Epi& E) {
;     ...
;             PG8_BAR; PG8_WAIT_L(0); PG8_MMA(1, 0, At, B0); PG8_BAR; PG8_SCHED;
;             PG8_STAGE(PG8_SB(0, 1), b2 + hstepB, voffB);
;             PG8_WAIT_V(6); PG8_BAR; PG8_MMA(1, 1, At, B1); PG8_BAR;
;             PG8_LDB(B0, 1, 0); PG8_SCHED; PG8_LDA(At, 1, 0); PG8_STAGE(PG8_SA(0, 1), a2 + hstepA, voffA);
;             PG8_WAIT_L(8); PG8_BAR; PG8_WAIT_L(0); PG8_MMA(0, 0, At, B0); PG8_BAR; PG8_SCHED;
;             PG8_LDB(B1, 1, 1); PG8_STAGE(PG8_SB(1, 0), b3, voffB);
;             PG8_BAR; PG8_WAIT_L(0); PG8_MMA(0, 1, At, B1); PG8_BAR;
;             PG8_LDA(At, 1, 1); PG8_STAGE(PG8_SA(1, 0), a3, voffA);
	s_add_u32 s48, s20, 0x100000
	s_addc_u32 s49, s21, 0
	s_add_i32 s47, s40, s31
	v_lshl_add_u64 v[144:145], s[48:49], 0, v[130:131]
	s_mov_b32 m0, s47
	s_nop 0
	global_load_lds_dwordx4 v[144:145], off
	v_lshl_add_u64 v[144:145], s[48:49], 0, v[134:135]
	s_add_i32 m0, s47, 0x2000
	s_nop 0
	global_load_lds_dwordx4 v[144:145], off
	s_waitcnt vmcnt(6)
	s_barrier
	v_mfma_f32_16x16x32_bf16 v[52:55], v[192:195], v[160:163], v[52:55]
	v_mfma_f32_16x16x32_bf16 v[44:47], v[206:209], v[160:163], v[44:47]
	v_mfma_f32_16x16x32_bf16 v[36:39], v[192:195], v[168:171], v[36:39]
	v_mfma_f32_16x16x32_bf16 v[28:31], v[206:209], v[168:171], v[28:31]
	v_mfma_f32_16x16x32_bf16 v[20:23], v[192:195], v[176:179], v[20:23]
	v_mfma_f32_16x16x32_bf16 v[12:15], v[206:209], v[176:179], v[12:15]
	v_mfma_f32_16x16x32_bf16 v[4:7], v[192:195], v[184:187], v[4:7]
	v_mfma_f32_16x16x32_bf16 v[0:3], v[206:209], v[184:187], v[0:3]
	v_mfma_f32_16x16x32_bf16 v[52:55], v[202:205], v[164:167], v[52:55]
	v_mfma_f32_16x16x32_bf16 v[44:47], v[210:213], v[164:167], v[44:47]
	v_mfma_f32_16x16x32_bf16 v[36:39], v[202:205], v[172:175], v[36:39]
	v_mfma_f32_16x16x32_bf16 v[28:31], v[210:213], v[172:175], v[28:31]
	v_mfma_f32_16x16x32_bf16 v[20:23], v[202:205], v[180:183], v[20:23]
	v_mfma_f32_16x16x32_bf16 v[12:15], v[210:213], v[180:183], v[12:15]
	v_mfma_f32_16x16x32_bf16 v[4:7], v[202:205], v[188:191], v[4:7]
	v_mfma_f32_16x16x32_bf16 v[0:3], v[210:213], v[188:191], v[0:3]
	s_add_i32 s47, 0, 0x18000
	v_add_u32_e32 v156, s47, v197
	s_barrier
	ds_read_b128 v[144:147], v156
	ds_read_b128 v[148:151], v156 offset:1024
	ds_read_b128 v[152:155], v156 offset:2048
	ds_read_b128 v[156:159], v156 offset:3072
	s_add_u32 s24, s24, 0x4000
	s_addc_u32 s25, s25, 0
	s_mov_b32 m0, s34
	v_lshl_add_u64 v[192:193], s[24:25], 0, v[128:129]
	ds_read_b128 v[160:163], v200 offset:32768
	ds_read_b128 v[164:167], v200 offset:33792
	ds_read_b128 v[168:171], v200 offset:34816
	ds_read_b128 v[172:175], v200 offset:35840
	ds_read_b128 v[176:179], v200 offset:36864
	ds_read_b128 v[180:183], v200 offset:37888
	ds_read_b128 v[184:187], v200 offset:38912
	ds_read_b128 v[188:191], v200 offset:39936
	global_load_lds_dwordx4 v[192:193], off
	v_lshl_add_u64 v[192:193], s[24:25], 0, v[132:133]
	s_mov_b32 m0, s35
	s_nop 0
	global_load_lds_dwordx4 v[192:193], off
	s_waitcnt lgkmcnt(8)
	s_barrier
	s_waitcnt lgkmcnt(0)
	s_waitcnt lgkmcnt(0)
	v_mfma_f32_16x16x32_bf16 v[124:127], v[144:147], v[160:163], v[124:127]
	v_mfma_f32_16x16x32_bf16 v[120:123], v[152:155], v[160:163], v[120:123]
	v_mfma_f32_16x16x32_bf16 v[112:115], v[144:147], v[168:171], v[112:115]
	v_mfma_f32_16x16x32_bf16 v[104:107], v[152:155], v[168:171], v[104:107]
	v_mfma_f32_16x16x32_bf16 v[96:99], v[144:147], v[176:179], v[96:99]
	v_mfma_f32_16x16x32_bf16 v[88:91], v[152:155], v[176:179], v[88:91]
	v_mfma_f32_16x16x32_bf16 v[80:83], v[144:147], v[184:187], v[80:83]
	v_mfma_f32_16x16x32_bf16 v[72:75], v[152:155], v[184:187], v[72:75]
	v_mfma_f32_16x16x32_bf16 v[124:127], v[148:151], v[164:167], v[124:127]
	v_mfma_f32_16x16x32_bf16 v[120:123], v[156:159], v[164:167], v[120:123]
	v_mfma_f32_16x16x32_bf16 v[112:115], v[148:151], v[172:175], v[112:115]
	v_mfma_f32_16x16x32_bf16 v[104:107], v[156:159], v[172:175], v[104:107]
	v_mfma_f32_16x16x32_bf16 v[96:99], v[148:151], v[180:183], v[96:99]
	v_mfma_f32_16x16x32_bf16 v[88:91], v[156:159], v[180:183], v[88:91]
	v_mfma_f32_16x16x32_bf16 v[80:83], v[148:151], v[188:191], v[80:83]
	v_mfma_f32_16x16x32_bf16 v[72:75], v[156:159], v[188:191], v[72:75]
	s_barrier
	s_add_i32 s24, 0, 0x1c000
	s_add_i32 s25, s47, s31
	v_add_u32_e32 v210, s24, v197
	v_lshl_add_u64 v[214:215], v[214:215], 0, s[6:7]
	s_mov_b32 m0, s25
	ds_read_b128 v[192:195], v210
	ds_read_b128 v[202:205], v210 offset:1024
	ds_read_b128 v[206:209], v210 offset:2048
	ds_read_b128 v[210:213], v210 offset:3072
	global_load_lds_dwordx4 v[214:215], off
	v_lshl_add_u64 v[214:215], v[216:217], 0, s[6:7]
	s_add_i32 m0, s25, 0x2000
	s_nop 0
	global_load_lds_dwordx4 v[214:215], off
	s_barrier
	s_waitcnt lgkmcnt(0)
	s_waitcnt lgkmcnt(0)
	v_mfma_f32_16x16x32_bf16 v[116:119], v[192:195], v[160:163], v[116:119]
	v_mfma_f32_16x16x32_bf16 v[108:111], v[206:209], v[160:163], v[108:111]
	v_mfma_f32_16x16x32_bf16 v[100:103], v[192:195], v[168:171], v[100:103]
	v_mfma_f32_16x16x32_bf16 v[92:95], v[206:209], v[168:171], v[92:95]
	v_mfma_f32_16x16x32_bf16 v[84:87], v[192:195], v[176:179], v[84:87]
	v_mfma_f32_16x16x32_bf16 v[76:79], v[206:209], v[176:179], v[76:79]
	v_mfma_f32_16x16x32_bf16 v[68:71], v[192:195], v[184:187], v[68:71]
	v_mfma_f32_16x16x32_bf16 v[64:67], v[206:209], v[184:187], v[64:67]
	v_mfma_f32_16x16x32_bf16 v[116:119], v[202:205], v[164:167], v[116:119]
	v_mfma_f32_16x16x32_bf16 v[108:111], v[210:213], v[164:167], v[108:111]
	v_mfma_f32_16x16x32_bf16 v[100:103], v[202:205], v[172:175], v[100:103]
	v_mfma_f32_16x16x32_bf16 v[92:95], v[210:213], v[172:175], v[92:95]
	v_mfma_f32_16x16x32_bf16 v[84:87], v[202:205], v[180:183], v[84:87]
	v_mfma_f32_16x16x32_bf16 v[76:79], v[210:213], v[180:183], v[76:79]
	v_mfma_f32_16x16x32_bf16 v[68:71], v[202:205], v[188:191], v[68:71]
	v_mfma_f32_16x16x32_bf16 v[64:67], v[210:213], v[188:191], v[64:67]
	s_mov_b32 m0, s37
	v_lshl_add_u64 v[214:215], s[22:23], 0, v[128:129]
	s_barrier
	ds_read_b128 v[160:163], v200 offset:49152
	ds_read_b128 v[164:167], v200 offset:50176
	ds_read_b128 v[168:171], v200 offset:51200
	ds_read_b128 v[172:175], v200 offset:52224
	ds_read_b128 v[176:179], v200 offset:53248
	ds_read_b128 v[180:183], v200 offset:54272
	ds_read_b128 v[184:187], v200 offset:55296
	ds_read_b128 v[188:191], v200 offset:56320
	global_load_lds_dwordx4 v[214:215], off
	v_lshl_add_u64 v[214:215], s[22:23], 0, v[132:133]
	s_mov_b32 m0, s38
	s_nop 0
	global_load_lds_dwordx4 v[214:215], off
	s_barrier
; #define PG8_STAGE(bufoff, gbase, voff) do { _Pragma("unroll") for (int _i = 0; _i < 2; ++_i) \
;         __builtin_amdgcn_global_load_lds((const unsigned*)((const char*)(gbase) + (voff)[_i]), (LAS unsigned*)(lds + (bufoff) + ldsw + _i * 8192), 16, 0, 0); } while (0)
; #define PG8_LDA(dst, b, h) do { _Pragma("unroll") for (int m = 0; m < 4; ++m) _Pragma("unroll") for (int k = 0; k < 2; ++k) dst[m][k] = *(const LAS bf16x8*)(lds + PG8_SA(b, h) + aoff + m * 2048 + k * 1024); } while (0)
; #define PG8_MMA(ai, bj, At, Bt) do { __builtin_amdgcn_s_setprio(1); _Pragma("unroll") for (int m = 0; m < 4; ++m) _Pragma("unroll") for (int n = 0; n < 2; ++n) _Pragma("unroll") for (int k = 0; k < 2; ++k) \
;         acc[ai][bj][m][n] = __builtin_amdgcn_mfma_f32_16x16x32_bf16(Bt[n][k], At[m][k], acc[ai][bj][m][n], 0, 0, 0); __builtin_amdgcn_s_setprio(0); } while (0)
; #define PG8_WAIT_V(n) asm volatile("s_waitcnt vmcnt(" #n ")" ::: "memory")
; #define PG8_WAIT_L(n) asm volatile("s_waitcnt lgkmcnt(" #n ")" ::: "memory")
; #define PG8_BAR __builtin_amdgcn_s_barrier()
; #define PG8_SCHED __builtin_amdgcn_sched_barrier(0)
; template <class Epi, class Sched>
; __device__ __forceinline__ void gemm_phase(const int wv, LAS unsigned char* lds, const Gemm g, const Sched& S, const Epi& E) {
;     ...
;             PG8_LDA(At, 1, 1); PG8_STAGE(PG8_SA(1, 0), a3, voffA);
;             PG8_BAR; PG8_WAIT_L(0); PG8_MMA(1, 0, At, B0); PG8_BAR; PG8_SCHED;
;             PG8_STAGE(PG8_SB(1, 1), b3 + hstepB, voffB);
;             PG8_WAIT_V(6); PG8_BAR; PG8_MMA(1, 1, At, B1); PG8_BAR;
;         }
;     __device__ __forceinline__ void operator()(const f32x4 (&acc)[2][2][4][2], const Unit& u, int wr, int wc, int fr, int fq) const {
;         const int row0 = u.pm * 256 + wr * 64 + fr; const int col0 = u.pn * 256 + wc * 32 + 4 * fq;
;         u32x2 xv[2][4][2][2];
; #pragma unroll
;         for (int ai = 0; ai < 2; ++ai)
; #pragma unroll
;             for (int m = 0; m < 4; ++m)
; #pragma unroll
;                 for (int bj = 0; bj < 2; ++bj)
; #pragma unroll
;                     for (int n = 0; n < 2; ++n) xv[ai][m][bj][n] = *(const u32x2*)(x1b + (size_t)(row0 + ai * 128 + m * 16) * 1024 + col0 + bj * 128 + n * 16);
	s_waitcnt lgkmcnt(0)
	s_waitcnt lgkmcnt(0)
	v_mfma_f32_16x16x32_bf16 v[60:63], v[144:147], v[160:163], v[60:63]
	v_mfma_f32_16x16x32_bf16 v[56:59], v[152:155], v[160:163], v[56:59]
	v_mfma_f32_16x16x32_bf16 v[48:51], v[144:147], v[168:171], v[48:51]
	v_mfma_f32_16x16x32_bf16 v[40:43], v[152:155], v[168:171], v[40:43]
	v_mfma_f32_16x16x32_bf16 v[32:35], v[144:147], v[176:179], v[32:35]
	v_mfma_f32_16x16x32_bf16 v[24:27], v[152:155], v[176:179], v[24:27]
	v_mfma_f32_16x16x32_bf16 v[16:19], v[144:147], v[184:187], v[16:19]
	v_mfma_f32_16x16x32_bf16 v[8:11], v[152:155], v[184:187], v[8:11]
	v_mfma_f32_16x16x32_bf16 v[60:63], v[148:151], v[164:167], v[60:63]
	v_mfma_f32_16x16x32_bf16 v[56:59], v[156:159], v[164:167], v[56:59]
	v_mfma_f32_16x16x32_bf16 v[48:51], v[148:151], v[172:175], v[48:51]
	v_mfma_f32_16x16x32_bf16 v[40:43], v[156:159], v[172:175], v[40:43]
	v_mfma_f32_16x16x32_bf16 v[32:35], v[148:151], v[180:183], v[32:35]
	v_mfma_f32_16x16x32_bf16 v[24:27], v[156:159], v[180:183], v[24:27]
	v_mfma_f32_16x16x32_bf16 v[16:19], v[148:151], v[188:191], v[16:19]
	v_mfma_f32_16x16x32_bf16 v[8:11], v[156:159], v[188:191], v[8:11]
	s_barrier
	s_add_u32 s20, s20, 0x100080
	s_addc_u32 s21, s21, 0
	s_add_i32 s22, s24, s31
	v_lshl_add_u64 v[144:145], s[20:21], 0, v[130:131]
	s_mov_b32 m0, s22
	s_nop 0
	global_load_lds_dwordx4 v[144:145], off
	v_lshl_add_u64 v[144:145], s[20:21], 0, v[134:135]
	s_add_i32 m0, s22, 0x2000
	s_nop 0
	global_load_lds_dwordx4 v[144:145], off
	s_waitcnt vmcnt(6)
	s_barrier
	v_mfma_f32_16x16x32_bf16 v[52:55], v[192:195], v[160:163], v[52:55]
	v_mfma_f32_16x16x32_bf16 v[44:47], v[206:209], v[160:163], v[44:47]
	v_mfma_f32_16x16x32_bf16 v[36:39], v[192:195], v[168:171], v[36:39]
	v_mfma_f32_16x16x32_bf16 v[28:31], v[206:209], v[168:171], v[28:31]
	v_mfma_f32_16x16x32_bf16 v[20:23], v[192:195], v[176:179], v[20:23]
	v_mfma_f32_16x16x32_bf16 v[12:15], v[206:209], v[176:179], v[12:15]
	v_mfma_f32_16x16x32_bf16 v[4:7], v[192:195], v[184:187], v[4:7]
	v_mfma_f32_16x16x32_bf16 v[0:3], v[206:209], v[184:187], v[0:3]
	v_mfma_f32_16x16x32_bf16 v[52:55], v[202:205], v[164:167], v[52:55]
	v_mfma_f32_16x16x32_bf16 v[44:47], v[210:213], v[164:167], v[44:47]
	v_mfma_f32_16x16x32_bf16 v[36:39], v[202:205], v[172:175], v[36:39]
	v_mfma_f32_16x16x32_bf16 v[28:31], v[210:213], v[172:175], v[28:31]
	v_mfma_f32_16x16x32_bf16 v[20:23], v[202:205], v[180:183], v[20:23]
	v_mfma_f32_16x16x32_bf16 v[12:15], v[210:213], v[180:183], v[12:15]
	v_mfma_f32_16x16x32_bf16 v[4:7], v[202:205], v[188:191], v[4:7]
	v_mfma_f32_16x16x32_bf16 v[0:3], v[210:213], v[188:191], v[0:3]
	s_add_i32 s46, s46, 2
	s_add_u32 s44, s44, 0x100
	s_addc_u32 s45, s45, 0
	s_add_u32 s18, s18, 0x10000
	s_addc_u32 s19, s19, 0
	s_cmp_gt_u32 s46, 61
	s_barrier
	s_cbranch_scc0 .LBB0_789
	v_lshl_add_u32 v146, s16, 8, v196
	v_lshl_or_b32 v148, s41, 8, v198
	v_ashrrev_i32_e32 v149, 31, v148
	v_ashrrev_i32_e32 v147, 31, v146
	v_lshl_add_u64 v[150:151], v[148:149], 1, s[2:3]
	v_lshlrev_b64 v[144:145], 11, v[146:147]
	v_lshl_add_u64 v[144:145], v[150:151], 0, v[144:145]
	global_load_dwordx2 v[202:203], v[144:145], off
	global_load_dwordx2 v[204:205], v[144:145], off offset:32
	global_load_dwordx2 v[206:207], v[144:145], off offset:256
	v_or_b32_e32 v208, 16, v146
	global_load_dwordx2 v[210:211], v[144:145], off offset:288
	v_ashrrev_i32_e32 v209, 31, v208
	v_lshlrev_b64 v[144:145], 11, v[208:209]
	v_lshl_add_u64 v[152:153], v[150:151], 0, v[144:145]
	global_load_dwordx2 v[212:213], v[152:153], off
	global_load_dwordx2 v[214:215], v[152:153], off offset:32
	global_load_dwordx2 v[216:217], v[152:153], off offset:256
	global_load_dwordx2 v[218:219], v[152:153], off offset:288
	v_or_b32_e32 v192, 32, v146
	v_or_b32_e32 v182, 48, v146
	v_add_u32_e32 v174, 0x80, v146
	v_add_u32_e32 v164, 0x90, v146
	v_add_u32_e32 v154, 0xa0, v146
	v_add_u32_e32 v144, 0xb0, v146
	v_ashrrev_i32_e32 v193, 31, v192
	v_ashrrev_i32_e32 v183, 31, v182
	v_ashrrev_i32_e32 v175, 31, v174
	v_ashrrev_i32_e32 v165, 31, v164
	v_ashrrev_i32_e32 v155, 31, v154
	v_ashrrev_i32_e32 v145, 31, v144
	v_lshlrev_b64 v[146:147], 12, v[146:147]
	v_lshlrev_b64 v[156:157], 11, v[192:193]
	v_lshlrev_b64 v[158:159], 11, v[182:183]
	v_lshlrev_b64 v[160:161], 11, v[174:175]
	v_lshlrev_b64 v[162:163], 11, v[164:165]
	v_lshlrev_b64 v[166:167], 11, v[154:155]
	v_lshlrev_b64 v[148:149], 2, v[148:149]
	v_lshlrev_b64 v[168:169], 11, v[144:145]
	v_lshl_add_u64 v[146:147], s[4:5], 0, v[146:147]
	v_lshl_add_u64 v[156:157], v[150:151], 0, v[156:157]
	v_lshl_add_u64 v[158:159], v[150:151], 0, v[158:159]
	v_lshl_add_u64 v[160:161], v[150:151], 0, v[160:161]
	v_lshl_add_u64 v[162:163], v[150:151], 0, v[162:163]
	v_lshl_add_u64 v[152:153], v[150:151], 0, v[166:167]
	v_lshl_add_u64 v[220:221], v[150:151], 0, v[168:169]
	v_lshl_add_u64 v[222:223], v[146:147], 0, v[148:149]
	global_load_dwordx2 v[224:225], v[156:157], off
	global_load_dwordx2 v[226:227], v[156:157], off offset:32
	global_load_dwordx2 v[228:229], v[156:157], off offset:256
	global_load_dwordx2 v[230:231], v[156:157], off offset:288
	global_load_dwordx2 v[232:233], v[158:159], off
	global_load_dwordx2 v[194:195], v[158:159], off offset:32
	global_load_dwordx2 v[190:191], v[158:159], off offset:256
	global_load_dwordx2 v[188:189], v[158:159], off offset:288
	global_load_dwordx2 v[186:187], v[160:161], off
	global_load_dwordx2 v[184:185], v[160:161], off offset:32
	global_load_dwordx2 v[180:181], v[160:161], off offset:256
	global_load_dwordx2 v[178:179], v[160:161], off offset:288
	global_load_dwordx2 v[176:177], v[162:163], off
	global_load_dwordx2 v[172:173], v[162:163], off offset:32
	global_load_dwordx2 v[170:171], v[162:163], off offset:256
	global_load_dwordx2 v[168:169], v[162:163], off offset:288
	global_load_dwordx2 v[166:167], v[152:153], off
	s_nop 0
	global_load_dwordx2 v[162:163], v[152:153], off offset:32
	global_load_dwordx2 v[160:161], v[152:153], off offset:256
	global_load_dwordx2 v[158:159], v[152:153], off offset:288
	global_load_dwordx2 v[156:157], v[220:221], off
	s_nop 0
	global_load_dwordx2 v[152:153], v[220:221], off offset:32
	global_load_dwordx2 v[150:151], v[220:221], off offset:256
	global_load_dwordx2 v[146:147], v[220:221], off offset:288
	s_and_b64 vcc, exec, s[0:1]
	s_mov_b32 s41, s8
	s_mov_b32 s16, s10
	s_mov_b64 s[18:19], s[14:15]
	s_mov_b64 s[20:21], s[12:13]
	s_waitcnt vmcnt(0)
; __device__ __forceinline__ float bflo(unsigned u) { return __uint_as_float(u << 16); }
; __device__ __forceinline__ float bfhi(unsigned u) { return __uint_as_float(u & 0xffff0000u); }
;     __device__ __forceinline__ void operator()(const f32x4 (&acc)[2][2][4][2], const Unit& u, int wr, int wc, int fr, int fq) const {
;     ...
; #pragma unroll
;         for (int ai = 0; ai < 2; ++ai)
; #pragma unroll
;             for (int m = 0; m < 4; ++m)
; #pragma unroll
;                 for (int bj = 0; bj < 2; ++bj)
; #pragma unroll
;                     for (int n = 0; n < 2; ++n) {
;                         const size_t o = (size_t)(row0 + ai * 128 + m * 16) * 1024 + col0 + bj * 128 + n * 16;
;                         const u32x2 v = xv[ai][m][bj][n]; const f32x4 a = acc[ai][bj][m][n];
;                         *(f32x4*)(out + o) = (f32x4){bflo(v.x) + a[0], bfhi(v.x) + a[1], bflo(v.y) + a[2], bfhi(v.y) + a[3]};
;                     }
	v_lshlrev_b32_e32 v220, 16, v202
	v_and_b32_e32 v221, 0xffff0000, v202
	v_lshlrev_b32_e32 v202, 16, v203
	v_and_b32_e32 v203, 0xffff0000, v203
	v_lshlrev_b32_e32 v234, 16, v204
	v_and_b32_e32 v235, 0xffff0000, v204
	v_lshlrev_b32_e32 v204, 16, v205
	v_and_b32_e32 v205, 0xffff0000, v205
	v_pk_add_f32 v[124:125], v[124:125], v[220:221]
	v_pk_add_f32 v[126:127], v[126:127], v[202:203]
	v_pk_add_f32 v[120:121], v[120:121], v[234:235]
	v_lshlrev_b32_e32 v236, 16, v206
	v_and_b32_e32 v237, 0xffff0000, v206
	v_pk_add_f32 v[122:123], v[122:123], v[204:205]
	global_store_dwordx4 v[222:223], v[124:127], off
	global_store_dwordx4 v[222:223], v[120:123], off offset:64
	v_pk_add_f32 v[116:117], v[116:117], v[236:237]
	s_nop 0
	v_lshlrev_b32_e32 v120, 16, v207
	v_and_b32_e32 v121, 0xffff0000, v207
	v_pk_add_f32 v[118:119], v[118:119], v[120:121]
	global_store_dwordx4 v[222:223], v[116:119], off offset:512
	s_nop 1
	v_lshlrev_b32_e32 v116, 16, v210
	v_and_b32_e32 v117, 0xffff0000, v210
	v_pk_add_f32 v[108:109], v[108:109], v[116:117]
	v_lshlrev_b32_e32 v116, 16, v211
	v_and_b32_e32 v117, 0xffff0000, v211
	v_pk_add_f32 v[110:111], v[110:111], v[116:117]
	global_store_dwordx4 v[222:223], v[108:111], off offset:576
	v_lshlrev_b64 v[116:117], 12, v[208:209]
	s_nop 0
	v_lshlrev_b32_e32 v108, 16, v212
	v_and_b32_e32 v109, 0xffff0000, v212
	v_pk_add_f32 v[108:109], v[112:113], v[108:109]
	v_lshlrev_b32_e32 v110, 16, v213
	v_and_b32_e32 v111, 0xffff0000, v213
	v_lshl_add_u64 v[112:113], s[4:5], 0, v[116:117]
	v_pk_add_f32 v[110:111], v[114:115], v[110:111]
	v_lshl_add_u64 v[112:113], v[112:113], 0, v[148:149]
	global_store_dwordx4 v[112:113], v[108:111], off
	s_nop 1
	v_lshlrev_b32_e32 v108, 16, v214
	v_and_b32_e32 v109, 0xffff0000, v214
	v_pk_add_f32 v[104:105], v[104:105], v[108:109]
	v_lshlrev_b32_e32 v108, 16, v215
	v_and_b32_e32 v109, 0xffff0000, v215
	v_pk_add_f32 v[106:107], v[106:107], v[108:109]
	global_store_dwordx4 v[112:113], v[104:107], off offset:64
	s_nop 1
	v_lshlrev_b32_e32 v104, 16, v216
	v_and_b32_e32 v105, 0xffff0000, v216
	v_pk_add_f32 v[100:101], v[100:101], v[104:105]
	v_lshlrev_b32_e32 v104, 16, v217
	v_and_b32_e32 v105, 0xffff0000, v217
	v_pk_add_f32 v[102:103], v[102:103], v[104:105]
	global_store_dwordx4 v[112:113], v[100:103], off offset:512
	s_nop 1
	v_lshlrev_b32_e32 v100, 16, v218
	v_and_b32_e32 v101, 0xffff0000, v218
	v_pk_add_f32 v[92:93], v[92:93], v[100:101]
	v_lshlrev_b32_e32 v100, 16, v219
	v_and_b32_e32 v101, 0xffff0000, v219
	v_pk_add_f32 v[94:95], v[94:95], v[100:101]
	global_store_dwordx4 v[112:113], v[92:95], off offset:576
	v_lshlrev_b64 v[100:101], 12, v[192:193]
	s_nop 0
	v_lshlrev_b32_e32 v92, 16, v224
	v_and_b32_e32 v93, 0xffff0000, v224
	v_pk_add_f32 v[92:93], v[96:97], v[92:93]
	v_lshlrev_b32_e32 v94, 16, v225
	v_and_b32_e32 v95, 0xffff0000, v225
	v_lshl_add_u64 v[96:97], s[4:5], 0, v[100:101]
	v_pk_add_f32 v[94:95], v[98:99], v[94:95]
	v_lshl_add_u64 v[96:97], v[96:97], 0, v[148:149]
	global_store_dwordx4 v[96:97], v[92:95], off
	s_nop 1
	v_lshlrev_b32_e32 v92, 16, v226
	v_and_b32_e32 v93, 0xffff0000, v226
	v_pk_add_f32 v[88:89], v[88:89], v[92:93]
	v_lshlrev_b32_e32 v92, 16, v227
	v_and_b32_e32 v93, 0xffff0000, v227
	v_pk_add_f32 v[90:91], v[90:91], v[92:93]
	global_store_dwordx4 v[96:97], v[88:91], off offset:64
	s_nop 1
	v_lshlrev_b32_e32 v88, 16, v228
	v_and_b32_e32 v89, 0xffff0000, v228
	v_pk_add_f32 v[84:85], v[84:85], v[88:89]
	v_lshlrev_b32_e32 v88, 16, v229
	v_and_b32_e32 v89, 0xffff0000, v229
	v_pk_add_f32 v[86:87], v[86:87], v[88:89]
	global_store_dwordx4 v[96:97], v[84:87], off offset:512
	s_nop 1
	v_lshlrev_b32_e32 v84, 16, v230
	v_and_b32_e32 v85, 0xffff0000, v230
	v_pk_add_f32 v[76:77], v[76:77], v[84:85]
	v_lshlrev_b32_e32 v84, 16, v231
	v_and_b32_e32 v85, 0xffff0000, v231
	v_pk_add_f32 v[78:79], v[78:79], v[84:85]
	global_store_dwordx4 v[96:97], v[76:79], off offset:576
	v_lshlrev_b64 v[84:85], 12, v[182:183]
	s_nop 0
	v_lshlrev_b32_e32 v76, 16, v232
	v_and_b32_e32 v77, 0xffff0000, v232
	v_pk_add_f32 v[76:77], v[80:81], v[76:77]
	v_lshlrev_b32_e32 v78, 16, v233
	v_and_b32_e32 v79, 0xffff0000, v233
	v_lshl_add_u64 v[80:81], s[4:5], 0, v[84:85]
	v_pk_add_f32 v[78:79], v[82:83], v[78:79]
	v_lshl_add_u64 v[80:81], v[80:81], 0, v[148:149]
	global_store_dwordx4 v[80:81], v[76:79], off
	s_nop 1
	v_lshlrev_b32_e32 v76, 16, v194
	v_and_b32_e32 v77, 0xffff0000, v194
	v_pk_add_f32 v[72:73], v[72:73], v[76:77]
	v_lshlrev_b32_e32 v76, 16, v195
	v_and_b32_e32 v77, 0xffff0000, v195
	v_pk_add_f32 v[74:75], v[74:75], v[76:77]
	global_store_dwordx4 v[80:81], v[72:75], off offset:64
	s_nop 1
	v_lshlrev_b32_e32 v72, 16, v190
	v_and_b32_e32 v73, 0xffff0000, v190
	v_pk_add_f32 v[68:69], v[68:69], v[72:73]
	v_lshlrev_b32_e32 v72, 16, v191
	v_and_b32_e32 v73, 0xffff0000, v191
	v_pk_add_f32 v[70:71], v[70:71], v[72:73]
	global_store_dwordx4 v[80:81], v[68:71], off offset:512
	s_nop 1
	v_lshlrev_b32_e32 v68, 16, v188
	v_and_b32_e32 v69, 0xffff0000, v188
	v_pk_add_f32 v[64:65], v[64:65], v[68:69]
	v_lshlrev_b32_e32 v68, 16, v189
	v_and_b32_e32 v69, 0xffff0000, v189
	v_pk_add_f32 v[66:67], v[66:67], v[68:69]
	global_store_dwordx4 v[80:81], v[64:67], off offset:576
	s_nop 1
; __device__ __forceinline__ float bflo(unsigned u) { return __uint_as_float(u << 16); }
; __device__ __forceinline__ float bfhi(unsigned u) { return __uint_as_float(u & 0xffff0000u); }
; #define PG8_WAIT_V(n) asm volatile("s_waitcnt vmcnt(" #n ")" ::: "memory")
; #define PG8_BAR __builtin_amdgcn_s_barrier()
; template <class Epi, class Sched>
; __device__ __forceinline__ void gemm_phase(const int wv, LAS unsigned char* lds, const Gemm g, const Sched& S, const Epi& E) {
;     ...
;     PG8_WAIT_V(0);
;     if (wr == 0) PG8_BAR;
;     PG8_BAR;
;     __device__ __forceinline__ void operator()(const f32x4 (&acc)[2][2][4][2], const Unit& u, int wr, int wc, int fr, int fq) const {
;     ...
; #pragma unroll
;         for (int ai = 0; ai < 2; ++ai)
; #pragma unroll
;             for (int m = 0; m < 4; ++m)
; #pragma unroll
;                 for (int bj = 0; bj < 2; ++bj)
; #pragma unroll
;                     for (int n = 0; n < 2; ++n) {
;                         const size_t o = (size_t)(row0 + ai * 128 + m * 16) * 1024 + col0 + bj * 128 + n * 16;
;                         const u32x2 v = xv[ai][m][bj][n]; const f32x4 a = acc[ai][bj][m][n];
;                         *(f32x4*)(out + o) = (f32x4){bflo(v.x) + a[0], bfhi(v.x) + a[1], bflo(v.y) + a[2], bfhi(v.y) + a[3]};
;                     }
	v_lshlrev_b64 v[64:65], 12, v[174:175]
	v_lshlrev_b32_e32 v66, 16, v186
	v_and_b32_e32 v67, 0xffff0000, v186
	v_pk_add_f32 v[60:61], v[60:61], v[66:67]
	v_lshlrev_b32_e32 v66, 16, v187
	v_and_b32_e32 v67, 0xffff0000, v187
	v_lshl_add_u64 v[64:65], s[4:5], 0, v[64:65]
	v_pk_add_f32 v[62:63], v[62:63], v[66:67]
	v_lshl_add_u64 v[64:65], v[64:65], 0, v[148:149]
	global_store_dwordx4 v[64:65], v[60:63], off
	s_nop 1
	v_lshlrev_b32_e32 v60, 16, v184
	v_and_b32_e32 v61, 0xffff0000, v184
	v_pk_add_f32 v[56:57], v[56:57], v[60:61]
	v_lshlrev_b32_e32 v60, 16, v185
	v_and_b32_e32 v61, 0xffff0000, v185
	v_pk_add_f32 v[58:59], v[58:59], v[60:61]
	global_store_dwordx4 v[64:65], v[56:59], off offset:64
	s_nop 1
	v_lshlrev_b32_e32 v56, 16, v180
	v_and_b32_e32 v57, 0xffff0000, v180
	v_pk_add_f32 v[52:53], v[52:53], v[56:57]
	v_lshlrev_b32_e32 v56, 16, v181
	v_and_b32_e32 v57, 0xffff0000, v181
	v_pk_add_f32 v[54:55], v[54:55], v[56:57]
	global_store_dwordx4 v[64:65], v[52:55], off offset:512
	s_nop 1
	v_lshlrev_b32_e32 v52, 16, v178
	v_and_b32_e32 v53, 0xffff0000, v178
	v_pk_add_f32 v[44:45], v[44:45], v[52:53]
	v_lshlrev_b32_e32 v52, 16, v179
	v_and_b32_e32 v53, 0xffff0000, v179
	v_pk_add_f32 v[46:47], v[46:47], v[52:53]
	global_store_dwordx4 v[64:65], v[44:47], off offset:576
	v_lshlrev_b64 v[52:53], 12, v[164:165]
	s_nop 0
	v_lshlrev_b32_e32 v44, 16, v176
	v_and_b32_e32 v45, 0xffff0000, v176
	v_pk_add_f32 v[44:45], v[48:49], v[44:45]
	v_lshlrev_b32_e32 v46, 16, v177
	v_and_b32_e32 v47, 0xffff0000, v177
	v_lshl_add_u64 v[48:49], s[4:5], 0, v[52:53]
	v_pk_add_f32 v[46:47], v[50:51], v[46:47]
	v_lshl_add_u64 v[48:49], v[48:49], 0, v[148:149]
	global_store_dwordx4 v[48:49], v[44:47], off
	s_nop 1
	v_lshlrev_b32_e32 v44, 16, v172
	v_and_b32_e32 v45, 0xffff0000, v172
	v_pk_add_f32 v[40:41], v[40:41], v[44:45]
	v_lshlrev_b32_e32 v44, 16, v173
	v_and_b32_e32 v45, 0xffff0000, v173
	v_pk_add_f32 v[42:43], v[42:43], v[44:45]
	global_store_dwordx4 v[48:49], v[40:43], off offset:64
	s_nop 1
	v_lshlrev_b32_e32 v40, 16, v170
	v_and_b32_e32 v41, 0xffff0000, v170
	v_pk_add_f32 v[36:37], v[36:37], v[40:41]
	v_lshlrev_b32_e32 v40, 16, v171
	v_and_b32_e32 v41, 0xffff0000, v171
	v_pk_add_f32 v[38:39], v[38:39], v[40:41]
	global_store_dwordx4 v[48:49], v[36:39], off offset:512
	s_nop 1
	v_lshlrev_b32_e32 v36, 16, v168
	v_and_b32_e32 v37, 0xffff0000, v168
	v_pk_add_f32 v[28:29], v[28:29], v[36:37]
	v_lshlrev_b32_e32 v36, 16, v169
	v_and_b32_e32 v37, 0xffff0000, v169
	v_pk_add_f32 v[30:31], v[30:31], v[36:37]
	global_store_dwordx4 v[48:49], v[28:31], off offset:576
	v_lshlrev_b64 v[36:37], 12, v[154:155]
	s_nop 0
	v_lshlrev_b32_e32 v28, 16, v166
	v_and_b32_e32 v29, 0xffff0000, v166
	v_pk_add_f32 v[28:29], v[32:33], v[28:29]
	v_lshlrev_b32_e32 v30, 16, v167
	v_and_b32_e32 v31, 0xffff0000, v167
	v_lshl_add_u64 v[32:33], s[4:5], 0, v[36:37]
	v_pk_add_f32 v[30:31], v[34:35], v[30:31]
	v_lshl_add_u64 v[32:33], v[32:33], 0, v[148:149]
	global_store_dwordx4 v[32:33], v[28:31], off
	s_nop 1
	v_lshlrev_b32_e32 v28, 16, v162
	v_and_b32_e32 v29, 0xffff0000, v162
	v_pk_add_f32 v[24:25], v[24:25], v[28:29]
	v_lshlrev_b32_e32 v28, 16, v163
	v_and_b32_e32 v29, 0xffff0000, v163
	v_pk_add_f32 v[26:27], v[26:27], v[28:29]
	global_store_dwordx4 v[32:33], v[24:27], off offset:64
	s_nop 1
	v_lshlrev_b32_e32 v24, 16, v160
	v_and_b32_e32 v25, 0xffff0000, v160
	v_pk_add_f32 v[20:21], v[20:21], v[24:25]
	v_lshlrev_b32_e32 v24, 16, v161
	v_and_b32_e32 v25, 0xffff0000, v161
	v_pk_add_f32 v[22:23], v[22:23], v[24:25]
	global_store_dwordx4 v[32:33], v[20:23], off offset:512
	s_nop 1
	v_lshlrev_b32_e32 v20, 16, v158
	v_and_b32_e32 v21, 0xffff0000, v158
	v_pk_add_f32 v[12:13], v[12:13], v[20:21]
	v_lshlrev_b32_e32 v20, 16, v159
	v_and_b32_e32 v21, 0xffff0000, v159
	v_pk_add_f32 v[14:15], v[14:15], v[20:21]
	global_store_dwordx4 v[32:33], v[12:15], off offset:576
	v_lshlrev_b64 v[20:21], 12, v[144:145]
	s_nop 0
	v_lshlrev_b32_e32 v12, 16, v156
	v_and_b32_e32 v13, 0xffff0000, v156
	v_pk_add_f32 v[12:13], v[16:17], v[12:13]
	v_lshlrev_b32_e32 v14, 16, v157
	v_and_b32_e32 v15, 0xffff0000, v157
	v_lshl_add_u64 v[16:17], s[4:5], 0, v[20:21]
	v_pk_add_f32 v[14:15], v[18:19], v[14:15]
	v_lshl_add_u64 v[16:17], v[16:17], 0, v[148:149]
	global_store_dwordx4 v[16:17], v[12:15], off
	s_nop 1
	v_lshlrev_b32_e32 v12, 16, v152
	v_and_b32_e32 v13, 0xffff0000, v152
	v_pk_add_f32 v[8:9], v[8:9], v[12:13]
	v_lshlrev_b32_e32 v12, 16, v153
	v_and_b32_e32 v13, 0xffff0000, v153
	v_pk_add_f32 v[10:11], v[10:11], v[12:13]
	global_store_dwordx4 v[16:17], v[8:11], off offset:64
	s_nop 1
	v_lshlrev_b32_e32 v8, 16, v150
	v_and_b32_e32 v9, 0xffff0000, v150
	v_pk_add_f32 v[4:5], v[4:5], v[8:9]
	v_lshlrev_b32_e32 v8, 16, v151
	v_and_b32_e32 v9, 0xffff0000, v151
	v_pk_add_f32 v[6:7], v[6:7], v[8:9]
	global_store_dwordx4 v[16:17], v[4:7], off offset:512
	s_nop 1
	v_lshlrev_b32_e32 v4, 16, v146
	v_and_b32_e32 v5, 0xffff0000, v146
	v_pk_add_f32 v[0:1], v[0:1], v[4:5]
	v_lshlrev_b32_e32 v4, 16, v147
	v_and_b32_e32 v5, 0xffff0000, v147
	v_pk_add_f32 v[2:3], v[2:3], v[4:5]
	global_store_dwordx4 v[16:17], v[0:3], off offset:576
	s_cbranch_vccz .LBB0_782
	s_waitcnt vmcnt(0)
	s_cmpk_gt_u32 s26, 0xff
	s_cbranch_scc1 .LBB0_793
	s_barrier
